# K-loop loader segments: LDS-DMA groups issued early with the fragment ds_reads threaded between them (was: all reads then all DMAs)
# speedup vs baseline: 1.0045x; 1.0045x over previous
; #define PG8_STAGE(bufoff, gbase, voff) do { _Pragma("unroll") for (int _i = 0; _i < 2; ++_i) \
;         __builtin_amdgcn_global_load_lds((const unsigned*)((const char*)(gbase) + (voff)[_i]), (LAS unsigned*)(lds + (bufoff) + ldsw + _i * 8192), 16, 0, 0); } while (0)
; #define PG8_LDA(dst, b, h) do { _Pragma("unroll") for (int m = 0; m < 4; ++m) _Pragma("unroll") for (int k = 0; k < 2; ++k) dst[m][k] = *(const LAS bf16x8*)(lds + PG8_SA(b, h) + aoff + m * 2048 + k * 1024); } while (0)
; #define PG8_LDB(dst, b, h) do { _Pragma("unroll") for (int n = 0; n < 2; ++n) _Pragma("unroll") for (int k = 0; k < 2; ++k) dst[n][k] = *(const LAS bf16x8*)(lds + PG8_SB(b, h) + boff + n * 2048 + k * 1024); } while (0)
; #define PG8_MMA(ai, bj, At, Bt) do { __builtin_amdgcn_s_setprio(1); _Pragma("unroll") for (int m = 0; m < 4; ++m) _Pragma("unroll") for (int n = 0; n < 2; ++n) _Pragma("unroll") for (int k = 0; k < 2; ++k) \
;         acc[ai][bj][m][n] = __builtin_amdgcn_mfma_f32_16x16x32_bf16(Bt[n][k], At[m][k], acc[ai][bj][m][n], 0, 0, 0); __builtin_amdgcn_s_setprio(0); } while (0)
; #define PG8_WAIT_V(n) asm volatile("s_waitcnt vmcnt(" #n ")" ::: "memory")
; #define PG8_WAIT_L(n) asm volatile("s_waitcnt lgkmcnt(" #n ")" ::: "memory")
; #define PG8_BAR __builtin_amdgcn_s_barrier()
; #define PG8_SCHED __builtin_amdgcn_sched_barrier(0)
; template <class Epi, class Sched, bool ALIGN_EPI = true, bool SP2 = true>
; __device__ __forceinline__ void gemm_phase(LAS unsigned char* lds, const Gemm g, const Sched& S, const Epi& E) {
;     ...
;             PG8_LDB(B0, 0, 0); PG8_LDB(B1, 0, 1); PG8_SCHED; PG8_LDA(At, 0, 0); PG8_STAGE(PG8_SA(1, 1), a1 + hstep, voffA);
;             PG8_WAIT_V(8); PG8_WAIT_L(0); PG8_BAR; PG8_MMA(0, 0, At, B0); PG8_MMA(0, 1, At, B1); PG8_BAR; PG8_SCHED;
;             PG8_LDA(At, 0, 1); PG8_STAGE(PG8_SB(0, 0), b2, voffB); PG8_STAGE(PG8_SB(0, 1), b2 + hstep, voffB); PG8_STAGE(PG8_SA(0, 0), a2, voffA);
;             PG8_WAIT_V(8); PG8_WAIT_L(0); PG8_BAR; PG8_MMA(1, 0, At, B0); PG8_MMA(1, 1, At, B1); PG8_BAR; PG8_SCHED;
.LBB0_40:
	s_add_u32 s24, s90, 0xfffe0080
	s_addc_u32 s25, s91, -1
	s_add_i32 s46, 0, 0x10000
	s_cmp_eq_u32 vcc_hi, 4
	s_cselect_b32 s83, s2, s25
	s_cselect_b32 s82, s3, s24
	v_add_u32_e32 v142, s46, v145
	s_cselect_b32 s25, s45, vcc_lo
	s_cselect_b32 s24, s53, s55
	s_add_i32 s48, 0, 0x14000
	ds_read_b128 v[138:141], v142
	ds_read_b128 v[148:151], v142 offset:1024
	ds_read_b128 v[152:155], v142 offset:2048
	ds_read_b128 v[156:159], v142 offset:3072
	v_add_u32_e32 v142, s48, v145
	s_add_i32 m0, s67, 0xc000
	ds_read_b128 v[170:173], v142
	global_load_lds_dwordx4 v134, s[90:91]
	ds_read_b128 v[174:177], v142 offset:1024
	ds_read_b128 v[178:181], v142 offset:2048
	ds_read_b128 v[182:185], v142 offset:3072
	ds_read_b128 v[186:189], v147
	ds_read_b128 v[190:193], v147 offset:1024
	ds_read_b128 v[194:197], v147 offset:2048
	s_add_i32 m0, s67, 0xe000
	ds_read_b128 v[198:201], v147 offset:3072
	global_load_lds_dwordx4 v136, s[90:91]
	ds_read_b128 v[202:205], v147 offset:4096
	ds_read_b128 v[206:209], v147 offset:5120
	ds_read_b128 v[210:213], v147 offset:6144
	ds_read_b128 v[214:217], v147 offset:7168
	s_waitcnt vmcnt(8)
	s_waitcnt lgkmcnt(0)
	s_barrier
	s_setprio 1
	s_waitcnt lgkmcnt(0)
	v_mfma_f32_16x16x32_bf16 v[124:127], v[138:141], v[186:189], v[124:127]
	v_mfma_f32_16x16x32_bf16 v[120:123], v[152:155], v[186:189], v[120:123]
	v_mfma_f32_16x16x32_bf16 v[108:111], v[138:141], v[194:197], v[108:111]
	v_mfma_f32_16x16x32_bf16 v[104:107], v[152:155], v[194:197], v[104:107]
	v_mfma_f32_16x16x32_bf16 v[92:95], v[138:141], v[202:205], v[92:95]
	v_mfma_f32_16x16x32_bf16 v[88:91], v[152:155], v[202:205], v[88:91]
	v_mfma_f32_16x16x32_bf16 v[76:79], v[138:141], v[210:213], v[76:79]
	v_mfma_f32_16x16x32_bf16 v[72:75], v[152:155], v[210:213], v[72:75]
	v_mfma_f32_16x16x32_bf16 v[124:127], v[148:151], v[190:193], v[124:127]
	v_mfma_f32_16x16x32_bf16 v[120:123], v[156:159], v[190:193], v[120:123]
	v_mfma_f32_16x16x32_bf16 v[108:111], v[148:151], v[198:201], v[108:111]
	v_mfma_f32_16x16x32_bf16 v[104:107], v[156:159], v[198:201], v[104:107]
	v_mfma_f32_16x16x32_bf16 v[92:95], v[148:151], v[206:209], v[92:95]
	v_mfma_f32_16x16x32_bf16 v[88:91], v[156:159], v[206:209], v[88:91]
	v_mfma_f32_16x16x32_bf16 v[76:79], v[148:151], v[214:217], v[76:79]
	v_mfma_f32_16x16x32_bf16 v[72:75], v[156:159], v[214:217], v[72:75]
	s_setprio 0
	s_setprio 1
	v_mfma_f32_16x16x32_bf16 v[116:119], v[170:173], v[186:189], v[116:119]
	v_mfma_f32_16x16x32_bf16 v[112:115], v[178:181], v[186:189], v[112:115]
	v_mfma_f32_16x16x32_bf16 v[100:103], v[170:173], v[194:197], v[100:103]
	v_mfma_f32_16x16x32_bf16 v[96:99], v[178:181], v[194:197], v[96:99]
	v_mfma_f32_16x16x32_bf16 v[84:87], v[170:173], v[202:205], v[84:87]
	v_mfma_f32_16x16x32_bf16 v[80:83], v[178:181], v[202:205], v[80:83]
	v_mfma_f32_16x16x32_bf16 v[68:71], v[170:173], v[210:213], v[68:71]
	v_mfma_f32_16x16x32_bf16 v[64:67], v[178:181], v[210:213], v[64:67]
	v_mfma_f32_16x16x32_bf16 v[116:119], v[174:177], v[190:193], v[116:119]
	v_mfma_f32_16x16x32_bf16 v[112:115], v[182:185], v[190:193], v[112:115]
	v_mfma_f32_16x16x32_bf16 v[100:103], v[174:177], v[198:201], v[100:103]
	v_mfma_f32_16x16x32_bf16 v[96:99], v[182:185], v[198:201], v[96:99]
	v_mfma_f32_16x16x32_bf16 v[84:87], v[174:177], v[206:209], v[84:87]
	v_mfma_f32_16x16x32_bf16 v[80:83], v[182:185], v[206:209], v[80:83]
	v_mfma_f32_16x16x32_bf16 v[68:71], v[174:177], v[214:217], v[68:71]
	v_mfma_f32_16x16x32_bf16 v[64:67], v[182:185], v[214:217], v[64:67]
	s_setprio 0
	s_barrier
	s_add_i32 s46, s46, s93
	s_mov_b32 m0, s46
	ds_read_b128 v[186:189], v147 offset:16384
	global_load_lds_dwordx4 v160, s[24:25]
	ds_read_b128 v[190:193], v147 offset:17408
	ds_read_b128 v[194:197], v147 offset:18432
	s_add_i32 m0, s46, 0x2000
	s_add_u32 s46, s24, 0x20000
	s_addc_u32 s47, s25, 0
	s_add_i32 s48, s48, s93
	global_load_lds_dwordx4 v132, s[24:25]
	ds_read_b128 v[198:201], v147 offset:19456
	s_mov_b32 m0, s48
	ds_read_b128 v[202:205], v147 offset:20480
	global_load_lds_dwordx4 v160, s[46:47]
	ds_read_b128 v[206:209], v147 offset:21504
	s_add_i32 m0, s48, 0x2000
	ds_read_b128 v[210:213], v147 offset:22528
	global_load_lds_dwordx4 v132, s[46:47]
	ds_read_b128 v[214:217], v147 offset:23552
	s_mov_b32 m0, s67
	s_nop 0
	global_load_lds_dwordx4 v128, s[82:83]
	s_mov_b32 m0, s73
	s_nop 0
	global_load_lds_dwordx4 v130, s[82:83]
	s_waitcnt vmcnt(8)
	s_waitcnt lgkmcnt(0)
	s_barrier
	s_setprio 1
	s_waitcnt lgkmcnt(0)
	v_mfma_f32_16x16x32_bf16 v[60:63], v[138:141], v[186:189], v[60:63]
	v_mfma_f32_16x16x32_bf16 v[56:59], v[152:155], v[186:189], v[56:59]
	v_mfma_f32_16x16x32_bf16 v[44:47], v[138:141], v[194:197], v[44:47]
	v_mfma_f32_16x16x32_bf16 v[40:43], v[152:155], v[194:197], v[40:43]
	v_mfma_f32_16x16x32_bf16 v[28:31], v[138:141], v[202:205], v[28:31]
	v_mfma_f32_16x16x32_bf16 v[24:27], v[152:155], v[202:205], v[24:27]
	v_mfma_f32_16x16x32_bf16 v[12:15], v[138:141], v[210:213], v[12:15]
	v_mfma_f32_16x16x32_bf16 v[8:11], v[152:155], v[210:213], v[8:11]
	v_mfma_f32_16x16x32_bf16 v[60:63], v[148:151], v[190:193], v[60:63]
	v_mfma_f32_16x16x32_bf16 v[56:59], v[156:159], v[190:193], v[56:59]
	v_mfma_f32_16x16x32_bf16 v[44:47], v[148:151], v[198:201], v[44:47]
	v_mfma_f32_16x16x32_bf16 v[40:43], v[156:159], v[198:201], v[40:43]
	v_mfma_f32_16x16x32_bf16 v[28:31], v[148:151], v[206:209], v[28:31]
	v_mfma_f32_16x16x32_bf16 v[24:27], v[156:159], v[206:209], v[24:27]
	v_mfma_f32_16x16x32_bf16 v[12:15], v[148:151], v[214:217], v[12:15]
	v_mfma_f32_16x16x32_bf16 v[8:11], v[156:159], v[214:217], v[8:11]
	s_setprio 0
	s_setprio 1
	v_mfma_f32_16x16x32_bf16 v[52:55], v[170:173], v[186:189], v[52:55]
	v_mfma_f32_16x16x32_bf16 v[48:51], v[178:181], v[186:189], v[48:51]
	v_mfma_f32_16x16x32_bf16 v[36:39], v[170:173], v[194:197], v[36:39]
	v_mfma_f32_16x16x32_bf16 v[32:35], v[178:181], v[194:197], v[32:35]
	v_mfma_f32_16x16x32_bf16 v[20:23], v[170:173], v[202:205], v[20:23]
	v_mfma_f32_16x16x32_bf16 v[16:19], v[178:181], v[202:205], v[16:19]
	v_mfma_f32_16x16x32_bf16 v[4:7], v[170:173], v[210:213], v[4:7]
	v_mfma_f32_16x16x32_bf16 v[0:3], v[178:181], v[210:213], v[0:3]
	v_mfma_f32_16x16x32_bf16 v[52:55], v[174:177], v[190:193], v[52:55]
	v_mfma_f32_16x16x32_bf16 v[48:51], v[182:185], v[190:193], v[48:51]
	v_mfma_f32_16x16x32_bf16 v[36:39], v[174:177], v[198:201], v[36:39]
	v_mfma_f32_16x16x32_bf16 v[32:35], v[182:185], v[198:201], v[32:35]
	v_mfma_f32_16x16x32_bf16 v[20:23], v[174:177], v[206:209], v[20:23]
	v_mfma_f32_16x16x32_bf16 v[16:19], v[182:185], v[206:209], v[16:19]
	v_mfma_f32_16x16x32_bf16 v[4:7], v[174:177], v[214:217], v[4:7]
	v_mfma_f32_16x16x32_bf16 v[0:3], v[182:185], v[214:217], v[0:3]
	s_setprio 0
	s_barrier
; #define PG8_STAGE(bufoff, gbase, voff) do { _Pragma("unroll") for (int _i = 0; _i < 2; ++_i) \
;         __builtin_amdgcn_global_load_lds((const unsigned*)((const char*)(gbase) + (voff)[_i]), (LAS unsigned*)(lds + (bufoff) + ldsw + _i * 8192), 16, 0, 0); } while (0)
; #define PG8_LDA(dst, b, h) do { _Pragma("unroll") for (int m = 0; m < 4; ++m) _Pragma("unroll") for (int k = 0; k < 2; ++k) dst[m][k] = *(const LAS bf16x8*)(lds + PG8_SA(b, h) + aoff + m * 2048 + k * 1024); } while (0)
; #define PG8_LDB(dst, b, h) do { _Pragma("unroll") for (int n = 0; n < 2; ++n) _Pragma("unroll") for (int k = 0; k < 2; ++k) dst[n][k] = *(const LAS bf16x8*)(lds + PG8_SB(b, h) + boff + n * 2048 + k * 1024); } while (0)
; #define PG8_MMA(ai, bj, At, Bt) do { __builtin_amdgcn_s_setprio(1); _Pragma("unroll") for (int m = 0; m < 4; ++m) _Pragma("unroll") for (int n = 0; n < 2; ++n) _Pragma("unroll") for (int k = 0; k < 2; ++k) \
;         acc[ai][bj][m][n] = __builtin_amdgcn_mfma_f32_16x16x32_bf16(Bt[n][k], At[m][k], acc[ai][bj][m][n], 0, 0, 0); __builtin_amdgcn_s_setprio(0); } while (0)
; #define PG8_WAIT_V(n) asm volatile("s_waitcnt vmcnt(" #n ")" ::: "memory")
; #define PG8_WAIT_L(n) asm volatile("s_waitcnt lgkmcnt(" #n ")" ::: "memory")
; #define PG8_BAR __builtin_amdgcn_s_barrier()
; #define PG8_SCHED __builtin_amdgcn_sched_barrier(0)
; template <class Epi, class Sched, bool ALIGN_EPI = true, bool SP2 = true>
; __device__ __forceinline__ void gemm_phase(LAS unsigned char* lds, const Gemm g, const Sched& S, const Epi& E) {
;     ...
;             PG8_LDB(B0, 1, 0); PG8_LDB(B1, 1, 1); PG8_SCHED; PG8_LDA(At, 1, 0); PG8_STAGE(PG8_SA(0, 1), a2 + hstep, voffA);
;             PG8_WAIT_V(8); PG8_WAIT_L(0); PG8_BAR; PG8_MMA(0, 0, At, B0); PG8_MMA(0, 1, At, B1); PG8_BAR; PG8_SCHED;
;             PG8_LDA(At, 1, 1); PG8_STAGE(PG8_SB(1, 0), b3, voffB); PG8_STAGE(PG8_SB(1, 1), b3 + hstep, voffB); PG8_STAGE(PG8_SA(1, 0), a3, voffA);
;             PG8_WAIT_V(8); PG8_WAIT_L(0); PG8_BAR; PG8_MMA(1, 0, At, B0); PG8_MMA(1, 1, At, B1); PG8_BAR; PG8_SCHED;
	s_add_i32 s48, 0, 0x18000
	s_add_i32 s49, 0, 0x1c000
	v_add_u32_e32 v156, s48, v145
	v_add_u32_e32 v182, s49, v145
	s_add_u32 s46, s82, 0x20000
	s_addc_u32 s47, s83, 0
	s_mov_b32 m0, s94
	ds_read_b128 v[138:141], v156
	global_load_lds_dwordx4 v128, s[46:47]
	ds_read_b128 v[148:151], v156 offset:1024
	ds_read_b128 v[152:155], v156 offset:2048
	ds_read_b128 v[156:159], v156 offset:3072
	ds_read_b128 v[170:173], v182
	ds_read_b128 v[174:177], v182 offset:1024
	ds_read_b128 v[178:181], v182 offset:2048
	ds_read_b128 v[182:185], v182 offset:3072
	ds_read_b128 v[186:189], v147 offset:32768
	s_mov_b32 m0, s95
	ds_read_b128 v[190:193], v147 offset:33792
	global_load_lds_dwordx4 v130, s[46:47]
	ds_read_b128 v[194:197], v147 offset:34816
	ds_read_b128 v[198:201], v147 offset:35840
	ds_read_b128 v[202:205], v147 offset:36864
	ds_read_b128 v[206:209], v147 offset:37888
	ds_read_b128 v[210:213], v147 offset:38912
	ds_read_b128 v[214:217], v147 offset:39936
	s_waitcnt vmcnt(8)
	s_waitcnt lgkmcnt(0)
	s_barrier
	s_setprio 1
	s_waitcnt lgkmcnt(0)
	v_mfma_f32_16x16x32_bf16 v[124:127], v[138:141], v[186:189], v[124:127]
	v_mfma_f32_16x16x32_bf16 v[120:123], v[152:155], v[186:189], v[120:123]
	v_mfma_f32_16x16x32_bf16 v[108:111], v[138:141], v[194:197], v[108:111]
	v_mfma_f32_16x16x32_bf16 v[104:107], v[152:155], v[194:197], v[104:107]
	v_mfma_f32_16x16x32_bf16 v[92:95], v[138:141], v[202:205], v[92:95]
	v_mfma_f32_16x16x32_bf16 v[88:91], v[152:155], v[202:205], v[88:91]
	v_mfma_f32_16x16x32_bf16 v[76:79], v[138:141], v[210:213], v[76:79]
	v_mfma_f32_16x16x32_bf16 v[72:75], v[152:155], v[210:213], v[72:75]
	v_mfma_f32_16x16x32_bf16 v[124:127], v[148:151], v[190:193], v[124:127]
	v_mfma_f32_16x16x32_bf16 v[120:123], v[156:159], v[190:193], v[120:123]
	v_mfma_f32_16x16x32_bf16 v[108:111], v[148:151], v[198:201], v[108:111]
	v_mfma_f32_16x16x32_bf16 v[104:107], v[156:159], v[198:201], v[104:107]
	v_mfma_f32_16x16x32_bf16 v[92:95], v[148:151], v[206:209], v[92:95]
	v_mfma_f32_16x16x32_bf16 v[88:91], v[156:159], v[206:209], v[88:91]
	v_mfma_f32_16x16x32_bf16 v[76:79], v[148:151], v[214:217], v[76:79]
	v_mfma_f32_16x16x32_bf16 v[72:75], v[156:159], v[214:217], v[72:75]
	s_setprio 0
	s_setprio 1
	v_mfma_f32_16x16x32_bf16 v[116:119], v[170:173], v[186:189], v[116:119]
	v_mfma_f32_16x16x32_bf16 v[112:115], v[178:181], v[186:189], v[112:115]
	v_mfma_f32_16x16x32_bf16 v[100:103], v[170:173], v[194:197], v[100:103]
	v_mfma_f32_16x16x32_bf16 v[96:99], v[178:181], v[194:197], v[96:99]
	v_mfma_f32_16x16x32_bf16 v[84:87], v[170:173], v[202:205], v[84:87]
	v_mfma_f32_16x16x32_bf16 v[80:83], v[178:181], v[202:205], v[80:83]
	v_mfma_f32_16x16x32_bf16 v[68:71], v[170:173], v[210:213], v[68:71]
	v_mfma_f32_16x16x32_bf16 v[64:67], v[178:181], v[210:213], v[64:67]
	v_mfma_f32_16x16x32_bf16 v[116:119], v[174:177], v[190:193], v[116:119]
	v_mfma_f32_16x16x32_bf16 v[112:115], v[182:185], v[190:193], v[112:115]
	v_mfma_f32_16x16x32_bf16 v[100:103], v[174:177], v[198:201], v[100:103]
	v_mfma_f32_16x16x32_bf16 v[96:99], v[182:185], v[198:201], v[96:99]
	v_mfma_f32_16x16x32_bf16 v[84:87], v[174:177], v[206:209], v[84:87]
	v_mfma_f32_16x16x32_bf16 v[80:83], v[182:185], v[206:209], v[80:83]
	v_mfma_f32_16x16x32_bf16 v[68:71], v[174:177], v[214:217], v[68:71]
	v_mfma_f32_16x16x32_bf16 v[64:67], v[182:185], v[214:217], v[64:67]
	s_setprio 0
	s_barrier
	s_add_i32 s46, s48, s93
	s_mov_b32 m0, s46
	s_add_u32 s98, s24, 0x80
	s_addc_u32 s99, s25, 0
	global_load_lds_dwordx4 v160, s[98:99]
	ds_read_b128 v[186:189], v147 offset:49152
	ds_read_b128 v[190:193], v147 offset:50176
	s_add_i32 m0, s46, 0x2000
	s_add_u32 s24, s24, 0x20080
	s_addc_u32 s25, s25, 0
	s_add_i32 s46, s49, s93
	global_load_lds_dwordx4 v132, s[98:99]
	ds_read_b128 v[194:197], v147 offset:51200
	ds_read_b128 v[198:201], v147 offset:52224
	s_mov_b32 m0, s46
	ds_read_b128 v[202:205], v147 offset:53248
	global_load_lds_dwordx4 v160, s[24:25]
	ds_read_b128 v[206:209], v147 offset:54272
	s_add_i32 m0, s46, 0x2000
	ds_read_b128 v[210:213], v147 offset:55296
	global_load_lds_dwordx4 v132, s[24:25]
	ds_read_b128 v[214:217], v147 offset:56320
	s_mov_b32 m0, s96
	s_add_u32 s98, s82, 0x80
	s_addc_u32 s99, s83, 0
	global_load_lds_dwordx4 v128, s[98:99]
	s_mov_b32 m0, s97
	s_nop 0
	global_load_lds_dwordx4 v130, s[98:99]
	s_waitcnt vmcnt(8)
	s_waitcnt lgkmcnt(0)
	s_barrier
	s_setprio 1
	s_waitcnt lgkmcnt(0)
	v_mfma_f32_16x16x32_bf16 v[60:63], v[138:141], v[186:189], v[60:63]
	v_mfma_f32_16x16x32_bf16 v[56:59], v[152:155], v[186:189], v[56:59]
	v_mfma_f32_16x16x32_bf16 v[44:47], v[138:141], v[194:197], v[44:47]
	v_mfma_f32_16x16x32_bf16 v[40:43], v[152:155], v[194:197], v[40:43]
	v_mfma_f32_16x16x32_bf16 v[28:31], v[138:141], v[202:205], v[28:31]
	v_mfma_f32_16x16x32_bf16 v[24:27], v[152:155], v[202:205], v[24:27]
	v_mfma_f32_16x16x32_bf16 v[12:15], v[138:141], v[210:213], v[12:15]
	v_mfma_f32_16x16x32_bf16 v[8:11], v[152:155], v[210:213], v[8:11]
	v_mfma_f32_16x16x32_bf16 v[60:63], v[148:151], v[190:193], v[60:63]
	v_mfma_f32_16x16x32_bf16 v[56:59], v[156:159], v[190:193], v[56:59]
	v_mfma_f32_16x16x32_bf16 v[44:47], v[148:151], v[198:201], v[44:47]
	v_mfma_f32_16x16x32_bf16 v[40:43], v[156:159], v[198:201], v[40:43]
	v_mfma_f32_16x16x32_bf16 v[28:31], v[148:151], v[206:209], v[28:31]
	v_mfma_f32_16x16x32_bf16 v[24:27], v[156:159], v[206:209], v[24:27]
	v_mfma_f32_16x16x32_bf16 v[12:15], v[148:151], v[214:217], v[12:15]
	v_mfma_f32_16x16x32_bf16 v[8:11], v[156:159], v[214:217], v[8:11]
	s_setprio 0
	s_setprio 1
	v_mfma_f32_16x16x32_bf16 v[52:55], v[170:173], v[186:189], v[52:55]
	v_mfma_f32_16x16x32_bf16 v[48:51], v[178:181], v[186:189], v[48:51]
	v_mfma_f32_16x16x32_bf16 v[36:39], v[170:173], v[194:197], v[36:39]
	v_mfma_f32_16x16x32_bf16 v[32:35], v[178:181], v[194:197], v[32:35]
	v_mfma_f32_16x16x32_bf16 v[20:23], v[170:173], v[202:205], v[20:23]
	v_mfma_f32_16x16x32_bf16 v[16:19], v[178:181], v[202:205], v[16:19]
	v_mfma_f32_16x16x32_bf16 v[4:7], v[170:173], v[210:213], v[4:7]
	v_mfma_f32_16x16x32_bf16 v[0:3], v[178:181], v[210:213], v[0:3]
	v_mfma_f32_16x16x32_bf16 v[52:55], v[174:177], v[190:193], v[52:55]
	v_mfma_f32_16x16x32_bf16 v[48:51], v[182:185], v[190:193], v[48:51]
	v_mfma_f32_16x16x32_bf16 v[36:39], v[174:177], v[198:201], v[36:39]
	v_mfma_f32_16x16x32_bf16 v[32:35], v[182:185], v[198:201], v[32:35]
	v_mfma_f32_16x16x32_bf16 v[20:23], v[174:177], v[206:209], v[20:23]
	v_mfma_f32_16x16x32_bf16 v[16:19], v[182:185], v[206:209], v[16:19]
	v_mfma_f32_16x16x32_bf16 v[4:7], v[174:177], v[214:217], v[4:7]
	v_mfma_f32_16x16x32_bf16 v[0:3], v[182:185], v[214:217], v[0:3]
	s_setprio 0
	s_barrier
	s_add_i32 vcc_hi, vcc_hi, 2
	s_add_u32 s90, s90, 0x100
	s_addc_u32 s91, s91, 0
	s_add_u32 s55, s55, 0x100
	s_addc_u32 vcc_lo, vcc_lo, 0
	s_cmp_gt_u32 vcc_hi, 5
	s_cbranch_scc0 .LBB0_40
	s_and_b64 vcc, exec, s[30:31]
	s_cbranch_vccz .LBB0_43
	s_barrier

; #define PG8_STAGE(bufoff, gbase, voff) do { _Pragma("unroll") for (int _i = 0; _i < 2; ++_i) \
;         __builtin_amdgcn_global_load_lds((const unsigned*)((const char*)(gbase) + (voff)[_i]), (LAS unsigned*)(lds + (bufoff) + ldsw + _i * 8192), 16, 0, 0); } while (0)
; #define PG8_LDA(dst, b, h) do { _Pragma("unroll") for (int m = 0; m < 4; ++m) _Pragma("unroll") for (int k = 0; k < 2; ++k) dst[m][k] = *(const LAS bf16x8*)(lds + PG8_SA(b, h) + aoff + m * 2048 + k * 1024); } while (0)
; #define PG8_LDB(dst, b, h) do { _Pragma("unroll") for (int n = 0; n < 2; ++n) _Pragma("unroll") for (int k = 0; k < 2; ++k) dst[n][k] = *(const LAS bf16x8*)(lds + PG8_SB(b, h) + boff + n * 2048 + k * 1024); } while (0)
; #define PG8_MMA(ai, bj, At, Bt) do { __builtin_amdgcn_s_setprio(1); _Pragma("unroll") for (int m = 0; m < 4; ++m) _Pragma("unroll") for (int n = 0; n < 2; ++n) _Pragma("unroll") for (int k = 0; k < 2; ++k) \
;         acc[ai][bj][m][n] = __builtin_amdgcn_mfma_f32_16x16x32_bf16(Bt[n][k], At[m][k], acc[ai][bj][m][n], 0, 0, 0); __builtin_amdgcn_s_setprio(0); } while (0)
; #define PG8_WAIT_V(n) asm volatile("s_waitcnt vmcnt(" #n ")" ::: "memory")
; #define PG8_WAIT_L(n) asm volatile("s_waitcnt lgkmcnt(" #n ")" ::: "memory")
; #define PG8_BAR __builtin_amdgcn_s_barrier()
; template <class Epi, class Sched, bool ALIGN_EPI = true, bool SP2 = true>
; __device__ __forceinline__ void gemm_phase(LAS unsigned char* lds, const Gemm g, const Sched& S, const Epi& E) {
;     ...
;         for (int t = 0; t < nt; t += 2) {
;             const bool last = (t == nt - 2);
;             const char* a1 = cA + (size_t)(t + 1) * kstep;
;             const char* a2 = last ? nA : cA + (size_t)(t + 2) * kstep; const char* b2 = last ? nB : cB + (size_t)(t + 2) * kstep;
;             const char* a3 = a2 + kstep; const char* b3 = b2 + kstep;
;             if constexpr (SP2) {
;             PG8_LDB(B0, 0, 0); PG8_LDB(B1, 0, 1); PG8_SCHED; PG8_LDA(At, 0, 0); PG8_STAGE(PG8_SA(1, 1), a1 + hstep, voffA);
;             PG8_WAIT_V(8); PG8_WAIT_L(0); PG8_BAR; PG8_MMA(0, 0, At, B0); PG8_MMA(0, 1, At, B1); PG8_BAR; PG8_SCHED;
;             PG8_LDA(At, 0, 1); PG8_STAGE(PG8_SB(0, 0), b2, voffB); PG8_STAGE(PG8_SB(0, 1), b2 + hstep, voffB); PG8_STAGE(PG8_SA(0, 0), a2, voffA);
;             PG8_WAIT_V(8); PG8_WAIT_L(0); PG8_BAR; PG8_MMA(1, 0, At, B0); PG8_MMA(1, 1, At, B1); PG8_BAR; PG8_SCHED;
.LBB0_93:
	s_add_u32 s24, s62, 0xfff80080
	s_addc_u32 s25, s63, -1
	s_add_i32 s46, 0, 0x10000
	s_cmp_eq_u32 s93, 28
	s_cselect_b32 s67, s2, s25
	s_cselect_b32 s66, s3, s24
	s_cselect_b32 s25, s19, s92
	s_cselect_b32 s24, s31, s91
	s_add_i32 s47, 0, 0x14000
	v_add_u32_e32 v154, s46, v143
	v_add_u32_e32 v158, s47, v143
	s_add_i32 m0, s44, 0xc000
	ds_read_b128 v[138:141], v154
	global_load_lds_dwordx4 v134, s[62:63]
	ds_read_b128 v[146:149], v154 offset:1024
	ds_read_b128 v[150:153], v154 offset:2048
	ds_read_b128 v[154:157], v154 offset:3072
	ds_read_b128 v[170:173], v158
	ds_read_b128 v[174:177], v158 offset:1024
	ds_read_b128 v[178:181], v158 offset:2048
	ds_read_b128 v[182:185], v158 offset:3072
	ds_read_b128 v[186:189], v145
	s_add_i32 m0, s44, 0xe000
	ds_read_b128 v[190:193], v145 offset:1024
	global_load_lds_dwordx4 v136, s[62:63]
	ds_read_b128 v[194:197], v145 offset:2048
	ds_read_b128 v[198:201], v145 offset:3072
	ds_read_b128 v[202:205], v145 offset:4096
	ds_read_b128 v[206:209], v145 offset:5120
	ds_read_b128 v[210:213], v145 offset:6144
	ds_read_b128 v[214:217], v145 offset:7168
	s_waitcnt vmcnt(8)
	s_waitcnt lgkmcnt(0)
	s_barrier
	s_setprio 1
	s_waitcnt lgkmcnt(0)
	v_mfma_f32_16x16x32_bf16 v[124:127], v[138:141], v[186:189], v[124:127]
	v_mfma_f32_16x16x32_bf16 v[120:123], v[150:153], v[186:189], v[120:123]
	v_mfma_f32_16x16x32_bf16 v[108:111], v[138:141], v[194:197], v[108:111]
	v_mfma_f32_16x16x32_bf16 v[104:107], v[150:153], v[194:197], v[104:107]
	v_mfma_f32_16x16x32_bf16 v[92:95], v[138:141], v[202:205], v[92:95]
	v_mfma_f32_16x16x32_bf16 v[88:91], v[150:153], v[202:205], v[88:91]
	v_mfma_f32_16x16x32_bf16 v[76:79], v[138:141], v[210:213], v[76:79]
	v_mfma_f32_16x16x32_bf16 v[72:75], v[150:153], v[210:213], v[72:75]
	v_mfma_f32_16x16x32_bf16 v[124:127], v[146:149], v[190:193], v[124:127]
	v_mfma_f32_16x16x32_bf16 v[120:123], v[154:157], v[190:193], v[120:123]
	v_mfma_f32_16x16x32_bf16 v[108:111], v[146:149], v[198:201], v[108:111]
	v_mfma_f32_16x16x32_bf16 v[104:107], v[154:157], v[198:201], v[104:107]
	v_mfma_f32_16x16x32_bf16 v[92:95], v[146:149], v[206:209], v[92:95]
	v_mfma_f32_16x16x32_bf16 v[88:91], v[154:157], v[206:209], v[88:91]
	v_mfma_f32_16x16x32_bf16 v[76:79], v[146:149], v[214:217], v[76:79]
	v_mfma_f32_16x16x32_bf16 v[72:75], v[154:157], v[214:217], v[72:75]
	s_setprio 0
	s_setprio 1
	v_mfma_f32_16x16x32_bf16 v[116:119], v[170:173], v[186:189], v[116:119]
	v_mfma_f32_16x16x32_bf16 v[112:115], v[178:181], v[186:189], v[112:115]
	v_mfma_f32_16x16x32_bf16 v[100:103], v[170:173], v[194:197], v[100:103]
	v_mfma_f32_16x16x32_bf16 v[96:99], v[178:181], v[194:197], v[96:99]
	v_mfma_f32_16x16x32_bf16 v[84:87], v[170:173], v[202:205], v[84:87]
	v_mfma_f32_16x16x32_bf16 v[80:83], v[178:181], v[202:205], v[80:83]
	v_mfma_f32_16x16x32_bf16 v[68:71], v[170:173], v[210:213], v[68:71]
	v_mfma_f32_16x16x32_bf16 v[64:67], v[178:181], v[210:213], v[64:67]
	v_mfma_f32_16x16x32_bf16 v[116:119], v[174:177], v[190:193], v[116:119]
	v_mfma_f32_16x16x32_bf16 v[112:115], v[182:185], v[190:193], v[112:115]
	v_mfma_f32_16x16x32_bf16 v[100:103], v[174:177], v[198:201], v[100:103]
	v_mfma_f32_16x16x32_bf16 v[96:99], v[182:185], v[198:201], v[96:99]
	v_mfma_f32_16x16x32_bf16 v[84:87], v[174:177], v[206:209], v[84:87]
	v_mfma_f32_16x16x32_bf16 v[80:83], v[182:185], v[206:209], v[80:83]
	v_mfma_f32_16x16x32_bf16 v[68:71], v[174:177], v[214:217], v[68:71]
	v_mfma_f32_16x16x32_bf16 v[64:67], v[182:185], v[214:217], v[64:67]
	s_setprio 0
	s_barrier
	s_add_i32 s46, s46, s43
	s_mov_b32 m0, s46
	ds_read_b128 v[186:189], v145 offset:16384
	global_load_lds_dwordx4 v160, s[24:25]
	ds_read_b128 v[190:193], v145 offset:17408
	ds_read_b128 v[194:197], v145 offset:18432
	s_add_i32 m0, s46, 0x2000
	s_add_u32 s94, s24, 0x80000
	s_addc_u32 s95, s25, 0
	s_add_i32 s46, s47, s43
	global_load_lds_dwordx4 v132, s[24:25]
	ds_read_b128 v[198:201], v145 offset:19456
	s_mov_b32 m0, s46
	ds_read_b128 v[202:205], v145 offset:20480
	global_load_lds_dwordx4 v160, s[94:95]
	ds_read_b128 v[206:209], v145 offset:21504
	s_add_i32 m0, s46, 0x2000
	ds_read_b128 v[210:213], v145 offset:22528
	global_load_lds_dwordx4 v132, s[94:95]
	ds_read_b128 v[214:217], v145 offset:23552
	s_mov_b32 m0, s44
	s_nop 0
	global_load_lds_dwordx4 v128, s[66:67]
	s_mov_b32 m0, s45
	s_nop 0
	global_load_lds_dwordx4 v130, s[66:67]
	s_waitcnt vmcnt(8)
	s_waitcnt lgkmcnt(0)
	s_barrier
	s_setprio 1
	s_waitcnt lgkmcnt(0)
	v_mfma_f32_16x16x32_bf16 v[60:63], v[138:141], v[186:189], v[60:63]
	v_mfma_f32_16x16x32_bf16 v[56:59], v[150:153], v[186:189], v[56:59]
	v_mfma_f32_16x16x32_bf16 v[44:47], v[138:141], v[194:197], v[44:47]
	v_mfma_f32_16x16x32_bf16 v[40:43], v[150:153], v[194:197], v[40:43]
	v_mfma_f32_16x16x32_bf16 v[28:31], v[138:141], v[202:205], v[28:31]
	v_mfma_f32_16x16x32_bf16 v[24:27], v[150:153], v[202:205], v[24:27]
	v_mfma_f32_16x16x32_bf16 v[12:15], v[138:141], v[210:213], v[12:15]
	v_mfma_f32_16x16x32_bf16 v[8:11], v[150:153], v[210:213], v[8:11]
	v_mfma_f32_16x16x32_bf16 v[60:63], v[146:149], v[190:193], v[60:63]
	v_mfma_f32_16x16x32_bf16 v[56:59], v[154:157], v[190:193], v[56:59]
	v_mfma_f32_16x16x32_bf16 v[44:47], v[146:149], v[198:201], v[44:47]
	v_mfma_f32_16x16x32_bf16 v[40:43], v[154:157], v[198:201], v[40:43]
	v_mfma_f32_16x16x32_bf16 v[28:31], v[146:149], v[206:209], v[28:31]
	v_mfma_f32_16x16x32_bf16 v[24:27], v[154:157], v[206:209], v[24:27]
	v_mfma_f32_16x16x32_bf16 v[12:15], v[146:149], v[214:217], v[12:15]
	v_mfma_f32_16x16x32_bf16 v[8:11], v[154:157], v[214:217], v[8:11]
	s_setprio 0
	s_setprio 1
	v_mfma_f32_16x16x32_bf16 v[52:55], v[170:173], v[186:189], v[52:55]
	v_mfma_f32_16x16x32_bf16 v[48:51], v[178:181], v[186:189], v[48:51]
	v_mfma_f32_16x16x32_bf16 v[36:39], v[170:173], v[194:197], v[36:39]
	v_mfma_f32_16x16x32_bf16 v[32:35], v[178:181], v[194:197], v[32:35]
	v_mfma_f32_16x16x32_bf16 v[20:23], v[170:173], v[202:205], v[20:23]
	v_mfma_f32_16x16x32_bf16 v[16:19], v[178:181], v[202:205], v[16:19]
	v_mfma_f32_16x16x32_bf16 v[4:7], v[170:173], v[210:213], v[4:7]
	v_mfma_f32_16x16x32_bf16 v[0:3], v[178:181], v[210:213], v[0:3]
	v_mfma_f32_16x16x32_bf16 v[52:55], v[174:177], v[190:193], v[52:55]
	v_mfma_f32_16x16x32_bf16 v[48:51], v[182:185], v[190:193], v[48:51]
	v_mfma_f32_16x16x32_bf16 v[36:39], v[174:177], v[198:201], v[36:39]
	v_mfma_f32_16x16x32_bf16 v[32:35], v[182:185], v[198:201], v[32:35]
	v_mfma_f32_16x16x32_bf16 v[20:23], v[174:177], v[206:209], v[20:23]
	v_mfma_f32_16x16x32_bf16 v[16:19], v[182:185], v[206:209], v[16:19]
	v_mfma_f32_16x16x32_bf16 v[4:7], v[174:177], v[214:217], v[4:7]
	v_mfma_f32_16x16x32_bf16 v[0:3], v[182:185], v[214:217], v[0:3]
	s_setprio 0
	s_barrier
; #define PG8_STAGE(bufoff, gbase, voff) do { _Pragma("unroll") for (int _i = 0; _i < 2; ++_i) \
;         __builtin_amdgcn_global_load_lds((const unsigned*)((const char*)(gbase) + (voff)[_i]), (LAS unsigned*)(lds + (bufoff) + ldsw + _i * 8192), 16, 0, 0); } while (0)
; #define PG8_LDA(dst, b, h) do { _Pragma("unroll") for (int m = 0; m < 4; ++m) _Pragma("unroll") for (int k = 0; k < 2; ++k) dst[m][k] = *(const LAS bf16x8*)(lds + PG8_SA(b, h) + aoff + m * 2048 + k * 1024); } while (0)
; #define PG8_LDB(dst, b, h) do { _Pragma("unroll") for (int n = 0; n < 2; ++n) _Pragma("unroll") for (int k = 0; k < 2; ++k) dst[n][k] = *(const LAS bf16x8*)(lds + PG8_SB(b, h) + boff + n * 2048 + k * 1024); } while (0)
; #define PG8_WAIT_V(n) asm volatile("s_waitcnt vmcnt(" #n ")" ::: "memory")
; #define PG8_WAIT_L(n) asm volatile("s_waitcnt lgkmcnt(" #n ")" ::: "memory")
; template <class Epi, class Sched, bool ALIGN_EPI = true, bool SP2 = true>
; __device__ __forceinline__ void gemm_phase(LAS unsigned char* lds, const Gemm g, const Sched& S, const Epi& E) {
;     ...
;             const char* a1 = cA + (size_t)(t + 1) * kstep;
;             const char* a2 = last ? nA : cA + (size_t)(t + 2) * kstep; const char* b2 = last ? nB : cB + (size_t)(t + 2) * kstep;
;             const char* a3 = a2 + kstep; const char* b3 = b2 + kstep;
;             if constexpr (SP2) {
;             PG8_LDB(B0, 0, 0); PG8_LDB(B1, 0, 1); PG8_SCHED; PG8_LDA(At, 0, 0); PG8_STAGE(PG8_SA(1, 1), a1 + hstep, voffA);
;             PG8_WAIT_V(8); PG8_WAIT_L(0); PG8_BAR; PG8_MMA(0, 0, At, B0); PG8_MMA(0, 1, At, B1); PG8_BAR; PG8_SCHED;
;             PG8_LDA(At, 0, 1); PG8_STAGE(PG8_SB(0, 0), b2, voffB); PG8_STAGE(PG8_SB(0, 1), b2 + hstep, voffB); PG8_STAGE(PG8_SA(0, 0), a2, voffA);
;             PG8_WAIT_V(8); PG8_WAIT_L(0); PG8_BAR; PG8_MMA(1, 0, At, B0); PG8_MMA(1, 1, At, B1); PG8_BAR; PG8_SCHED;
;             PG8_LDB(B0, 1, 0); PG8_LDB(B1, 1, 1); PG8_SCHED; PG8_LDA(At, 1, 0); PG8_STAGE(PG8_SA(0, 1), a2 + hstep, voffA);
;             PG8_WAIT_V(8); PG8_WAIT_L(0); PG8_BAR; PG8_MMA(0, 0, At, B0); PG8_MMA(0, 1, At, B1); PG8_BAR; PG8_SCHED;
;             PG8_LDA(At, 1, 1); PG8_STAGE(PG8_SB(1, 0), b3, voffB); PG8_STAGE(PG8_SB(1, 1), b3 + hstep, voffB); PG8_STAGE(PG8_SA(1, 0), a3, voffA);
;             PG8_WAIT_V(8); PG8_WAIT_L(0); PG8_BAR; PG8_MMA(1, 0, At, B0); PG8_MMA(1, 1, At, B1); PG8_BAR; PG8_SCHED;
	s_add_i32 s46, 0, 0x18000
	s_add_i32 s47, 0, 0x1c000
	v_add_u32_e32 v154, s46, v143
	v_add_u32_e32 v182, s47, v143
	s_add_u32 s66, s66, 0x80000
	s_addc_u32 s67, s67, 0
	s_mov_b32 m0, s61
	ds_read_b128 v[138:141], v154
	global_load_lds_dwordx4 v128, s[66:67]
	ds_read_b128 v[146:149], v154 offset:1024
	ds_read_b128 v[150:153], v154 offset:2048
	ds_read_b128 v[154:157], v154 offset:3072
	ds_read_b128 v[170:173], v182
	ds_read_b128 v[174:177], v182 offset:1024
	ds_read_b128 v[178:181], v182 offset:2048
	ds_read_b128 v[182:185], v182 offset:3072
	ds_read_b128 v[186:189], v145 offset:32768
	s_mov_b32 m0, s72
	ds_read_b128 v[190:193], v145 offset:33792
	global_load_lds_dwordx4 v130, s[66:67]
	ds_read_b128 v[194:197], v145 offset:34816
	ds_read_b128 v[198:201], v145 offset:35840
	ds_read_b128 v[202:205], v145 offset:36864
	ds_read_b128 v[206:209], v145 offset:37888
	ds_read_b128 v[210:213], v145 offset:38912
	ds_read_b128 v[214:217], v145 offset:39936
	s_waitcnt vmcnt(8)
	s_waitcnt lgkmcnt(0)
	s_barrier
	s_setprio 1
	s_waitcnt lgkmcnt(0)
	v_mfma_f32_16x16x32_bf16 v[124:127], v[138:141], v[186:189], v[124:127]
	v_mfma_f32_16x16x32_bf16 v[120:123], v[150:153], v[186:189], v[120:123]
	v_mfma_f32_16x16x32_bf16 v[108:111], v[138:141], v[194:197], v[108:111]
	v_mfma_f32_16x16x32_bf16 v[104:107], v[150:153], v[194:197], v[104:107]
	v_mfma_f32_16x16x32_bf16 v[92:95], v[138:141], v[202:205], v[92:95]
	v_mfma_f32_16x16x32_bf16 v[88:91], v[150:153], v[202:205], v[88:91]
	v_mfma_f32_16x16x32_bf16 v[76:79], v[138:141], v[210:213], v[76:79]
	v_mfma_f32_16x16x32_bf16 v[72:75], v[150:153], v[210:213], v[72:75]
	v_mfma_f32_16x16x32_bf16 v[124:127], v[146:149], v[190:193], v[124:127]
	v_mfma_f32_16x16x32_bf16 v[120:123], v[154:157], v[190:193], v[120:123]
	v_mfma_f32_16x16x32_bf16 v[108:111], v[146:149], v[198:201], v[108:111]
	v_mfma_f32_16x16x32_bf16 v[104:107], v[154:157], v[198:201], v[104:107]
	v_mfma_f32_16x16x32_bf16 v[92:95], v[146:149], v[206:209], v[92:95]
	v_mfma_f32_16x16x32_bf16 v[88:91], v[154:157], v[206:209], v[88:91]
	v_mfma_f32_16x16x32_bf16 v[76:79], v[146:149], v[214:217], v[76:79]
	v_mfma_f32_16x16x32_bf16 v[72:75], v[154:157], v[214:217], v[72:75]
	s_setprio 0
	s_setprio 1
	v_mfma_f32_16x16x32_bf16 v[116:119], v[170:173], v[186:189], v[116:119]
	v_mfma_f32_16x16x32_bf16 v[112:115], v[178:181], v[186:189], v[112:115]
	v_mfma_f32_16x16x32_bf16 v[100:103], v[170:173], v[194:197], v[100:103]
	v_mfma_f32_16x16x32_bf16 v[96:99], v[178:181], v[194:197], v[96:99]
	v_mfma_f32_16x16x32_bf16 v[84:87], v[170:173], v[202:205], v[84:87]
	v_mfma_f32_16x16x32_bf16 v[80:83], v[178:181], v[202:205], v[80:83]
	v_mfma_f32_16x16x32_bf16 v[68:71], v[170:173], v[210:213], v[68:71]
	v_mfma_f32_16x16x32_bf16 v[64:67], v[178:181], v[210:213], v[64:67]
	v_mfma_f32_16x16x32_bf16 v[116:119], v[174:177], v[190:193], v[116:119]
	v_mfma_f32_16x16x32_bf16 v[112:115], v[182:185], v[190:193], v[112:115]
	v_mfma_f32_16x16x32_bf16 v[100:103], v[174:177], v[198:201], v[100:103]
	v_mfma_f32_16x16x32_bf16 v[96:99], v[182:185], v[198:201], v[96:99]
	v_mfma_f32_16x16x32_bf16 v[84:87], v[174:177], v[206:209], v[84:87]
	v_mfma_f32_16x16x32_bf16 v[80:83], v[182:185], v[206:209], v[80:83]
	v_mfma_f32_16x16x32_bf16 v[68:71], v[174:177], v[214:217], v[68:71]
	v_mfma_f32_16x16x32_bf16 v[64:67], v[182:185], v[214:217], v[64:67]
	s_setprio 0
	s_barrier
	s_add_i32 s46, s46, s43
	s_mov_b32 m0, s46
	s_add_u32 s98, s24, 0x80
	s_addc_u32 s99, s25, 0
	global_load_lds_dwordx4 v160, s[98:99]
	ds_read_b128 v[186:189], v145 offset:49152
	ds_read_b128 v[190:193], v145 offset:50176
	s_add_i32 m0, s46, 0x2000
	s_add_u32 s24, s24, 0x80080
	s_addc_u32 s25, s25, 0
	s_add_i32 s46, s47, s43
	global_load_lds_dwordx4 v132, s[98:99]
	ds_read_b128 v[194:197], v145 offset:51200
	ds_read_b128 v[198:201], v145 offset:52224
	s_mov_b32 m0, s46
	ds_read_b128 v[202:205], v145 offset:53248
	global_load_lds_dwordx4 v160, s[24:25]
	ds_read_b128 v[206:209], v145 offset:54272
	s_add_i32 m0, s46, 0x2000
	ds_read_b128 v[210:213], v145 offset:55296
	global_load_lds_dwordx4 v132, s[24:25]
	ds_read_b128 v[214:217], v145 offset:56320
	s_mov_b32 m0, s73
	s_add_u32 s98, s66, 0xfff80080
	s_addc_u32 s99, s67, -1
	global_load_lds_dwordx4 v128, s[98:99]
	s_mov_b32 m0, s79
	s_nop 0
	global_load_lds_dwordx4 v130, s[98:99]
	s_waitcnt vmcnt(8)
	s_waitcnt lgkmcnt(0)
	s_barrier
	s_setprio 1
	s_waitcnt lgkmcnt(0)
	v_mfma_f32_16x16x32_bf16 v[60:63], v[138:141], v[186:189], v[60:63]
	v_mfma_f32_16x16x32_bf16 v[56:59], v[150:153], v[186:189], v[56:59]
	v_mfma_f32_16x16x32_bf16 v[44:47], v[138:141], v[194:197], v[44:47]
	v_mfma_f32_16x16x32_bf16 v[40:43], v[150:153], v[194:197], v[40:43]
	v_mfma_f32_16x16x32_bf16 v[28:31], v[138:141], v[202:205], v[28:31]
	v_mfma_f32_16x16x32_bf16 v[24:27], v[150:153], v[202:205], v[24:27]
	v_mfma_f32_16x16x32_bf16 v[12:15], v[138:141], v[210:213], v[12:15]
	v_mfma_f32_16x16x32_bf16 v[8:11], v[150:153], v[210:213], v[8:11]
	v_mfma_f32_16x16x32_bf16 v[60:63], v[146:149], v[190:193], v[60:63]
	v_mfma_f32_16x16x32_bf16 v[56:59], v[154:157], v[190:193], v[56:59]
	v_mfma_f32_16x16x32_bf16 v[44:47], v[146:149], v[198:201], v[44:47]
	v_mfma_f32_16x16x32_bf16 v[40:43], v[154:157], v[198:201], v[40:43]
	v_mfma_f32_16x16x32_bf16 v[28:31], v[146:149], v[206:209], v[28:31]
	v_mfma_f32_16x16x32_bf16 v[24:27], v[154:157], v[206:209], v[24:27]
	v_mfma_f32_16x16x32_bf16 v[12:15], v[146:149], v[214:217], v[12:15]
	v_mfma_f32_16x16x32_bf16 v[8:11], v[154:157], v[214:217], v[8:11]
	s_setprio 0
	s_setprio 1
	v_mfma_f32_16x16x32_bf16 v[52:55], v[170:173], v[186:189], v[52:55]
	v_mfma_f32_16x16x32_bf16 v[48:51], v[178:181], v[186:189], v[48:51]
	v_mfma_f32_16x16x32_bf16 v[36:39], v[170:173], v[194:197], v[36:39]
	v_mfma_f32_16x16x32_bf16 v[32:35], v[178:181], v[194:197], v[32:35]
	v_mfma_f32_16x16x32_bf16 v[20:23], v[170:173], v[202:205], v[20:23]
	v_mfma_f32_16x16x32_bf16 v[16:19], v[178:181], v[202:205], v[16:19]
	v_mfma_f32_16x16x32_bf16 v[4:7], v[170:173], v[210:213], v[4:7]
	v_mfma_f32_16x16x32_bf16 v[0:3], v[178:181], v[210:213], v[0:3]
	v_mfma_f32_16x16x32_bf16 v[52:55], v[174:177], v[190:193], v[52:55]
	v_mfma_f32_16x16x32_bf16 v[48:51], v[182:185], v[190:193], v[48:51]
	v_mfma_f32_16x16x32_bf16 v[36:39], v[174:177], v[198:201], v[36:39]
	v_mfma_f32_16x16x32_bf16 v[32:35], v[182:185], v[198:201], v[32:35]
	v_mfma_f32_16x16x32_bf16 v[20:23], v[174:177], v[206:209], v[20:23]
	v_mfma_f32_16x16x32_bf16 v[16:19], v[182:185], v[206:209], v[16:19]
	v_mfma_f32_16x16x32_bf16 v[4:7], v[174:177], v[214:217], v[4:7]
	v_mfma_f32_16x16x32_bf16 v[0:3], v[182:185], v[214:217], v[0:3]
	s_setprio 0
	s_barrier
	s_add_i32 s93, s93, 2
	s_add_u32 s62, s62, 0x100
	s_addc_u32 s63, s63, 0
	s_add_u32 s91, s91, 0x100
	s_addc_u32 s92, s92, 0
	s_cmp_gt_u32 s93, 29
	s_cbranch_scc0 .LBB0_93
	s_and_b64 vcc, exec, s[16:17]
	s_movk_i32 s91, 0x161
	s_movk_i32 s92, 0x7ff
	s_cbranch_vccz .LBB0_96
	s_barrier

; #define PG8_STAGE(bufoff, gbase, voff) do { _Pragma("unroll") for (int _i = 0; _i < 2; ++_i) \
;         __builtin_amdgcn_global_load_lds((const unsigned*)((const char*)(gbase) + (voff)[_i]), (LAS unsigned*)(lds + (bufoff) + ldsw + _i * 8192), 16, 0, 0); } while (0)
; #define PG8_LDA(dst, b, h) do { _Pragma("unroll") for (int m = 0; m < 4; ++m) _Pragma("unroll") for (int k = 0; k < 2; ++k) dst[m][k] = *(const LAS bf16x8*)(lds + PG8_SA(b, h) + aoff + m * 2048 + k * 1024); } while (0)
; #define PG8_LDB(dst, b, h) do { _Pragma("unroll") for (int n = 0; n < 2; ++n) _Pragma("unroll") for (int k = 0; k < 2; ++k) dst[n][k] = *(const LAS bf16x8*)(lds + PG8_SB(b, h) + boff + n * 2048 + k * 1024); } while (0)
; #define PG8_MMA(ai, bj, At, Bt) do { __builtin_amdgcn_s_setprio(1); _Pragma("unroll") for (int m = 0; m < 4; ++m) _Pragma("unroll") for (int n = 0; n < 2; ++n) _Pragma("unroll") for (int k = 0; k < 2; ++k) \
;         acc[ai][bj][m][n] = __builtin_amdgcn_mfma_f32_16x16x32_bf16(Bt[n][k], At[m][k], acc[ai][bj][m][n], 0, 0, 0); __builtin_amdgcn_s_setprio(0); } while (0)
; #define PG8_WAIT_V(n) asm volatile("s_waitcnt vmcnt(" #n ")" ::: "memory")
; #define PG8_WAIT_L(n) asm volatile("s_waitcnt lgkmcnt(" #n ")" ::: "memory")
; #define PG8_BAR __builtin_amdgcn_s_barrier()
; #define PG8_SCHED __builtin_amdgcn_sched_barrier(0)
; template <class Epi, class Sched, bool ALIGN_EPI = true, bool SP2 = true>
; __device__ __forceinline__ void gemm_phase(LAS unsigned char* lds, const Gemm g, const Sched& S, const Epi& E) {
;     ...
;             const char* a1 = cA + (size_t)(t + 1) * kstep;
;             const char* a2 = last ? nA : cA + (size_t)(t + 2) * kstep; const char* b2 = last ? nB : cB + (size_t)(t + 2) * kstep;
;             const char* a3 = a2 + kstep; const char* b3 = b2 + kstep;
;             if constexpr (SP2) {
;             PG8_LDB(B0, 0, 0); PG8_LDB(B1, 0, 1); PG8_SCHED; PG8_LDA(At, 0, 0); PG8_STAGE(PG8_SA(1, 1), a1 + hstep, voffA);
;             PG8_WAIT_V(8); PG8_WAIT_L(0); PG8_BAR; PG8_MMA(0, 0, At, B0); PG8_MMA(0, 1, At, B1); PG8_BAR; PG8_SCHED;
;             PG8_LDA(At, 0, 1); PG8_STAGE(PG8_SB(0, 0), b2, voffB); PG8_STAGE(PG8_SB(0, 1), b2 + hstep, voffB); PG8_STAGE(PG8_SA(0, 0), a2, voffA);
;             PG8_WAIT_V(8); PG8_WAIT_L(0); PG8_BAR; PG8_MMA(1, 0, At, B0); PG8_MMA(1, 1, At, B1); PG8_BAR; PG8_SCHED;
.LBB0_117:
	s_add_u32 s24, s62, 0xfff80080
	s_addc_u32 s25, s63, -1
	s_add_i32 s46, 0, 0x10000
	s_cmp_eq_u32 s96, 28
	s_cselect_b32 s67, s2, s25
	s_cselect_b32 s66, s3, s24
	s_cselect_b32 s25, s17, s95
	s_cselect_b32 s24, s19, s94
	s_add_i32 s47, 0, 0x14000
	v_add_u32_e32 v154, s46, v143
	v_add_u32_e32 v158, s47, v143
	s_add_i32 m0, s61, 0xc000
	ds_read_b128 v[138:141], v154
	global_load_lds_dwordx4 v134, s[62:63]
	ds_read_b128 v[146:149], v154 offset:1024
	ds_read_b128 v[150:153], v154 offset:2048
	ds_read_b128 v[154:157], v154 offset:3072
	ds_read_b128 v[170:173], v158
	ds_read_b128 v[174:177], v158 offset:1024
	ds_read_b128 v[178:181], v158 offset:2048
	ds_read_b128 v[182:185], v158 offset:3072
	ds_read_b128 v[186:189], v145
	s_add_i32 m0, s61, 0xe000
	ds_read_b128 v[190:193], v145 offset:1024
	global_load_lds_dwordx4 v136, s[62:63]
	ds_read_b128 v[194:197], v145 offset:2048
	ds_read_b128 v[198:201], v145 offset:3072
	ds_read_b128 v[202:205], v145 offset:4096
	ds_read_b128 v[206:209], v145 offset:5120
	ds_read_b128 v[210:213], v145 offset:6144
	ds_read_b128 v[214:217], v145 offset:7168
	s_waitcnt vmcnt(8)
	s_waitcnt lgkmcnt(0)
	s_barrier
	s_setprio 1
	s_waitcnt lgkmcnt(0)
	v_mfma_f32_16x16x32_bf16 v[124:127], v[138:141], v[186:189], v[124:127]
	v_mfma_f32_16x16x32_bf16 v[120:123], v[150:153], v[186:189], v[120:123]
	v_mfma_f32_16x16x32_bf16 v[108:111], v[138:141], v[194:197], v[108:111]
	v_mfma_f32_16x16x32_bf16 v[104:107], v[150:153], v[194:197], v[104:107]
	v_mfma_f32_16x16x32_bf16 v[92:95], v[138:141], v[202:205], v[92:95]
	v_mfma_f32_16x16x32_bf16 v[88:91], v[150:153], v[202:205], v[88:91]
	v_mfma_f32_16x16x32_bf16 v[76:79], v[138:141], v[210:213], v[76:79]
	v_mfma_f32_16x16x32_bf16 v[72:75], v[150:153], v[210:213], v[72:75]
	v_mfma_f32_16x16x32_bf16 v[124:127], v[146:149], v[190:193], v[124:127]
	v_mfma_f32_16x16x32_bf16 v[120:123], v[154:157], v[190:193], v[120:123]
	v_mfma_f32_16x16x32_bf16 v[108:111], v[146:149], v[198:201], v[108:111]
	v_mfma_f32_16x16x32_bf16 v[104:107], v[154:157], v[198:201], v[104:107]
	v_mfma_f32_16x16x32_bf16 v[92:95], v[146:149], v[206:209], v[92:95]
	v_mfma_f32_16x16x32_bf16 v[88:91], v[154:157], v[206:209], v[88:91]
	v_mfma_f32_16x16x32_bf16 v[76:79], v[146:149], v[214:217], v[76:79]
	v_mfma_f32_16x16x32_bf16 v[72:75], v[154:157], v[214:217], v[72:75]
	s_setprio 0
	s_setprio 1
	v_mfma_f32_16x16x32_bf16 v[116:119], v[170:173], v[186:189], v[116:119]
	v_mfma_f32_16x16x32_bf16 v[112:115], v[178:181], v[186:189], v[112:115]
	v_mfma_f32_16x16x32_bf16 v[100:103], v[170:173], v[194:197], v[100:103]
	v_mfma_f32_16x16x32_bf16 v[96:99], v[178:181], v[194:197], v[96:99]
	v_mfma_f32_16x16x32_bf16 v[84:87], v[170:173], v[202:205], v[84:87]
	v_mfma_f32_16x16x32_bf16 v[80:83], v[178:181], v[202:205], v[80:83]
	v_mfma_f32_16x16x32_bf16 v[68:71], v[170:173], v[210:213], v[68:71]
	v_mfma_f32_16x16x32_bf16 v[64:67], v[178:181], v[210:213], v[64:67]
	v_mfma_f32_16x16x32_bf16 v[116:119], v[174:177], v[190:193], v[116:119]
	v_mfma_f32_16x16x32_bf16 v[112:115], v[182:185], v[190:193], v[112:115]
	v_mfma_f32_16x16x32_bf16 v[100:103], v[174:177], v[198:201], v[100:103]
	v_mfma_f32_16x16x32_bf16 v[96:99], v[182:185], v[198:201], v[96:99]
	v_mfma_f32_16x16x32_bf16 v[84:87], v[174:177], v[206:209], v[84:87]
	v_mfma_f32_16x16x32_bf16 v[80:83], v[182:185], v[206:209], v[80:83]
	v_mfma_f32_16x16x32_bf16 v[68:71], v[174:177], v[214:217], v[68:71]
	v_mfma_f32_16x16x32_bf16 v[64:67], v[182:185], v[214:217], v[64:67]
	s_setprio 0
	s_barrier
	s_add_i32 s46, s46, s44
	s_mov_b32 m0, s46
	ds_read_b128 v[186:189], v145 offset:16384
	global_load_lds_dwordx4 v160, s[24:25]
	ds_read_b128 v[190:193], v145 offset:17408
	ds_read_b128 v[194:197], v145 offset:18432
	s_add_i32 m0, s46, 0x2000
	s_add_u32 vcc_lo, s24, 0x80000
	s_addc_u32 vcc_hi, s25, 0
	s_add_i32 s46, s47, s44
	global_load_lds_dwordx4 v132, s[24:25]
	ds_read_b128 v[198:201], v145 offset:19456
	v_lshl_add_u64 v[218:219], vcc, 0, v[160:161]
	s_mov_b32 m0, s46
	ds_read_b128 v[202:205], v145 offset:20480
	global_load_lds_dwordx4 v[218:219], off
	ds_read_b128 v[206:209], v145 offset:21504
	v_lshl_add_u64 v[218:219], vcc, 0, v[132:133]
	s_add_i32 m0, s46, 0x2000
	ds_read_b128 v[210:213], v145 offset:22528
	global_load_lds_dwordx4 v[218:219], off
	ds_read_b128 v[214:217], v145 offset:23552
	s_mov_b32 m0, s61
	s_nop 0
	global_load_lds_dwordx4 v128, s[66:67]
	s_mov_b32 m0, s73
	s_nop 0
	global_load_lds_dwordx4 v130, s[66:67]
	s_waitcnt vmcnt(8)
	s_waitcnt lgkmcnt(0)
	s_barrier
; #define PG8_STAGE(bufoff, gbase, voff) do { _Pragma("unroll") for (int _i = 0; _i < 2; ++_i) \
;         __builtin_amdgcn_global_load_lds((const unsigned*)((const char*)(gbase) + (voff)[_i]), (LAS unsigned*)(lds + (bufoff) + ldsw + _i * 8192), 16, 0, 0); } while (0)
; #define PG8_LDA(dst, b, h) do { _Pragma("unroll") for (int m = 0; m < 4; ++m) _Pragma("unroll") for (int k = 0; k < 2; ++k) dst[m][k] = *(const LAS bf16x8*)(lds + PG8_SA(b, h) + aoff + m * 2048 + k * 1024); } while (0)
; #define PG8_LDB(dst, b, h) do { _Pragma("unroll") for (int n = 0; n < 2; ++n) _Pragma("unroll") for (int k = 0; k < 2; ++k) dst[n][k] = *(const LAS bf16x8*)(lds + PG8_SB(b, h) + boff + n * 2048 + k * 1024); } while (0)
; #define PG8_MMA(ai, bj, At, Bt) do { __builtin_amdgcn_s_setprio(1); _Pragma("unroll") for (int m = 0; m < 4; ++m) _Pragma("unroll") for (int n = 0; n < 2; ++n) _Pragma("unroll") for (int k = 0; k < 2; ++k) \
;         acc[ai][bj][m][n] = __builtin_amdgcn_mfma_f32_16x16x32_bf16(Bt[n][k], At[m][k], acc[ai][bj][m][n], 0, 0, 0); __builtin_amdgcn_s_setprio(0); } while (0)
; #define PG8_WAIT_V(n) asm volatile("s_waitcnt vmcnt(" #n ")" ::: "memory")
; #define PG8_WAIT_L(n) asm volatile("s_waitcnt lgkmcnt(" #n ")" ::: "memory")
; #define PG8_BAR __builtin_amdgcn_s_barrier()
; #define PG8_SCHED __builtin_amdgcn_sched_barrier(0)
; template <class Epi, class Sched, bool ALIGN_EPI = true, bool SP2 = true>
; __device__ __forceinline__ void gemm_phase(LAS unsigned char* lds, const Gemm g, const Sched& S, const Epi& E) {
;     ...
;             PG8_WAIT_V(8); PG8_WAIT_L(0); PG8_BAR; PG8_MMA(1, 0, At, B0); PG8_MMA(1, 1, At, B1); PG8_BAR; PG8_SCHED;
;             PG8_LDB(B0, 1, 0); PG8_LDB(B1, 1, 1); PG8_SCHED; PG8_LDA(At, 1, 0); PG8_STAGE(PG8_SA(0, 1), a2 + hstep, voffA);
;             PG8_WAIT_V(8); PG8_WAIT_L(0); PG8_BAR; PG8_MMA(0, 0, At, B0); PG8_MMA(0, 1, At, B1); PG8_BAR; PG8_SCHED;
	s_setprio 1
	s_waitcnt lgkmcnt(0)
	v_mfma_f32_16x16x32_bf16 v[60:63], v[138:141], v[186:189], v[60:63]
	v_mfma_f32_16x16x32_bf16 v[56:59], v[150:153], v[186:189], v[56:59]
	v_mfma_f32_16x16x32_bf16 v[44:47], v[138:141], v[194:197], v[44:47]
	v_mfma_f32_16x16x32_bf16 v[40:43], v[150:153], v[194:197], v[40:43]
	v_mfma_f32_16x16x32_bf16 v[28:31], v[138:141], v[202:205], v[28:31]
	v_mfma_f32_16x16x32_bf16 v[24:27], v[150:153], v[202:205], v[24:27]
	v_mfma_f32_16x16x32_bf16 v[12:15], v[138:141], v[210:213], v[12:15]
	v_mfma_f32_16x16x32_bf16 v[8:11], v[150:153], v[210:213], v[8:11]
	v_mfma_f32_16x16x32_bf16 v[60:63], v[146:149], v[190:193], v[60:63]
	v_mfma_f32_16x16x32_bf16 v[56:59], v[154:157], v[190:193], v[56:59]
	v_mfma_f32_16x16x32_bf16 v[44:47], v[146:149], v[198:201], v[44:47]
	v_mfma_f32_16x16x32_bf16 v[40:43], v[154:157], v[198:201], v[40:43]
	v_mfma_f32_16x16x32_bf16 v[28:31], v[146:149], v[206:209], v[28:31]
	v_mfma_f32_16x16x32_bf16 v[24:27], v[154:157], v[206:209], v[24:27]
	v_mfma_f32_16x16x32_bf16 v[12:15], v[146:149], v[214:217], v[12:15]
	v_mfma_f32_16x16x32_bf16 v[8:11], v[154:157], v[214:217], v[8:11]
	s_setprio 0
	s_setprio 1
	v_mfma_f32_16x16x32_bf16 v[52:55], v[170:173], v[186:189], v[52:55]
	v_mfma_f32_16x16x32_bf16 v[48:51], v[178:181], v[186:189], v[48:51]
	v_mfma_f32_16x16x32_bf16 v[36:39], v[170:173], v[194:197], v[36:39]
	v_mfma_f32_16x16x32_bf16 v[32:35], v[178:181], v[194:197], v[32:35]
	v_mfma_f32_16x16x32_bf16 v[20:23], v[170:173], v[202:205], v[20:23]
	v_mfma_f32_16x16x32_bf16 v[16:19], v[178:181], v[202:205], v[16:19]
	v_mfma_f32_16x16x32_bf16 v[4:7], v[170:173], v[210:213], v[4:7]
	v_mfma_f32_16x16x32_bf16 v[0:3], v[178:181], v[210:213], v[0:3]
	v_mfma_f32_16x16x32_bf16 v[52:55], v[174:177], v[190:193], v[52:55]
	v_mfma_f32_16x16x32_bf16 v[48:51], v[182:185], v[190:193], v[48:51]
	v_mfma_f32_16x16x32_bf16 v[36:39], v[174:177], v[198:201], v[36:39]
	v_mfma_f32_16x16x32_bf16 v[32:35], v[182:185], v[198:201], v[32:35]
	v_mfma_f32_16x16x32_bf16 v[20:23], v[174:177], v[206:209], v[20:23]
	v_mfma_f32_16x16x32_bf16 v[16:19], v[182:185], v[206:209], v[16:19]
	v_mfma_f32_16x16x32_bf16 v[4:7], v[174:177], v[214:217], v[4:7]
	v_mfma_f32_16x16x32_bf16 v[0:3], v[182:185], v[214:217], v[0:3]
	s_setprio 0
	s_barrier
	s_add_i32 s46, 0, 0x18000
	s_add_i32 s47, 0, 0x1c000
	v_add_u32_e32 v154, s46, v143
	v_add_u32_e32 v182, s47, v143
	s_add_u32 s66, s66, 0x80000
	s_addc_u32 s67, s67, 0
	s_mov_b32 m0, s79
	ds_read_b128 v[138:141], v154
	global_load_lds_dwordx4 v128, s[66:67]
	ds_read_b128 v[146:149], v154 offset:1024
	ds_read_b128 v[150:153], v154 offset:2048
	ds_read_b128 v[154:157], v154 offset:3072
	ds_read_b128 v[170:173], v182
	ds_read_b128 v[174:177], v182 offset:1024
	ds_read_b128 v[178:181], v182 offset:2048
	ds_read_b128 v[182:185], v182 offset:3072
	ds_read_b128 v[186:189], v145 offset:32768
	s_mov_b32 m0, s82
	ds_read_b128 v[190:193], v145 offset:33792
	global_load_lds_dwordx4 v130, s[66:67]
	ds_read_b128 v[194:197], v145 offset:34816
	ds_read_b128 v[198:201], v145 offset:35840
	ds_read_b128 v[202:205], v145 offset:36864
	ds_read_b128 v[206:209], v145 offset:37888
	ds_read_b128 v[210:213], v145 offset:38912
	ds_read_b128 v[214:217], v145 offset:39936
	s_waitcnt vmcnt(8)
	s_waitcnt lgkmcnt(0)
	s_barrier
	s_setprio 1
	s_waitcnt lgkmcnt(0)
	v_mfma_f32_16x16x32_bf16 v[124:127], v[138:141], v[186:189], v[124:127]
	v_mfma_f32_16x16x32_bf16 v[120:123], v[150:153], v[186:189], v[120:123]
	v_mfma_f32_16x16x32_bf16 v[108:111], v[138:141], v[194:197], v[108:111]
	v_mfma_f32_16x16x32_bf16 v[104:107], v[150:153], v[194:197], v[104:107]
	v_mfma_f32_16x16x32_bf16 v[92:95], v[138:141], v[202:205], v[92:95]
	v_mfma_f32_16x16x32_bf16 v[88:91], v[150:153], v[202:205], v[88:91]
	v_mfma_f32_16x16x32_bf16 v[76:79], v[138:141], v[210:213], v[76:79]
	v_mfma_f32_16x16x32_bf16 v[72:75], v[150:153], v[210:213], v[72:75]
	v_mfma_f32_16x16x32_bf16 v[124:127], v[146:149], v[190:193], v[124:127]
	v_mfma_f32_16x16x32_bf16 v[120:123], v[154:157], v[190:193], v[120:123]
	v_mfma_f32_16x16x32_bf16 v[108:111], v[146:149], v[198:201], v[108:111]
	v_mfma_f32_16x16x32_bf16 v[104:107], v[154:157], v[198:201], v[104:107]
	v_mfma_f32_16x16x32_bf16 v[92:95], v[146:149], v[206:209], v[92:95]
	v_mfma_f32_16x16x32_bf16 v[88:91], v[154:157], v[206:209], v[88:91]
	v_mfma_f32_16x16x32_bf16 v[76:79], v[146:149], v[214:217], v[76:79]
	v_mfma_f32_16x16x32_bf16 v[72:75], v[154:157], v[214:217], v[72:75]
	s_setprio 0
	s_setprio 1
	v_mfma_f32_16x16x32_bf16 v[116:119], v[170:173], v[186:189], v[116:119]
	v_mfma_f32_16x16x32_bf16 v[112:115], v[178:181], v[186:189], v[112:115]
	v_mfma_f32_16x16x32_bf16 v[100:103], v[170:173], v[194:197], v[100:103]
	v_mfma_f32_16x16x32_bf16 v[96:99], v[178:181], v[194:197], v[96:99]
	v_mfma_f32_16x16x32_bf16 v[84:87], v[170:173], v[202:205], v[84:87]
	v_mfma_f32_16x16x32_bf16 v[80:83], v[178:181], v[202:205], v[80:83]
	v_mfma_f32_16x16x32_bf16 v[68:71], v[170:173], v[210:213], v[68:71]
	v_mfma_f32_16x16x32_bf16 v[64:67], v[178:181], v[210:213], v[64:67]
	v_mfma_f32_16x16x32_bf16 v[116:119], v[174:177], v[190:193], v[116:119]
	v_mfma_f32_16x16x32_bf16 v[112:115], v[182:185], v[190:193], v[112:115]
	v_mfma_f32_16x16x32_bf16 v[100:103], v[174:177], v[198:201], v[100:103]
	v_mfma_f32_16x16x32_bf16 v[96:99], v[182:185], v[198:201], v[96:99]
	v_mfma_f32_16x16x32_bf16 v[84:87], v[174:177], v[206:209], v[84:87]
	v_mfma_f32_16x16x32_bf16 v[80:83], v[182:185], v[206:209], v[80:83]
	v_mfma_f32_16x16x32_bf16 v[68:71], v[174:177], v[214:217], v[68:71]
	v_mfma_f32_16x16x32_bf16 v[64:67], v[182:185], v[214:217], v[64:67]
	s_setprio 0
	s_barrier
; #define PG8_STAGE(bufoff, gbase, voff) do { _Pragma("unroll") for (int _i = 0; _i < 2; ++_i) \
;         __builtin_amdgcn_global_load_lds((const unsigned*)((const char*)(gbase) + (voff)[_i]), (LAS unsigned*)(lds + (bufoff) + ldsw + _i * 8192), 16, 0, 0); } while (0)
; #define PG8_LDA(dst, b, h) do { _Pragma("unroll") for (int m = 0; m < 4; ++m) _Pragma("unroll") for (int k = 0; k < 2; ++k) dst[m][k] = *(const LAS bf16x8*)(lds + PG8_SA(b, h) + aoff + m * 2048 + k * 1024); } while (0)
; #define PG8_MMA(ai, bj, At, Bt) do { __builtin_amdgcn_s_setprio(1); _Pragma("unroll") for (int m = 0; m < 4; ++m) _Pragma("unroll") for (int n = 0; n < 2; ++n) _Pragma("unroll") for (int k = 0; k < 2; ++k) \
;         acc[ai][bj][m][n] = __builtin_amdgcn_mfma_f32_16x16x32_bf16(Bt[n][k], At[m][k], acc[ai][bj][m][n], 0, 0, 0); __builtin_amdgcn_s_setprio(0); } while (0)
; #define PG8_WAIT_V(n) asm volatile("s_waitcnt vmcnt(" #n ")" ::: "memory")
; #define PG8_WAIT_L(n) asm volatile("s_waitcnt lgkmcnt(" #n ")" ::: "memory")
; #define PG8_BAR __builtin_amdgcn_s_barrier()
; #define PG8_SCHED __builtin_amdgcn_sched_barrier(0)
; template <class Epi, class Sched, bool ALIGN_EPI = true, bool SP2 = true>
; __device__ __forceinline__ void gemm_phase(LAS unsigned char* lds, const Gemm g, const Sched& S, const Epi& E) {
;     ...
;         for (int t = 0; t < nt; t += 2) {
;     ...
;             PG8_LDA(At, 1, 1); PG8_STAGE(PG8_SB(1, 0), b3, voffB); PG8_STAGE(PG8_SB(1, 1), b3 + hstep, voffB); PG8_STAGE(PG8_SA(1, 0), a3, voffA);
;             PG8_WAIT_V(8); PG8_WAIT_L(0); PG8_BAR; PG8_MMA(1, 0, At, B0); PG8_MMA(1, 1, At, B1); PG8_BAR; PG8_SCHED;
	s_add_i32 s46, s46, s44
	s_mov_b32 m0, s46
	s_add_u32 s98, s24, 0x80
	s_addc_u32 s99, s25, 0
	global_load_lds_dwordx4 v160, s[98:99]
	ds_read_b128 v[186:189], v145 offset:49152
	ds_read_b128 v[190:193], v145 offset:50176
	s_add_i32 m0, s46, 0x2000
	s_add_u32 s24, s24, 0x80080
	s_addc_u32 s25, s25, 0
	s_add_i32 s46, s47, s44
	global_load_lds_dwordx4 v132, s[98:99]
	ds_read_b128 v[194:197], v145 offset:51200
	ds_read_b128 v[198:201], v145 offset:52224
	s_mov_b32 m0, s46
	ds_read_b128 v[202:205], v145 offset:53248
	global_load_lds_dwordx4 v160, s[24:25]
	ds_read_b128 v[206:209], v145 offset:54272
	s_add_i32 m0, s46, 0x2000
	ds_read_b128 v[210:213], v145 offset:55296
	global_load_lds_dwordx4 v132, s[24:25]
	ds_read_b128 v[214:217], v145 offset:56320
	s_mov_b32 m0, s83
	s_add_u32 s98, s66, 0xfff80080
	s_addc_u32 s99, s67, -1
	global_load_lds_dwordx4 v128, s[98:99]
	s_mov_b32 m0, s90
	s_nop 0
	global_load_lds_dwordx4 v130, s[98:99]
	s_waitcnt vmcnt(8)
	s_waitcnt lgkmcnt(0)
	s_barrier
	s_setprio 1
	s_waitcnt lgkmcnt(0)
	v_mfma_f32_16x16x32_bf16 v[60:63], v[138:141], v[186:189], v[60:63]
	v_mfma_f32_16x16x32_bf16 v[56:59], v[150:153], v[186:189], v[56:59]
	v_mfma_f32_16x16x32_bf16 v[44:47], v[138:141], v[194:197], v[44:47]
	v_mfma_f32_16x16x32_bf16 v[40:43], v[150:153], v[194:197], v[40:43]
	v_mfma_f32_16x16x32_bf16 v[28:31], v[138:141], v[202:205], v[28:31]
	v_mfma_f32_16x16x32_bf16 v[24:27], v[150:153], v[202:205], v[24:27]
	v_mfma_f32_16x16x32_bf16 v[12:15], v[138:141], v[210:213], v[12:15]
	v_mfma_f32_16x16x32_bf16 v[8:11], v[150:153], v[210:213], v[8:11]
	v_mfma_f32_16x16x32_bf16 v[60:63], v[146:149], v[190:193], v[60:63]
	v_mfma_f32_16x16x32_bf16 v[56:59], v[154:157], v[190:193], v[56:59]
	v_mfma_f32_16x16x32_bf16 v[44:47], v[146:149], v[198:201], v[44:47]
	v_mfma_f32_16x16x32_bf16 v[40:43], v[154:157], v[198:201], v[40:43]
	v_mfma_f32_16x16x32_bf16 v[28:31], v[146:149], v[206:209], v[28:31]
	v_mfma_f32_16x16x32_bf16 v[24:27], v[154:157], v[206:209], v[24:27]
	v_mfma_f32_16x16x32_bf16 v[12:15], v[146:149], v[214:217], v[12:15]
	v_mfma_f32_16x16x32_bf16 v[8:11], v[154:157], v[214:217], v[8:11]
	s_setprio 0
	s_setprio 1
	v_mfma_f32_16x16x32_bf16 v[52:55], v[170:173], v[186:189], v[52:55]
	v_mfma_f32_16x16x32_bf16 v[48:51], v[178:181], v[186:189], v[48:51]
	v_mfma_f32_16x16x32_bf16 v[36:39], v[170:173], v[194:197], v[36:39]
	v_mfma_f32_16x16x32_bf16 v[32:35], v[178:181], v[194:197], v[32:35]
	v_mfma_f32_16x16x32_bf16 v[20:23], v[170:173], v[202:205], v[20:23]
	v_mfma_f32_16x16x32_bf16 v[16:19], v[178:181], v[202:205], v[16:19]
	v_mfma_f32_16x16x32_bf16 v[4:7], v[170:173], v[210:213], v[4:7]
	v_mfma_f32_16x16x32_bf16 v[0:3], v[178:181], v[210:213], v[0:3]
	v_mfma_f32_16x16x32_bf16 v[52:55], v[174:177], v[190:193], v[52:55]
	v_mfma_f32_16x16x32_bf16 v[48:51], v[182:185], v[190:193], v[48:51]
	v_mfma_f32_16x16x32_bf16 v[36:39], v[174:177], v[198:201], v[36:39]
	v_mfma_f32_16x16x32_bf16 v[32:35], v[182:185], v[198:201], v[32:35]
	v_mfma_f32_16x16x32_bf16 v[20:23], v[174:177], v[206:209], v[20:23]
	v_mfma_f32_16x16x32_bf16 v[16:19], v[182:185], v[206:209], v[16:19]
	v_mfma_f32_16x16x32_bf16 v[4:7], v[174:177], v[214:217], v[4:7]
	v_mfma_f32_16x16x32_bf16 v[0:3], v[182:185], v[214:217], v[0:3]
	s_setprio 0
	s_barrier
	s_add_i32 s96, s96, 2
	s_add_u32 s62, s62, 0x100
	s_addc_u32 s63, s63, 0
	s_add_u32 s94, s94, 0x100
	s_addc_u32 s95, s95, 0
	s_cmp_gt_u32 s96, 29
	s_cbranch_scc0 .LBB0_117
	s_and_b64 vcc, exec, s[10:11]
	s_mov_b64 s[96:97], 0x80000
	s_cbranch_vccz .LBB0_120
	s_barrier

; #define PG8_STAGE(bufoff, gbase, voff) do { _Pragma("unroll") for (int _i = 0; _i < 2; ++_i) \
;         __builtin_amdgcn_global_load_lds((const unsigned*)((const char*)(gbase) + (voff)[_i]), (LAS unsigned*)(lds + (bufoff) + ldsw + _i * 8192), 16, 0, 0); } while (0)
; #define PG8_LDA(dst, b, h) do { _Pragma("unroll") for (int m = 0; m < 4; ++m) _Pragma("unroll") for (int k = 0; k < 2; ++k) dst[m][k] = *(const LAS bf16x8*)(lds + PG8_SA(b, h) + aoff + m * 2048 + k * 1024); } while (0)
; #define PG8_LDB(dst, b, h) do { _Pragma("unroll") for (int n = 0; n < 2; ++n) _Pragma("unroll") for (int k = 0; k < 2; ++k) dst[n][k] = *(const LAS bf16x8*)(lds + PG8_SB(b, h) + boff + n * 2048 + k * 1024); } while (0)
; #define PG8_MMA(ai, bj, At, Bt) do { __builtin_amdgcn_s_setprio(1); _Pragma("unroll") for (int m = 0; m < 4; ++m) _Pragma("unroll") for (int n = 0; n < 2; ++n) _Pragma("unroll") for (int k = 0; k < 2; ++k) \
;         acc[ai][bj][m][n] = __builtin_amdgcn_mfma_f32_16x16x32_bf16(Bt[n][k], At[m][k], acc[ai][bj][m][n], 0, 0, 0); __builtin_amdgcn_s_setprio(0); } while (0)
; #define PG8_WAIT_V(n) asm volatile("s_waitcnt vmcnt(" #n ")" ::: "memory")
; #define PG8_WAIT_L(n) asm volatile("s_waitcnt lgkmcnt(" #n ")" ::: "memory")
; #define PG8_BAR __builtin_amdgcn_s_barrier()
; #define PG8_SCHED __builtin_amdgcn_sched_barrier(0)
; template <class Epi, class Sched, bool ALIGN_EPI = true, bool SP2 = true>
; __device__ __forceinline__ void gemm_phase(LAS unsigned char* lds, const Gemm g, const Sched& S, const Epi& E) {
;     ...
;             const char* a1 = cA + (size_t)(t + 1) * kstep;
;             const char* a2 = last ? nA : cA + (size_t)(t + 2) * kstep; const char* b2 = last ? nB : cB + (size_t)(t + 2) * kstep;
;             const char* a3 = a2 + kstep; const char* b3 = b2 + kstep;
;             if constexpr (SP2) {
;             PG8_LDB(B0, 0, 0); PG8_LDB(B1, 0, 1); PG8_SCHED; PG8_LDA(At, 0, 0); PG8_STAGE(PG8_SA(1, 1), a1 + hstep, voffA);
;             PG8_WAIT_V(8); PG8_WAIT_L(0); PG8_BAR; PG8_MMA(0, 0, At, B0); PG8_MMA(0, 1, At, B1); PG8_BAR; PG8_SCHED;
;             PG8_LDA(At, 0, 1); PG8_STAGE(PG8_SB(0, 0), b2, voffB); PG8_STAGE(PG8_SB(0, 1), b2 + hstep, voffB); PG8_STAGE(PG8_SA(0, 0), a2, voffA);
;             PG8_WAIT_V(8); PG8_WAIT_L(0); PG8_BAR; PG8_MMA(1, 0, At, B0); PG8_MMA(1, 1, At, B1); PG8_BAR; PG8_SCHED;
.LBB0_145:
	s_add_u32 s24, s72, 0xfff80080
	s_addc_u32 s25, s73, -1
	s_add_i32 s46, 0, 0x10000
	s_cmp_eq_u32 s95, 28
	s_cselect_b32 s83, s2, s25
	s_cselect_b32 s82, s3, s24
	v_add_u32_e32 v142, s46, v145
	s_cselect_b32 s25, s31, s53
	s_cselect_b32 s24, s44, s45
	s_add_i32 s47, 0, 0x14000
	ds_read_b128 v[138:141], v142
	ds_read_b128 v[148:151], v142 offset:1024
	ds_read_b128 v[152:155], v142 offset:2048
	ds_read_b128 v[156:159], v142 offset:3072
	v_add_u32_e32 v142, s47, v145
	s_add_i32 m0, s63, 0xc000
	ds_read_b128 v[170:173], v142
	global_load_lds_dwordx4 v134, s[72:73]
	ds_read_b128 v[174:177], v142 offset:1024
	ds_read_b128 v[178:181], v142 offset:2048
	ds_read_b128 v[182:185], v142 offset:3072
	ds_read_b128 v[186:189], v147
	ds_read_b128 v[190:193], v147 offset:1024
	ds_read_b128 v[194:197], v147 offset:2048
	s_add_i32 m0, s63, 0xe000
	ds_read_b128 v[198:201], v147 offset:3072
	global_load_lds_dwordx4 v136, s[72:73]
	ds_read_b128 v[202:205], v147 offset:4096
	ds_read_b128 v[206:209], v147 offset:5120
	ds_read_b128 v[210:213], v147 offset:6144
	ds_read_b128 v[214:217], v147 offset:7168
	s_waitcnt vmcnt(8)
	s_waitcnt lgkmcnt(0)
	s_barrier
	s_setprio 1
	s_waitcnt lgkmcnt(0)
	v_mfma_f32_16x16x32_bf16 v[124:127], v[138:141], v[186:189], v[124:127]
	v_mfma_f32_16x16x32_bf16 v[120:123], v[152:155], v[186:189], v[120:123]
	v_mfma_f32_16x16x32_bf16 v[108:111], v[138:141], v[194:197], v[108:111]
	v_mfma_f32_16x16x32_bf16 v[104:107], v[152:155], v[194:197], v[104:107]
	v_mfma_f32_16x16x32_bf16 v[92:95], v[138:141], v[202:205], v[92:95]
	v_mfma_f32_16x16x32_bf16 v[88:91], v[152:155], v[202:205], v[88:91]
	v_mfma_f32_16x16x32_bf16 v[76:79], v[138:141], v[210:213], v[76:79]
	v_mfma_f32_16x16x32_bf16 v[72:75], v[152:155], v[210:213], v[72:75]
	v_mfma_f32_16x16x32_bf16 v[124:127], v[148:151], v[190:193], v[124:127]
	v_mfma_f32_16x16x32_bf16 v[120:123], v[156:159], v[190:193], v[120:123]
	v_mfma_f32_16x16x32_bf16 v[108:111], v[148:151], v[198:201], v[108:111]
	v_mfma_f32_16x16x32_bf16 v[104:107], v[156:159], v[198:201], v[104:107]
	v_mfma_f32_16x16x32_bf16 v[92:95], v[148:151], v[206:209], v[92:95]
	v_mfma_f32_16x16x32_bf16 v[88:91], v[156:159], v[206:209], v[88:91]
	v_mfma_f32_16x16x32_bf16 v[76:79], v[148:151], v[214:217], v[76:79]
	v_mfma_f32_16x16x32_bf16 v[72:75], v[156:159], v[214:217], v[72:75]
	s_setprio 0
	s_setprio 1
	v_mfma_f32_16x16x32_bf16 v[116:119], v[170:173], v[186:189], v[116:119]
	v_mfma_f32_16x16x32_bf16 v[112:115], v[178:181], v[186:189], v[112:115]
	v_mfma_f32_16x16x32_bf16 v[100:103], v[170:173], v[194:197], v[100:103]
	v_mfma_f32_16x16x32_bf16 v[96:99], v[178:181], v[194:197], v[96:99]
	v_mfma_f32_16x16x32_bf16 v[84:87], v[170:173], v[202:205], v[84:87]
	v_mfma_f32_16x16x32_bf16 v[80:83], v[178:181], v[202:205], v[80:83]
	v_mfma_f32_16x16x32_bf16 v[68:71], v[170:173], v[210:213], v[68:71]
	v_mfma_f32_16x16x32_bf16 v[64:67], v[178:181], v[210:213], v[64:67]
	v_mfma_f32_16x16x32_bf16 v[116:119], v[174:177], v[190:193], v[116:119]
	v_mfma_f32_16x16x32_bf16 v[112:115], v[182:185], v[190:193], v[112:115]
	v_mfma_f32_16x16x32_bf16 v[100:103], v[174:177], v[198:201], v[100:103]
	v_mfma_f32_16x16x32_bf16 v[96:99], v[182:185], v[198:201], v[96:99]
	v_mfma_f32_16x16x32_bf16 v[84:87], v[174:177], v[206:209], v[84:87]
	v_mfma_f32_16x16x32_bf16 v[80:83], v[182:185], v[206:209], v[80:83]
	v_mfma_f32_16x16x32_bf16 v[68:71], v[174:177], v[214:217], v[68:71]
	v_mfma_f32_16x16x32_bf16 v[64:67], v[182:185], v[214:217], v[64:67]
	s_setprio 0
	s_barrier
	s_add_i32 s46, s46, s79
	s_mov_b32 m0, s46
	ds_read_b128 v[186:189], v147 offset:16384
	global_load_lds_dwordx4 v160, s[24:25]
	ds_read_b128 v[190:193], v147 offset:17408
	ds_read_b128 v[194:197], v147 offset:18432
	s_add_i32 m0, s46, 0x2000
	s_add_u32 s96, s24, 0x80000
	s_addc_u32 s97, s25, 0
	s_add_i32 s46, s47, s79
	global_load_lds_dwordx4 v132, s[24:25]
	ds_read_b128 v[198:201], v147 offset:19456
	s_mov_b32 m0, s46
	ds_read_b128 v[202:205], v147 offset:20480
	global_load_lds_dwordx4 v160, s[96:97]
	ds_read_b128 v[206:209], v147 offset:21504
	s_add_i32 m0, s46, 0x2000
	ds_read_b128 v[210:213], v147 offset:22528
	global_load_lds_dwordx4 v132, s[96:97]
	ds_read_b128 v[214:217], v147 offset:23552
	s_mov_b32 m0, s63
	s_nop 0
	global_load_lds_dwordx4 v128, s[82:83]
	s_mov_b32 m0, s67
	s_nop 0
	global_load_lds_dwordx4 v130, s[82:83]
	s_waitcnt vmcnt(8)
	s_waitcnt lgkmcnt(0)
	s_barrier
	s_setprio 1
	s_waitcnt lgkmcnt(0)
	v_mfma_f32_16x16x32_bf16 v[60:63], v[138:141], v[186:189], v[60:63]
	v_mfma_f32_16x16x32_bf16 v[56:59], v[152:155], v[186:189], v[56:59]
	v_mfma_f32_16x16x32_bf16 v[44:47], v[138:141], v[194:197], v[44:47]
	v_mfma_f32_16x16x32_bf16 v[40:43], v[152:155], v[194:197], v[40:43]
	v_mfma_f32_16x16x32_bf16 v[28:31], v[138:141], v[202:205], v[28:31]
	v_mfma_f32_16x16x32_bf16 v[24:27], v[152:155], v[202:205], v[24:27]
	v_mfma_f32_16x16x32_bf16 v[12:15], v[138:141], v[210:213], v[12:15]
	v_mfma_f32_16x16x32_bf16 v[8:11], v[152:155], v[210:213], v[8:11]
	v_mfma_f32_16x16x32_bf16 v[60:63], v[148:151], v[190:193], v[60:63]
	v_mfma_f32_16x16x32_bf16 v[56:59], v[156:159], v[190:193], v[56:59]
	v_mfma_f32_16x16x32_bf16 v[44:47], v[148:151], v[198:201], v[44:47]
	v_mfma_f32_16x16x32_bf16 v[40:43], v[156:159], v[198:201], v[40:43]
	v_mfma_f32_16x16x32_bf16 v[28:31], v[148:151], v[206:209], v[28:31]
	v_mfma_f32_16x16x32_bf16 v[24:27], v[156:159], v[206:209], v[24:27]
	v_mfma_f32_16x16x32_bf16 v[12:15], v[148:151], v[214:217], v[12:15]
	v_mfma_f32_16x16x32_bf16 v[8:11], v[156:159], v[214:217], v[8:11]
	s_setprio 0
	s_setprio 1
	v_mfma_f32_16x16x32_bf16 v[52:55], v[170:173], v[186:189], v[52:55]
	v_mfma_f32_16x16x32_bf16 v[48:51], v[178:181], v[186:189], v[48:51]
	v_mfma_f32_16x16x32_bf16 v[36:39], v[170:173], v[194:197], v[36:39]
	v_mfma_f32_16x16x32_bf16 v[32:35], v[178:181], v[194:197], v[32:35]
	v_mfma_f32_16x16x32_bf16 v[20:23], v[170:173], v[202:205], v[20:23]
	v_mfma_f32_16x16x32_bf16 v[16:19], v[178:181], v[202:205], v[16:19]
	v_mfma_f32_16x16x32_bf16 v[4:7], v[170:173], v[210:213], v[4:7]
	v_mfma_f32_16x16x32_bf16 v[0:3], v[178:181], v[210:213], v[0:3]
	v_mfma_f32_16x16x32_bf16 v[52:55], v[174:177], v[190:193], v[52:55]
	v_mfma_f32_16x16x32_bf16 v[48:51], v[182:185], v[190:193], v[48:51]
	v_mfma_f32_16x16x32_bf16 v[36:39], v[174:177], v[198:201], v[36:39]
	v_mfma_f32_16x16x32_bf16 v[32:35], v[182:185], v[198:201], v[32:35]
	v_mfma_f32_16x16x32_bf16 v[20:23], v[174:177], v[206:209], v[20:23]
	v_mfma_f32_16x16x32_bf16 v[16:19], v[182:185], v[206:209], v[16:19]
	v_mfma_f32_16x16x32_bf16 v[4:7], v[174:177], v[214:217], v[4:7]
	v_mfma_f32_16x16x32_bf16 v[0:3], v[182:185], v[214:217], v[0:3]
	s_setprio 0
	s_barrier
; #define PG8_STAGE(bufoff, gbase, voff) do { _Pragma("unroll") for (int _i = 0; _i < 2; ++_i) \
;         __builtin_amdgcn_global_load_lds((const unsigned*)((const char*)(gbase) + (voff)[_i]), (LAS unsigned*)(lds + (bufoff) + ldsw + _i * 8192), 16, 0, 0); } while (0)
; #define PG8_LDA(dst, b, h) do { _Pragma("unroll") for (int m = 0; m < 4; ++m) _Pragma("unroll") for (int k = 0; k < 2; ++k) dst[m][k] = *(const LAS bf16x8*)(lds + PG8_SA(b, h) + aoff + m * 2048 + k * 1024); } while (0)
; #define PG8_LDB(dst, b, h) do { _Pragma("unroll") for (int n = 0; n < 2; ++n) _Pragma("unroll") for (int k = 0; k < 2; ++k) dst[n][k] = *(const LAS bf16x8*)(lds + PG8_SB(b, h) + boff + n * 2048 + k * 1024); } while (0)
; #define PG8_WAIT_V(n) asm volatile("s_waitcnt vmcnt(" #n ")" ::: "memory")
; #define PG8_WAIT_L(n) asm volatile("s_waitcnt lgkmcnt(" #n ")" ::: "memory")
; template <class Epi, class Sched, bool ALIGN_EPI = true, bool SP2 = true>
; __device__ __forceinline__ void gemm_phase(LAS unsigned char* lds, const Gemm g, const Sched& S, const Epi& E) {
;     ...
;             const char* a1 = cA + (size_t)(t + 1) * kstep;
;             const char* a2 = last ? nA : cA + (size_t)(t + 2) * kstep; const char* b2 = last ? nB : cB + (size_t)(t + 2) * kstep;
;             const char* a3 = a2 + kstep; const char* b3 = b2 + kstep;
;             if constexpr (SP2) {
;             PG8_LDB(B0, 0, 0); PG8_LDB(B1, 0, 1); PG8_SCHED; PG8_LDA(At, 0, 0); PG8_STAGE(PG8_SA(1, 1), a1 + hstep, voffA);
;             PG8_WAIT_V(8); PG8_WAIT_L(0); PG8_BAR; PG8_MMA(0, 0, At, B0); PG8_MMA(0, 1, At, B1); PG8_BAR; PG8_SCHED;
;             PG8_LDA(At, 0, 1); PG8_STAGE(PG8_SB(0, 0), b2, voffB); PG8_STAGE(PG8_SB(0, 1), b2 + hstep, voffB); PG8_STAGE(PG8_SA(0, 0), a2, voffA);
;             PG8_WAIT_V(8); PG8_WAIT_L(0); PG8_BAR; PG8_MMA(1, 0, At, B0); PG8_MMA(1, 1, At, B1); PG8_BAR; PG8_SCHED;
;             PG8_LDB(B0, 1, 0); PG8_LDB(B1, 1, 1); PG8_SCHED; PG8_LDA(At, 1, 0); PG8_STAGE(PG8_SA(0, 1), a2 + hstep, voffA);
;             PG8_WAIT_V(8); PG8_WAIT_L(0); PG8_BAR; PG8_MMA(0, 0, At, B0); PG8_MMA(0, 1, At, B1); PG8_BAR; PG8_SCHED;
;             PG8_LDA(At, 1, 1); PG8_STAGE(PG8_SB(1, 0), b3, voffB); PG8_STAGE(PG8_SB(1, 1), b3 + hstep, voffB); PG8_STAGE(PG8_SA(1, 0), a3, voffA);
;             PG8_WAIT_V(8); PG8_WAIT_L(0); PG8_BAR; PG8_MMA(1, 0, At, B0); PG8_MMA(1, 1, At, B1); PG8_BAR; PG8_SCHED;
	s_add_i32 s46, 0, 0x18000
	s_add_i32 s47, 0, 0x1c000
	v_add_u32_e32 v156, s46, v145
	v_add_u32_e32 v182, s47, v145
	s_add_u32 s82, s82, 0x80000
	s_addc_u32 s83, s83, 0
	s_mov_b32 m0, s90
	ds_read_b128 v[138:141], v156
	global_load_lds_dwordx4 v128, s[82:83]
	ds_read_b128 v[148:151], v156 offset:1024
	ds_read_b128 v[152:155], v156 offset:2048
	ds_read_b128 v[156:159], v156 offset:3072
	ds_read_b128 v[170:173], v182
	ds_read_b128 v[174:177], v182 offset:1024
	ds_read_b128 v[178:181], v182 offset:2048
	ds_read_b128 v[182:185], v182 offset:3072
	ds_read_b128 v[186:189], v147 offset:32768
	s_mov_b32 m0, s91
	ds_read_b128 v[190:193], v147 offset:33792
	global_load_lds_dwordx4 v130, s[82:83]
	ds_read_b128 v[194:197], v147 offset:34816
	ds_read_b128 v[198:201], v147 offset:35840
	ds_read_b128 v[202:205], v147 offset:36864
	ds_read_b128 v[206:209], v147 offset:37888
	ds_read_b128 v[210:213], v147 offset:38912
	ds_read_b128 v[214:217], v147 offset:39936
	s_waitcnt vmcnt(8)
	s_waitcnt lgkmcnt(0)
	s_barrier
	s_setprio 1
	s_waitcnt lgkmcnt(0)
	v_mfma_f32_16x16x32_bf16 v[124:127], v[138:141], v[186:189], v[124:127]
	v_mfma_f32_16x16x32_bf16 v[120:123], v[152:155], v[186:189], v[120:123]
	v_mfma_f32_16x16x32_bf16 v[108:111], v[138:141], v[194:197], v[108:111]
	v_mfma_f32_16x16x32_bf16 v[104:107], v[152:155], v[194:197], v[104:107]
	v_mfma_f32_16x16x32_bf16 v[92:95], v[138:141], v[202:205], v[92:95]
	v_mfma_f32_16x16x32_bf16 v[88:91], v[152:155], v[202:205], v[88:91]
	v_mfma_f32_16x16x32_bf16 v[76:79], v[138:141], v[210:213], v[76:79]
	v_mfma_f32_16x16x32_bf16 v[72:75], v[152:155], v[210:213], v[72:75]
	v_mfma_f32_16x16x32_bf16 v[124:127], v[148:151], v[190:193], v[124:127]
	v_mfma_f32_16x16x32_bf16 v[120:123], v[156:159], v[190:193], v[120:123]
	v_mfma_f32_16x16x32_bf16 v[108:111], v[148:151], v[198:201], v[108:111]
	v_mfma_f32_16x16x32_bf16 v[104:107], v[156:159], v[198:201], v[104:107]
	v_mfma_f32_16x16x32_bf16 v[92:95], v[148:151], v[206:209], v[92:95]
	v_mfma_f32_16x16x32_bf16 v[88:91], v[156:159], v[206:209], v[88:91]
	v_mfma_f32_16x16x32_bf16 v[76:79], v[148:151], v[214:217], v[76:79]
	v_mfma_f32_16x16x32_bf16 v[72:75], v[156:159], v[214:217], v[72:75]
	s_setprio 0
	s_setprio 1
	v_mfma_f32_16x16x32_bf16 v[116:119], v[170:173], v[186:189], v[116:119]
	v_mfma_f32_16x16x32_bf16 v[112:115], v[178:181], v[186:189], v[112:115]
	v_mfma_f32_16x16x32_bf16 v[100:103], v[170:173], v[194:197], v[100:103]
	v_mfma_f32_16x16x32_bf16 v[96:99], v[178:181], v[194:197], v[96:99]
	v_mfma_f32_16x16x32_bf16 v[84:87], v[170:173], v[202:205], v[84:87]
	v_mfma_f32_16x16x32_bf16 v[80:83], v[178:181], v[202:205], v[80:83]
	v_mfma_f32_16x16x32_bf16 v[68:71], v[170:173], v[210:213], v[68:71]
	v_mfma_f32_16x16x32_bf16 v[64:67], v[178:181], v[210:213], v[64:67]
	v_mfma_f32_16x16x32_bf16 v[116:119], v[174:177], v[190:193], v[116:119]
	v_mfma_f32_16x16x32_bf16 v[112:115], v[182:185], v[190:193], v[112:115]
	v_mfma_f32_16x16x32_bf16 v[100:103], v[174:177], v[198:201], v[100:103]
	v_mfma_f32_16x16x32_bf16 v[96:99], v[182:185], v[198:201], v[96:99]
	v_mfma_f32_16x16x32_bf16 v[84:87], v[174:177], v[206:209], v[84:87]
	v_mfma_f32_16x16x32_bf16 v[80:83], v[182:185], v[206:209], v[80:83]
	v_mfma_f32_16x16x32_bf16 v[68:71], v[174:177], v[214:217], v[68:71]
	v_mfma_f32_16x16x32_bf16 v[64:67], v[182:185], v[214:217], v[64:67]
	s_setprio 0
	s_barrier
	s_add_i32 s46, s46, s79
	s_mov_b32 m0, s46
	s_add_u32 s98, s24, 0x80
	s_addc_u32 s99, s25, 0
	global_load_lds_dwordx4 v160, s[98:99]
	ds_read_b128 v[186:189], v147 offset:49152
	ds_read_b128 v[190:193], v147 offset:50176
	s_add_i32 m0, s46, 0x2000
	s_add_u32 s24, s24, 0x80080
	s_addc_u32 s25, s25, 0
	s_add_i32 s46, s47, s79
	global_load_lds_dwordx4 v132, s[98:99]
	ds_read_b128 v[194:197], v147 offset:51200
	ds_read_b128 v[198:201], v147 offset:52224
	s_mov_b32 m0, s46
	ds_read_b128 v[202:205], v147 offset:53248
	global_load_lds_dwordx4 v160, s[24:25]
	ds_read_b128 v[206:209], v147 offset:54272
	s_add_i32 m0, s46, 0x2000
	ds_read_b128 v[210:213], v147 offset:55296
	global_load_lds_dwordx4 v132, s[24:25]
	ds_read_b128 v[214:217], v147 offset:56320
	s_mov_b32 m0, s92
	s_add_u32 s98, s82, 0xfff80080
	s_addc_u32 s99, s83, -1
	global_load_lds_dwordx4 v128, s[98:99]
	s_mov_b32 m0, s93
	s_nop 0
	global_load_lds_dwordx4 v130, s[98:99]
	s_waitcnt vmcnt(8)
	s_waitcnt lgkmcnt(0)
	s_barrier
	s_setprio 1
	s_waitcnt lgkmcnt(0)
	v_mfma_f32_16x16x32_bf16 v[60:63], v[138:141], v[186:189], v[60:63]
	v_mfma_f32_16x16x32_bf16 v[56:59], v[152:155], v[186:189], v[56:59]
	v_mfma_f32_16x16x32_bf16 v[44:47], v[138:141], v[194:197], v[44:47]
	v_mfma_f32_16x16x32_bf16 v[40:43], v[152:155], v[194:197], v[40:43]
	v_mfma_f32_16x16x32_bf16 v[28:31], v[138:141], v[202:205], v[28:31]
	v_mfma_f32_16x16x32_bf16 v[24:27], v[152:155], v[202:205], v[24:27]
	v_mfma_f32_16x16x32_bf16 v[12:15], v[138:141], v[210:213], v[12:15]
	v_mfma_f32_16x16x32_bf16 v[8:11], v[152:155], v[210:213], v[8:11]
	v_mfma_f32_16x16x32_bf16 v[60:63], v[148:151], v[190:193], v[60:63]
	v_mfma_f32_16x16x32_bf16 v[56:59], v[156:159], v[190:193], v[56:59]
	v_mfma_f32_16x16x32_bf16 v[44:47], v[148:151], v[198:201], v[44:47]
	v_mfma_f32_16x16x32_bf16 v[40:43], v[156:159], v[198:201], v[40:43]
	v_mfma_f32_16x16x32_bf16 v[28:31], v[148:151], v[206:209], v[28:31]
	v_mfma_f32_16x16x32_bf16 v[24:27], v[156:159], v[206:209], v[24:27]
	v_mfma_f32_16x16x32_bf16 v[12:15], v[148:151], v[214:217], v[12:15]
	v_mfma_f32_16x16x32_bf16 v[8:11], v[156:159], v[214:217], v[8:11]
	s_setprio 0
	s_setprio 1
	v_mfma_f32_16x16x32_bf16 v[52:55], v[170:173], v[186:189], v[52:55]
	v_mfma_f32_16x16x32_bf16 v[48:51], v[178:181], v[186:189], v[48:51]
	v_mfma_f32_16x16x32_bf16 v[36:39], v[170:173], v[194:197], v[36:39]
	v_mfma_f32_16x16x32_bf16 v[32:35], v[178:181], v[194:197], v[32:35]
	v_mfma_f32_16x16x32_bf16 v[20:23], v[170:173], v[202:205], v[20:23]
	v_mfma_f32_16x16x32_bf16 v[16:19], v[178:181], v[202:205], v[16:19]
	v_mfma_f32_16x16x32_bf16 v[4:7], v[170:173], v[210:213], v[4:7]
	v_mfma_f32_16x16x32_bf16 v[0:3], v[178:181], v[210:213], v[0:3]
	v_mfma_f32_16x16x32_bf16 v[52:55], v[174:177], v[190:193], v[52:55]
	v_mfma_f32_16x16x32_bf16 v[48:51], v[182:185], v[190:193], v[48:51]
	v_mfma_f32_16x16x32_bf16 v[36:39], v[174:177], v[198:201], v[36:39]
	v_mfma_f32_16x16x32_bf16 v[32:35], v[182:185], v[198:201], v[32:35]
	v_mfma_f32_16x16x32_bf16 v[20:23], v[174:177], v[206:209], v[20:23]
	v_mfma_f32_16x16x32_bf16 v[16:19], v[182:185], v[206:209], v[16:19]
	v_mfma_f32_16x16x32_bf16 v[4:7], v[174:177], v[214:217], v[4:7]
	v_mfma_f32_16x16x32_bf16 v[0:3], v[182:185], v[214:217], v[0:3]
	s_setprio 0
	s_barrier
	s_add_i32 s95, s95, 2
	s_add_u32 s72, s72, 0x100
	s_addc_u32 s73, s73, 0
	s_add_u32 s45, s45, 0x100
	s_addc_u32 s53, s53, 0
	s_cmp_gt_u32 s95, 29
	s_cbranch_scc0 .LBB0_145
	s_and_b64 vcc, exec, s[18:19]
	s_cbranch_vccz .LBB0_148
	s_barrier

; #define PG8_STAGE(bufoff, gbase, voff) do { _Pragma("unroll") for (int _i = 0; _i < 2; ++_i) \
;         __builtin_amdgcn_global_load_lds((const unsigned*)((const char*)(gbase) + (voff)[_i]), (LAS unsigned*)(lds + (bufoff) + ldsw + _i * 8192), 16, 0, 0); } while (0)
; #define PG8_LDA(dst, b, h) do { _Pragma("unroll") for (int m = 0; m < 4; ++m) _Pragma("unroll") for (int k = 0; k < 2; ++k) dst[m][k] = *(const LAS bf16x8*)(lds + PG8_SA(b, h) + aoff + m * 2048 + k * 1024); } while (0)
; #define PG8_LDB(dst, b, h) do { _Pragma("unroll") for (int n = 0; n < 2; ++n) _Pragma("unroll") for (int k = 0; k < 2; ++k) dst[n][k] = *(const LAS bf16x8*)(lds + PG8_SB(b, h) + boff + n * 2048 + k * 1024); } while (0)
; #define PG8_MMA(ai, bj, At, Bt) do { __builtin_amdgcn_s_setprio(1); _Pragma("unroll") for (int m = 0; m < 4; ++m) _Pragma("unroll") for (int n = 0; n < 2; ++n) _Pragma("unroll") for (int k = 0; k < 2; ++k) \
;         acc[ai][bj][m][n] = __builtin_amdgcn_mfma_f32_16x16x32_bf16(Bt[n][k], At[m][k], acc[ai][bj][m][n], 0, 0, 0); __builtin_amdgcn_s_setprio(0); } while (0)
; #define PG8_WAIT_V(n) asm volatile("s_waitcnt vmcnt(" #n ")" ::: "memory")
; #define PG8_WAIT_L(n) asm volatile("s_waitcnt lgkmcnt(" #n ")" ::: "memory")
; #define PG8_BAR __builtin_amdgcn_s_barrier()
; #define PG8_SCHED __builtin_amdgcn_sched_barrier(0)
; template <class Epi, class Sched, bool ALIGN_EPI = true, bool SP2 = true>
; __device__ __forceinline__ void gemm_phase(LAS unsigned char* lds, const Gemm g, const Sched& S, const Epi& E) {
;     ...
;             const char* a1 = cA + (size_t)(t + 1) * kstep;
;             const char* a2 = last ? nA : cA + (size_t)(t + 2) * kstep; const char* b2 = last ? nB : cB + (size_t)(t + 2) * kstep;
;             const char* a3 = a2 + kstep; const char* b3 = b2 + kstep;
;             if constexpr (SP2) {
;             PG8_LDB(B0, 0, 0); PG8_LDB(B1, 0, 1); PG8_SCHED; PG8_LDA(At, 0, 0); PG8_STAGE(PG8_SA(1, 1), a1 + hstep, voffA);
;             PG8_WAIT_V(8); PG8_WAIT_L(0); PG8_BAR; PG8_MMA(0, 0, At, B0); PG8_MMA(0, 1, At, B1); PG8_BAR; PG8_SCHED;
;             PG8_LDA(At, 0, 1); PG8_STAGE(PG8_SB(0, 0), b2, voffB); PG8_STAGE(PG8_SB(0, 1), b2 + hstep, voffB); PG8_STAGE(PG8_SA(0, 0), a2, voffA);
;             PG8_WAIT_V(8); PG8_WAIT_L(0); PG8_BAR; PG8_MMA(1, 0, At, B0); PG8_MMA(1, 1, At, B1); PG8_BAR; PG8_SCHED;
.LBB0_187:
	s_add_u32 s24, s66, 0xfffc0080
	s_addc_u32 s25, s67, -1
	s_add_i32 s46, 0, 0x10000
	s_cmp_eq_u32 s53, 12
	s_cselect_b32 s73, s2, s25
	s_cselect_b32 s72, s3, s24
	s_cselect_b32 s25, s31, s45
	s_cselect_b32 s24, s43, s44
	s_add_i32 s47, 0, 0x14000
	v_add_u32_e32 v154, s46, v147
	v_add_u32_e32 v158, s47, v147
	s_add_i32 m0, s63, 0xc000
	ds_read_b128 v[138:141], v154
	global_load_lds_dwordx4 v134, s[66:67]
	ds_read_b128 v[142:145], v154 offset:1024
	ds_read_b128 v[150:153], v154 offset:2048
	ds_read_b128 v[154:157], v154 offset:3072
	ds_read_b128 v[170:173], v158
	ds_read_b128 v[174:177], v158 offset:1024
	ds_read_b128 v[178:181], v158 offset:2048
	ds_read_b128 v[182:185], v158 offset:3072
	ds_read_b128 v[186:189], v149
	s_add_i32 m0, s63, 0xe000
	ds_read_b128 v[190:193], v149 offset:1024
	global_load_lds_dwordx4 v136, s[66:67]
	ds_read_b128 v[194:197], v149 offset:2048
	ds_read_b128 v[198:201], v149 offset:3072
	ds_read_b128 v[202:205], v149 offset:4096
	ds_read_b128 v[206:209], v149 offset:5120
	ds_read_b128 v[210:213], v149 offset:6144
	ds_read_b128 v[214:217], v149 offset:7168
	s_waitcnt vmcnt(8)
	s_waitcnt lgkmcnt(0)
	s_barrier
	s_setprio 1
	s_waitcnt lgkmcnt(0)
	v_mfma_f32_16x16x32_bf16 v[124:127], v[138:141], v[186:189], v[124:127]
	v_mfma_f32_16x16x32_bf16 v[120:123], v[150:153], v[186:189], v[120:123]
	v_mfma_f32_16x16x32_bf16 v[108:111], v[138:141], v[194:197], v[108:111]
	v_mfma_f32_16x16x32_bf16 v[104:107], v[150:153], v[194:197], v[104:107]
	v_mfma_f32_16x16x32_bf16 v[92:95], v[138:141], v[202:205], v[92:95]
	v_mfma_f32_16x16x32_bf16 v[88:91], v[150:153], v[202:205], v[88:91]
	v_mfma_f32_16x16x32_bf16 v[76:79], v[138:141], v[210:213], v[76:79]
	v_mfma_f32_16x16x32_bf16 v[72:75], v[150:153], v[210:213], v[72:75]
	v_mfma_f32_16x16x32_bf16 v[124:127], v[142:145], v[190:193], v[124:127]
	v_mfma_f32_16x16x32_bf16 v[120:123], v[154:157], v[190:193], v[120:123]
	v_mfma_f32_16x16x32_bf16 v[108:111], v[142:145], v[198:201], v[108:111]
	v_mfma_f32_16x16x32_bf16 v[104:107], v[154:157], v[198:201], v[104:107]
	v_mfma_f32_16x16x32_bf16 v[92:95], v[142:145], v[206:209], v[92:95]
	v_mfma_f32_16x16x32_bf16 v[88:91], v[154:157], v[206:209], v[88:91]
	v_mfma_f32_16x16x32_bf16 v[76:79], v[142:145], v[214:217], v[76:79]
	v_mfma_f32_16x16x32_bf16 v[72:75], v[154:157], v[214:217], v[72:75]
	s_setprio 0
	s_setprio 1
	v_mfma_f32_16x16x32_bf16 v[116:119], v[170:173], v[186:189], v[116:119]
	v_mfma_f32_16x16x32_bf16 v[112:115], v[178:181], v[186:189], v[112:115]
	v_mfma_f32_16x16x32_bf16 v[100:103], v[170:173], v[194:197], v[100:103]
	v_mfma_f32_16x16x32_bf16 v[96:99], v[178:181], v[194:197], v[96:99]
	v_mfma_f32_16x16x32_bf16 v[84:87], v[170:173], v[202:205], v[84:87]
	v_mfma_f32_16x16x32_bf16 v[80:83], v[178:181], v[202:205], v[80:83]
	v_mfma_f32_16x16x32_bf16 v[68:71], v[170:173], v[210:213], v[68:71]
	v_mfma_f32_16x16x32_bf16 v[64:67], v[178:181], v[210:213], v[64:67]
	v_mfma_f32_16x16x32_bf16 v[116:119], v[174:177], v[190:193], v[116:119]
	v_mfma_f32_16x16x32_bf16 v[112:115], v[182:185], v[190:193], v[112:115]
	v_mfma_f32_16x16x32_bf16 v[100:103], v[174:177], v[198:201], v[100:103]
	v_mfma_f32_16x16x32_bf16 v[96:99], v[182:185], v[198:201], v[96:99]
	v_mfma_f32_16x16x32_bf16 v[84:87], v[174:177], v[206:209], v[84:87]
	v_mfma_f32_16x16x32_bf16 v[80:83], v[182:185], v[206:209], v[80:83]
	v_mfma_f32_16x16x32_bf16 v[68:71], v[174:177], v[214:217], v[68:71]
	v_mfma_f32_16x16x32_bf16 v[64:67], v[182:185], v[214:217], v[64:67]
	s_setprio 0
	s_barrier
	s_add_i32 s46, s46, s90
	s_mov_b32 m0, s46
	ds_read_b128 v[186:189], v149 offset:16384
	global_load_lds_dwordx4 v160, s[24:25]
	ds_read_b128 v[190:193], v149 offset:17408
	ds_read_b128 v[194:197], v149 offset:18432
	s_add_i32 m0, s46, 0x2000
	s_add_u32 vcc_lo, s24, 0x40000
	s_addc_u32 vcc_hi, s25, 0
	s_add_i32 s46, s47, s90
	global_load_lds_dwordx4 v132, s[24:25]
	ds_read_b128 v[198:201], v149 offset:19456
	v_lshl_add_u64 v[218:219], vcc, 0, v[160:161]
	s_mov_b32 m0, s46
	ds_read_b128 v[202:205], v149 offset:20480
	global_load_lds_dwordx4 v[218:219], off
	ds_read_b128 v[206:209], v149 offset:21504
	v_lshl_add_u64 v[218:219], vcc, 0, v[132:133]
	s_add_i32 m0, s46, 0x2000
	ds_read_b128 v[210:213], v149 offset:22528
	global_load_lds_dwordx4 v[218:219], off
	ds_read_b128 v[214:217], v149 offset:23552
	s_mov_b32 m0, s63
	s_nop 0
	global_load_lds_dwordx4 v128, s[72:73]
	s_mov_b32 m0, s91
	s_nop 0
	global_load_lds_dwordx4 v130, s[72:73]
	s_waitcnt vmcnt(8)
	s_waitcnt lgkmcnt(0)
	s_barrier
; #define PG8_STAGE(bufoff, gbase, voff) do { _Pragma("unroll") for (int _i = 0; _i < 2; ++_i) \
;         __builtin_amdgcn_global_load_lds((const unsigned*)((const char*)(gbase) + (voff)[_i]), (LAS unsigned*)(lds + (bufoff) + ldsw + _i * 8192), 16, 0, 0); } while (0)
; #define PG8_LDA(dst, b, h) do { _Pragma("unroll") for (int m = 0; m < 4; ++m) _Pragma("unroll") for (int k = 0; k < 2; ++k) dst[m][k] = *(const LAS bf16x8*)(lds + PG8_SA(b, h) + aoff + m * 2048 + k * 1024); } while (0)
; #define PG8_LDB(dst, b, h) do { _Pragma("unroll") for (int n = 0; n < 2; ++n) _Pragma("unroll") for (int k = 0; k < 2; ++k) dst[n][k] = *(const LAS bf16x8*)(lds + PG8_SB(b, h) + boff + n * 2048 + k * 1024); } while (0)
; #define PG8_MMA(ai, bj, At, Bt) do { __builtin_amdgcn_s_setprio(1); _Pragma("unroll") for (int m = 0; m < 4; ++m) _Pragma("unroll") for (int n = 0; n < 2; ++n) _Pragma("unroll") for (int k = 0; k < 2; ++k) \
;         acc[ai][bj][m][n] = __builtin_amdgcn_mfma_f32_16x16x32_bf16(Bt[n][k], At[m][k], acc[ai][bj][m][n], 0, 0, 0); __builtin_amdgcn_s_setprio(0); } while (0)
; #define PG8_WAIT_V(n) asm volatile("s_waitcnt vmcnt(" #n ")" ::: "memory")
; #define PG8_WAIT_L(n) asm volatile("s_waitcnt lgkmcnt(" #n ")" ::: "memory")
; #define PG8_BAR __builtin_amdgcn_s_barrier()
; #define PG8_SCHED __builtin_amdgcn_sched_barrier(0)
; template <class Epi, class Sched, bool ALIGN_EPI = true, bool SP2 = true>
; __device__ __forceinline__ void gemm_phase(LAS unsigned char* lds, const Gemm g, const Sched& S, const Epi& E) {
;     ...
;             PG8_WAIT_V(8); PG8_WAIT_L(0); PG8_BAR; PG8_MMA(1, 0, At, B0); PG8_MMA(1, 1, At, B1); PG8_BAR; PG8_SCHED;
;             PG8_LDB(B0, 1, 0); PG8_LDB(B1, 1, 1); PG8_SCHED; PG8_LDA(At, 1, 0); PG8_STAGE(PG8_SA(0, 1), a2 + hstep, voffA);
;             PG8_WAIT_V(8); PG8_WAIT_L(0); PG8_BAR; PG8_MMA(0, 0, At, B0); PG8_MMA(0, 1, At, B1); PG8_BAR; PG8_SCHED;
	s_setprio 1
	s_waitcnt lgkmcnt(0)
	v_mfma_f32_16x16x32_bf16 v[60:63], v[138:141], v[186:189], v[60:63]
	v_mfma_f32_16x16x32_bf16 v[56:59], v[150:153], v[186:189], v[56:59]
	v_mfma_f32_16x16x32_bf16 v[44:47], v[138:141], v[194:197], v[44:47]
	v_mfma_f32_16x16x32_bf16 v[40:43], v[150:153], v[194:197], v[40:43]
	v_mfma_f32_16x16x32_bf16 v[28:31], v[138:141], v[202:205], v[28:31]
	v_mfma_f32_16x16x32_bf16 v[24:27], v[150:153], v[202:205], v[24:27]
	v_mfma_f32_16x16x32_bf16 v[12:15], v[138:141], v[210:213], v[12:15]
	v_mfma_f32_16x16x32_bf16 v[8:11], v[150:153], v[210:213], v[8:11]
	v_mfma_f32_16x16x32_bf16 v[60:63], v[142:145], v[190:193], v[60:63]
	v_mfma_f32_16x16x32_bf16 v[56:59], v[154:157], v[190:193], v[56:59]
	v_mfma_f32_16x16x32_bf16 v[44:47], v[142:145], v[198:201], v[44:47]
	v_mfma_f32_16x16x32_bf16 v[40:43], v[154:157], v[198:201], v[40:43]
	v_mfma_f32_16x16x32_bf16 v[28:31], v[142:145], v[206:209], v[28:31]
	v_mfma_f32_16x16x32_bf16 v[24:27], v[154:157], v[206:209], v[24:27]
	v_mfma_f32_16x16x32_bf16 v[12:15], v[142:145], v[214:217], v[12:15]
	v_mfma_f32_16x16x32_bf16 v[8:11], v[154:157], v[214:217], v[8:11]
	s_setprio 0
	s_setprio 1
	v_mfma_f32_16x16x32_bf16 v[52:55], v[170:173], v[186:189], v[52:55]
	v_mfma_f32_16x16x32_bf16 v[48:51], v[178:181], v[186:189], v[48:51]
	v_mfma_f32_16x16x32_bf16 v[36:39], v[170:173], v[194:197], v[36:39]
	v_mfma_f32_16x16x32_bf16 v[32:35], v[178:181], v[194:197], v[32:35]
	v_mfma_f32_16x16x32_bf16 v[20:23], v[170:173], v[202:205], v[20:23]
	v_mfma_f32_16x16x32_bf16 v[16:19], v[178:181], v[202:205], v[16:19]
	v_mfma_f32_16x16x32_bf16 v[4:7], v[170:173], v[210:213], v[4:7]
	v_mfma_f32_16x16x32_bf16 v[0:3], v[178:181], v[210:213], v[0:3]
	v_mfma_f32_16x16x32_bf16 v[52:55], v[174:177], v[190:193], v[52:55]
	v_mfma_f32_16x16x32_bf16 v[48:51], v[182:185], v[190:193], v[48:51]
	v_mfma_f32_16x16x32_bf16 v[36:39], v[174:177], v[198:201], v[36:39]
	v_mfma_f32_16x16x32_bf16 v[32:35], v[182:185], v[198:201], v[32:35]
	v_mfma_f32_16x16x32_bf16 v[20:23], v[174:177], v[206:209], v[20:23]
	v_mfma_f32_16x16x32_bf16 v[16:19], v[182:185], v[206:209], v[16:19]
	v_mfma_f32_16x16x32_bf16 v[4:7], v[174:177], v[214:217], v[4:7]
	v_mfma_f32_16x16x32_bf16 v[0:3], v[182:185], v[214:217], v[0:3]
	s_setprio 0
	s_barrier
	s_add_i32 s46, 0, 0x18000
	s_add_i32 s47, 0, 0x1c000
	v_add_u32_e32 v154, s46, v147
	v_add_u32_e32 v182, s47, v147
	s_add_u32 s72, s72, 0x40000
	s_addc_u32 s73, s73, 0
	s_mov_b32 m0, s92
	ds_read_b128 v[138:141], v154
	global_load_lds_dwordx4 v128, s[72:73]
	ds_read_b128 v[142:145], v154 offset:1024
	ds_read_b128 v[150:153], v154 offset:2048
	ds_read_b128 v[154:157], v154 offset:3072
	ds_read_b128 v[170:173], v182
	ds_read_b128 v[174:177], v182 offset:1024
	ds_read_b128 v[178:181], v182 offset:2048
	ds_read_b128 v[182:185], v182 offset:3072
	ds_read_b128 v[186:189], v149 offset:32768
	s_mov_b32 m0, s93
	ds_read_b128 v[190:193], v149 offset:33792
	global_load_lds_dwordx4 v130, s[72:73]
	ds_read_b128 v[194:197], v149 offset:34816
	ds_read_b128 v[198:201], v149 offset:35840
	ds_read_b128 v[202:205], v149 offset:36864
	ds_read_b128 v[206:209], v149 offset:37888
	ds_read_b128 v[210:213], v149 offset:38912
	ds_read_b128 v[214:217], v149 offset:39936
	s_waitcnt vmcnt(8)
	s_waitcnt lgkmcnt(0)
	s_barrier
	s_setprio 1
	s_waitcnt lgkmcnt(0)
	v_mfma_f32_16x16x32_bf16 v[124:127], v[138:141], v[186:189], v[124:127]
	v_mfma_f32_16x16x32_bf16 v[120:123], v[150:153], v[186:189], v[120:123]
	v_mfma_f32_16x16x32_bf16 v[108:111], v[138:141], v[194:197], v[108:111]
	v_mfma_f32_16x16x32_bf16 v[104:107], v[150:153], v[194:197], v[104:107]
	v_mfma_f32_16x16x32_bf16 v[92:95], v[138:141], v[202:205], v[92:95]
	v_mfma_f32_16x16x32_bf16 v[88:91], v[150:153], v[202:205], v[88:91]
	v_mfma_f32_16x16x32_bf16 v[76:79], v[138:141], v[210:213], v[76:79]
	v_mfma_f32_16x16x32_bf16 v[72:75], v[150:153], v[210:213], v[72:75]
	v_mfma_f32_16x16x32_bf16 v[124:127], v[142:145], v[190:193], v[124:127]
	v_mfma_f32_16x16x32_bf16 v[120:123], v[154:157], v[190:193], v[120:123]
	v_mfma_f32_16x16x32_bf16 v[108:111], v[142:145], v[198:201], v[108:111]
	v_mfma_f32_16x16x32_bf16 v[104:107], v[154:157], v[198:201], v[104:107]
	v_mfma_f32_16x16x32_bf16 v[92:95], v[142:145], v[206:209], v[92:95]
	v_mfma_f32_16x16x32_bf16 v[88:91], v[154:157], v[206:209], v[88:91]
	v_mfma_f32_16x16x32_bf16 v[76:79], v[142:145], v[214:217], v[76:79]
	v_mfma_f32_16x16x32_bf16 v[72:75], v[154:157], v[214:217], v[72:75]
	s_setprio 0
	s_setprio 1
	v_mfma_f32_16x16x32_bf16 v[116:119], v[170:173], v[186:189], v[116:119]
	v_mfma_f32_16x16x32_bf16 v[112:115], v[178:181], v[186:189], v[112:115]
	v_mfma_f32_16x16x32_bf16 v[100:103], v[170:173], v[194:197], v[100:103]
	v_mfma_f32_16x16x32_bf16 v[96:99], v[178:181], v[194:197], v[96:99]
	v_mfma_f32_16x16x32_bf16 v[84:87], v[170:173], v[202:205], v[84:87]
	v_mfma_f32_16x16x32_bf16 v[80:83], v[178:181], v[202:205], v[80:83]
	v_mfma_f32_16x16x32_bf16 v[68:71], v[170:173], v[210:213], v[68:71]
	v_mfma_f32_16x16x32_bf16 v[64:67], v[178:181], v[210:213], v[64:67]
	v_mfma_f32_16x16x32_bf16 v[116:119], v[174:177], v[190:193], v[116:119]
	v_mfma_f32_16x16x32_bf16 v[112:115], v[182:185], v[190:193], v[112:115]
	v_mfma_f32_16x16x32_bf16 v[100:103], v[174:177], v[198:201], v[100:103]
	v_mfma_f32_16x16x32_bf16 v[96:99], v[182:185], v[198:201], v[96:99]
	v_mfma_f32_16x16x32_bf16 v[84:87], v[174:177], v[206:209], v[84:87]
	v_mfma_f32_16x16x32_bf16 v[80:83], v[182:185], v[206:209], v[80:83]
	v_mfma_f32_16x16x32_bf16 v[68:71], v[174:177], v[214:217], v[68:71]
	v_mfma_f32_16x16x32_bf16 v[64:67], v[182:185], v[214:217], v[64:67]
	s_setprio 0
	s_barrier
; #define PG8_STAGE(bufoff, gbase, voff) do { _Pragma("unroll") for (int _i = 0; _i < 2; ++_i) \
;         __builtin_amdgcn_global_load_lds((const unsigned*)((const char*)(gbase) + (voff)[_i]), (LAS unsigned*)(lds + (bufoff) + ldsw + _i * 8192), 16, 0, 0); } while (0)
; #define PG8_LDA(dst, b, h) do { _Pragma("unroll") for (int m = 0; m < 4; ++m) _Pragma("unroll") for (int k = 0; k < 2; ++k) dst[m][k] = *(const LAS bf16x8*)(lds + PG8_SA(b, h) + aoff + m * 2048 + k * 1024); } while (0)
; #define PG8_MMA(ai, bj, At, Bt) do { __builtin_amdgcn_s_setprio(1); _Pragma("unroll") for (int m = 0; m < 4; ++m) _Pragma("unroll") for (int n = 0; n < 2; ++n) _Pragma("unroll") for (int k = 0; k < 2; ++k) \
;         acc[ai][bj][m][n] = __builtin_amdgcn_mfma_f32_16x16x32_bf16(Bt[n][k], At[m][k], acc[ai][bj][m][n], 0, 0, 0); __builtin_amdgcn_s_setprio(0); } while (0)
; #define PG8_WAIT_V(n) asm volatile("s_waitcnt vmcnt(" #n ")" ::: "memory")
; #define PG8_WAIT_L(n) asm volatile("s_waitcnt lgkmcnt(" #n ")" ::: "memory")
; #define PG8_BAR __builtin_amdgcn_s_barrier()
; #define PG8_SCHED __builtin_amdgcn_sched_barrier(0)
; template <class Epi, class Sched, bool ALIGN_EPI = true, bool SP2 = true>
; __device__ __forceinline__ void gemm_phase(LAS unsigned char* lds, const Gemm g, const Sched& S, const Epi& E) {
;     ...
;         for (int t = 0; t < nt; t += 2) {
;     ...
;             PG8_LDA(At, 1, 1); PG8_STAGE(PG8_SB(1, 0), b3, voffB); PG8_STAGE(PG8_SB(1, 1), b3 + hstep, voffB); PG8_STAGE(PG8_SA(1, 0), a3, voffA);
;             PG8_WAIT_V(8); PG8_WAIT_L(0); PG8_BAR; PG8_MMA(1, 0, At, B0); PG8_MMA(1, 1, At, B1); PG8_BAR; PG8_SCHED;
	s_add_i32 s46, s46, s90
	s_mov_b32 m0, s46
	s_add_u32 s98, s24, 0x80
	s_addc_u32 s99, s25, 0
	global_load_lds_dwordx4 v160, s[98:99]
	ds_read_b128 v[186:189], v149 offset:49152
	ds_read_b128 v[190:193], v149 offset:50176
	s_add_i32 m0, s46, 0x2000
	s_add_u32 s24, s24, 0x40080
	s_addc_u32 s25, s25, 0
	s_add_i32 s46, s47, s90
	global_load_lds_dwordx4 v132, s[98:99]
	ds_read_b128 v[194:197], v149 offset:51200
	ds_read_b128 v[198:201], v149 offset:52224
	s_mov_b32 m0, s46
	ds_read_b128 v[202:205], v149 offset:53248
	global_load_lds_dwordx4 v160, s[24:25]
	ds_read_b128 v[206:209], v149 offset:54272
	s_add_i32 m0, s46, 0x2000
	ds_read_b128 v[210:213], v149 offset:55296
	global_load_lds_dwordx4 v132, s[24:25]
	ds_read_b128 v[214:217], v149 offset:56320
	s_mov_b32 m0, s94
	s_add_u32 s98, s72, 0xfffc0080
	s_addc_u32 s99, s73, -1
	global_load_lds_dwordx4 v128, s[98:99]
	s_mov_b32 m0, s95
	s_nop 0
	global_load_lds_dwordx4 v130, s[98:99]
	s_waitcnt vmcnt(8)
	s_waitcnt lgkmcnt(0)
	s_barrier
	s_setprio 1
	s_waitcnt lgkmcnt(0)
	v_mfma_f32_16x16x32_bf16 v[60:63], v[138:141], v[186:189], v[60:63]
	v_mfma_f32_16x16x32_bf16 v[56:59], v[150:153], v[186:189], v[56:59]
	v_mfma_f32_16x16x32_bf16 v[44:47], v[138:141], v[194:197], v[44:47]
	v_mfma_f32_16x16x32_bf16 v[40:43], v[150:153], v[194:197], v[40:43]
	v_mfma_f32_16x16x32_bf16 v[28:31], v[138:141], v[202:205], v[28:31]
	v_mfma_f32_16x16x32_bf16 v[24:27], v[150:153], v[202:205], v[24:27]
	v_mfma_f32_16x16x32_bf16 v[12:15], v[138:141], v[210:213], v[12:15]
	v_mfma_f32_16x16x32_bf16 v[8:11], v[150:153], v[210:213], v[8:11]
	v_mfma_f32_16x16x32_bf16 v[60:63], v[142:145], v[190:193], v[60:63]
	v_mfma_f32_16x16x32_bf16 v[56:59], v[154:157], v[190:193], v[56:59]
	v_mfma_f32_16x16x32_bf16 v[44:47], v[142:145], v[198:201], v[44:47]
	v_mfma_f32_16x16x32_bf16 v[40:43], v[154:157], v[198:201], v[40:43]
	v_mfma_f32_16x16x32_bf16 v[28:31], v[142:145], v[206:209], v[28:31]
	v_mfma_f32_16x16x32_bf16 v[24:27], v[154:157], v[206:209], v[24:27]
	v_mfma_f32_16x16x32_bf16 v[12:15], v[142:145], v[214:217], v[12:15]
	v_mfma_f32_16x16x32_bf16 v[8:11], v[154:157], v[214:217], v[8:11]
	s_setprio 0
	s_setprio 1
	v_mfma_f32_16x16x32_bf16 v[52:55], v[170:173], v[186:189], v[52:55]
	v_mfma_f32_16x16x32_bf16 v[48:51], v[178:181], v[186:189], v[48:51]
	v_mfma_f32_16x16x32_bf16 v[36:39], v[170:173], v[194:197], v[36:39]
	v_mfma_f32_16x16x32_bf16 v[32:35], v[178:181], v[194:197], v[32:35]
	v_mfma_f32_16x16x32_bf16 v[20:23], v[170:173], v[202:205], v[20:23]
	v_mfma_f32_16x16x32_bf16 v[16:19], v[178:181], v[202:205], v[16:19]
	v_mfma_f32_16x16x32_bf16 v[4:7], v[170:173], v[210:213], v[4:7]
	v_mfma_f32_16x16x32_bf16 v[0:3], v[178:181], v[210:213], v[0:3]
	v_mfma_f32_16x16x32_bf16 v[52:55], v[174:177], v[190:193], v[52:55]
	v_mfma_f32_16x16x32_bf16 v[48:51], v[182:185], v[190:193], v[48:51]
	v_mfma_f32_16x16x32_bf16 v[36:39], v[174:177], v[198:201], v[36:39]
	v_mfma_f32_16x16x32_bf16 v[32:35], v[182:185], v[198:201], v[32:35]
	v_mfma_f32_16x16x32_bf16 v[20:23], v[174:177], v[206:209], v[20:23]
	v_mfma_f32_16x16x32_bf16 v[16:19], v[182:185], v[206:209], v[16:19]
	v_mfma_f32_16x16x32_bf16 v[4:7], v[174:177], v[214:217], v[4:7]
	v_mfma_f32_16x16x32_bf16 v[0:3], v[182:185], v[214:217], v[0:3]
	s_setprio 0
	s_barrier
	s_add_i32 s53, s53, 2
	s_add_u32 s66, s66, 0x100
	s_addc_u32 s67, s67, 0
	s_add_u32 s44, s44, 0x100
	s_addc_u32 s45, s45, 0
	s_cmp_gt_u32 s53, 13
	s_cbranch_scc0 .LBB0_187
	s_and_b64 vcc, exec, s[18:19]
	s_cbranch_vccz .LBB0_190
	s_barrier

; #define PG8_STAGE(bufoff, gbase, voff) do { _Pragma("unroll") for (int _i = 0; _i < 2; ++_i) \
;         __builtin_amdgcn_global_load_lds((const unsigned*)((const char*)(gbase) + (voff)[_i]), (LAS unsigned*)(lds + (bufoff) + ldsw + _i * 8192), 16, 0, 0); } while (0)
; #define PG8_LDA(dst, b, h) do { _Pragma("unroll") for (int m = 0; m < 4; ++m) _Pragma("unroll") for (int k = 0; k < 2; ++k) dst[m][k] = *(const LAS bf16x8*)(lds + PG8_SA(b, h) + aoff + m * 2048 + k * 1024); } while (0)
; #define PG8_LDB(dst, b, h) do { _Pragma("unroll") for (int n = 0; n < 2; ++n) _Pragma("unroll") for (int k = 0; k < 2; ++k) dst[n][k] = *(const LAS bf16x8*)(lds + PG8_SB(b, h) + boff + n * 2048 + k * 1024); } while (0)
; #define PG8_MMA(ai, bj, At, Bt) do { __builtin_amdgcn_s_setprio(1); _Pragma("unroll") for (int m = 0; m < 4; ++m) _Pragma("unroll") for (int n = 0; n < 2; ++n) _Pragma("unroll") for (int k = 0; k < 2; ++k) \
;         acc[ai][bj][m][n] = __builtin_amdgcn_mfma_f32_16x16x32_bf16(Bt[n][k], At[m][k], acc[ai][bj][m][n], 0, 0, 0); __builtin_amdgcn_s_setprio(0); } while (0)
; #define PG8_WAIT_V(n) asm volatile("s_waitcnt vmcnt(" #n ")" ::: "memory")
; #define PG8_WAIT_L(n) asm volatile("s_waitcnt lgkmcnt(" #n ")" ::: "memory")
; #define PG8_BAR __builtin_amdgcn_s_barrier()
; #define PG8_SCHED __builtin_amdgcn_sched_barrier(0)
; template <class Epi, class Sched, bool ALIGN_EPI = true, bool SP2 = true>
; __device__ __forceinline__ void gemm_phase(LAS unsigned char* lds, const Gemm g, const Sched& S, const Epi& E) {
;     ...
;             const char* a1 = cA + (size_t)(t + 1) * kstep;
;             const char* a2 = last ? nA : cA + (size_t)(t + 2) * kstep; const char* b2 = last ? nB : cB + (size_t)(t + 2) * kstep;
;             const char* a3 = a2 + kstep; const char* b3 = b2 + kstep;
;             if constexpr (SP2) {
;             PG8_LDB(B0, 0, 0); PG8_LDB(B1, 0, 1); PG8_SCHED; PG8_LDA(At, 0, 0); PG8_STAGE(PG8_SA(1, 1), a1 + hstep, voffA);
;             PG8_WAIT_V(8); PG8_WAIT_L(0); PG8_BAR; PG8_MMA(0, 0, At, B0); PG8_MMA(0, 1, At, B1); PG8_BAR; PG8_SCHED;
;             PG8_LDA(At, 0, 1); PG8_STAGE(PG8_SB(0, 0), b2, voffB); PG8_STAGE(PG8_SB(0, 1), b2 + hstep, voffB); PG8_STAGE(PG8_SA(0, 0), a2, voffA);
;             PG8_WAIT_V(8); PG8_WAIT_L(0); PG8_BAR; PG8_MMA(1, 0, At, B0); PG8_MMA(1, 1, At, B1); PG8_BAR; PG8_SCHED;
.LBB0_211:
	s_add_u32 s24, s60, 0xfffc0080
	s_addc_u32 s25, s61, -1
	s_add_i32 s46, 0, 0x10000
	s_cmp_eq_u32 s45, 12
	s_cselect_b32 s63, s2, s25
	s_cselect_b32 s62, s3, s24
	s_cselect_b32 s25, s17, s44
	s_cselect_b32 s24, s19, s43
	s_add_i32 s47, 0, 0x14000
	v_add_u32_e32 v154, s46, v147
	v_add_u32_e32 v158, s47, v147
	s_add_i32 m0, s55, 0xc000
	ds_read_b128 v[138:141], v154
	global_load_lds_dwordx4 v134, s[60:61]
	ds_read_b128 v[142:145], v154 offset:1024
	ds_read_b128 v[150:153], v154 offset:2048
	ds_read_b128 v[154:157], v154 offset:3072
	ds_read_b128 v[170:173], v158
	ds_read_b128 v[174:177], v158 offset:1024
	ds_read_b128 v[178:181], v158 offset:2048
	ds_read_b128 v[182:185], v158 offset:3072
	ds_read_b128 v[186:189], v149
	s_add_i32 m0, s55, 0xe000
	ds_read_b128 v[190:193], v149 offset:1024
	global_load_lds_dwordx4 v136, s[60:61]
	ds_read_b128 v[194:197], v149 offset:2048
	ds_read_b128 v[198:201], v149 offset:3072
	ds_read_b128 v[202:205], v149 offset:4096
	ds_read_b128 v[206:209], v149 offset:5120
	ds_read_b128 v[210:213], v149 offset:6144
	ds_read_b128 v[214:217], v149 offset:7168
	s_waitcnt vmcnt(8)
	s_waitcnt lgkmcnt(0)
	s_barrier
	s_setprio 1
	s_waitcnt lgkmcnt(0)
	v_mfma_f32_16x16x32_bf16 v[124:127], v[138:141], v[186:189], v[124:127]
	v_mfma_f32_16x16x32_bf16 v[120:123], v[150:153], v[186:189], v[120:123]
	v_mfma_f32_16x16x32_bf16 v[108:111], v[138:141], v[194:197], v[108:111]
	v_mfma_f32_16x16x32_bf16 v[104:107], v[150:153], v[194:197], v[104:107]
	v_mfma_f32_16x16x32_bf16 v[92:95], v[138:141], v[202:205], v[92:95]
	v_mfma_f32_16x16x32_bf16 v[88:91], v[150:153], v[202:205], v[88:91]
	v_mfma_f32_16x16x32_bf16 v[76:79], v[138:141], v[210:213], v[76:79]
	v_mfma_f32_16x16x32_bf16 v[72:75], v[150:153], v[210:213], v[72:75]
	v_mfma_f32_16x16x32_bf16 v[124:127], v[142:145], v[190:193], v[124:127]
	v_mfma_f32_16x16x32_bf16 v[120:123], v[154:157], v[190:193], v[120:123]
	v_mfma_f32_16x16x32_bf16 v[108:111], v[142:145], v[198:201], v[108:111]
	v_mfma_f32_16x16x32_bf16 v[104:107], v[154:157], v[198:201], v[104:107]
	v_mfma_f32_16x16x32_bf16 v[92:95], v[142:145], v[206:209], v[92:95]
	v_mfma_f32_16x16x32_bf16 v[88:91], v[154:157], v[206:209], v[88:91]
	v_mfma_f32_16x16x32_bf16 v[76:79], v[142:145], v[214:217], v[76:79]
	v_mfma_f32_16x16x32_bf16 v[72:75], v[154:157], v[214:217], v[72:75]
	s_setprio 0
	s_setprio 1
	v_mfma_f32_16x16x32_bf16 v[116:119], v[170:173], v[186:189], v[116:119]
	v_mfma_f32_16x16x32_bf16 v[112:115], v[178:181], v[186:189], v[112:115]
	v_mfma_f32_16x16x32_bf16 v[100:103], v[170:173], v[194:197], v[100:103]
	v_mfma_f32_16x16x32_bf16 v[96:99], v[178:181], v[194:197], v[96:99]
	v_mfma_f32_16x16x32_bf16 v[84:87], v[170:173], v[202:205], v[84:87]
	v_mfma_f32_16x16x32_bf16 v[80:83], v[178:181], v[202:205], v[80:83]
	v_mfma_f32_16x16x32_bf16 v[68:71], v[170:173], v[210:213], v[68:71]
	v_mfma_f32_16x16x32_bf16 v[64:67], v[178:181], v[210:213], v[64:67]
	v_mfma_f32_16x16x32_bf16 v[116:119], v[174:177], v[190:193], v[116:119]
	v_mfma_f32_16x16x32_bf16 v[112:115], v[182:185], v[190:193], v[112:115]
	v_mfma_f32_16x16x32_bf16 v[100:103], v[174:177], v[198:201], v[100:103]
	v_mfma_f32_16x16x32_bf16 v[96:99], v[182:185], v[198:201], v[96:99]
	v_mfma_f32_16x16x32_bf16 v[84:87], v[174:177], v[206:209], v[84:87]
	v_mfma_f32_16x16x32_bf16 v[80:83], v[182:185], v[206:209], v[80:83]
	v_mfma_f32_16x16x32_bf16 v[68:71], v[174:177], v[214:217], v[68:71]
	v_mfma_f32_16x16x32_bf16 v[64:67], v[182:185], v[214:217], v[64:67]
	s_setprio 0
	s_barrier
	s_add_i32 s46, s46, s73
	s_mov_b32 m0, s46
	ds_read_b128 v[186:189], v149 offset:16384
	global_load_lds_dwordx4 v160, s[24:25]
	ds_read_b128 v[190:193], v149 offset:17408
	ds_read_b128 v[194:197], v149 offset:18432
	s_add_i32 m0, s46, 0x2000
	s_add_u32 s94, s24, 0x40000
	s_addc_u32 s95, s25, 0
	s_add_i32 s46, s47, s73
	global_load_lds_dwordx4 v132, s[24:25]
	ds_read_b128 v[198:201], v149 offset:19456
	s_mov_b32 m0, s46
	ds_read_b128 v[202:205], v149 offset:20480
	global_load_lds_dwordx4 v160, s[94:95]
	ds_read_b128 v[206:209], v149 offset:21504
	s_add_i32 m0, s46, 0x2000
	ds_read_b128 v[210:213], v149 offset:22528
	global_load_lds_dwordx4 v132, s[94:95]
	ds_read_b128 v[214:217], v149 offset:23552
	s_mov_b32 m0, s55
	s_nop 0
	global_load_lds_dwordx4 v128, s[62:63]
	s_mov_b32 m0, s79
	s_nop 0
	global_load_lds_dwordx4 v130, s[62:63]
	s_waitcnt vmcnt(8)
	s_waitcnt lgkmcnt(0)
	s_barrier
	s_setprio 1
	s_waitcnt lgkmcnt(0)
	v_mfma_f32_16x16x32_bf16 v[60:63], v[138:141], v[186:189], v[60:63]
	v_mfma_f32_16x16x32_bf16 v[56:59], v[150:153], v[186:189], v[56:59]
	v_mfma_f32_16x16x32_bf16 v[44:47], v[138:141], v[194:197], v[44:47]
	v_mfma_f32_16x16x32_bf16 v[40:43], v[150:153], v[194:197], v[40:43]
	v_mfma_f32_16x16x32_bf16 v[28:31], v[138:141], v[202:205], v[28:31]
	v_mfma_f32_16x16x32_bf16 v[24:27], v[150:153], v[202:205], v[24:27]
	v_mfma_f32_16x16x32_bf16 v[12:15], v[138:141], v[210:213], v[12:15]
	v_mfma_f32_16x16x32_bf16 v[8:11], v[150:153], v[210:213], v[8:11]
	v_mfma_f32_16x16x32_bf16 v[60:63], v[142:145], v[190:193], v[60:63]
	v_mfma_f32_16x16x32_bf16 v[56:59], v[154:157], v[190:193], v[56:59]
	v_mfma_f32_16x16x32_bf16 v[44:47], v[142:145], v[198:201], v[44:47]
	v_mfma_f32_16x16x32_bf16 v[40:43], v[154:157], v[198:201], v[40:43]
	v_mfma_f32_16x16x32_bf16 v[28:31], v[142:145], v[206:209], v[28:31]
	v_mfma_f32_16x16x32_bf16 v[24:27], v[154:157], v[206:209], v[24:27]
	v_mfma_f32_16x16x32_bf16 v[12:15], v[142:145], v[214:217], v[12:15]
	v_mfma_f32_16x16x32_bf16 v[8:11], v[154:157], v[214:217], v[8:11]
	s_setprio 0
	s_setprio 1
	v_mfma_f32_16x16x32_bf16 v[52:55], v[170:173], v[186:189], v[52:55]
	v_mfma_f32_16x16x32_bf16 v[48:51], v[178:181], v[186:189], v[48:51]
	v_mfma_f32_16x16x32_bf16 v[36:39], v[170:173], v[194:197], v[36:39]
	v_mfma_f32_16x16x32_bf16 v[32:35], v[178:181], v[194:197], v[32:35]
	v_mfma_f32_16x16x32_bf16 v[20:23], v[170:173], v[202:205], v[20:23]
	v_mfma_f32_16x16x32_bf16 v[16:19], v[178:181], v[202:205], v[16:19]
	v_mfma_f32_16x16x32_bf16 v[4:7], v[170:173], v[210:213], v[4:7]
	v_mfma_f32_16x16x32_bf16 v[0:3], v[178:181], v[210:213], v[0:3]
	v_mfma_f32_16x16x32_bf16 v[52:55], v[174:177], v[190:193], v[52:55]
	v_mfma_f32_16x16x32_bf16 v[48:51], v[182:185], v[190:193], v[48:51]
	v_mfma_f32_16x16x32_bf16 v[36:39], v[174:177], v[198:201], v[36:39]
	v_mfma_f32_16x16x32_bf16 v[32:35], v[182:185], v[198:201], v[32:35]
	v_mfma_f32_16x16x32_bf16 v[20:23], v[174:177], v[206:209], v[20:23]
	v_mfma_f32_16x16x32_bf16 v[16:19], v[182:185], v[206:209], v[16:19]
	v_mfma_f32_16x16x32_bf16 v[4:7], v[174:177], v[214:217], v[4:7]
	v_mfma_f32_16x16x32_bf16 v[0:3], v[182:185], v[214:217], v[0:3]
	s_setprio 0
	s_barrier
; #define PG8_STAGE(bufoff, gbase, voff) do { _Pragma("unroll") for (int _i = 0; _i < 2; ++_i) \
;         __builtin_amdgcn_global_load_lds((const unsigned*)((const char*)(gbase) + (voff)[_i]), (LAS unsigned*)(lds + (bufoff) + ldsw + _i * 8192), 16, 0, 0); } while (0)
; #define PG8_LDA(dst, b, h) do { _Pragma("unroll") for (int m = 0; m < 4; ++m) _Pragma("unroll") for (int k = 0; k < 2; ++k) dst[m][k] = *(const LAS bf16x8*)(lds + PG8_SA(b, h) + aoff + m * 2048 + k * 1024); } while (0)
; #define PG8_LDB(dst, b, h) do { _Pragma("unroll") for (int n = 0; n < 2; ++n) _Pragma("unroll") for (int k = 0; k < 2; ++k) dst[n][k] = *(const LAS bf16x8*)(lds + PG8_SB(b, h) + boff + n * 2048 + k * 1024); } while (0)
; #define PG8_WAIT_V(n) asm volatile("s_waitcnt vmcnt(" #n ")" ::: "memory")
; #define PG8_WAIT_L(n) asm volatile("s_waitcnt lgkmcnt(" #n ")" ::: "memory")
; template <class Epi, class Sched, bool ALIGN_EPI = true, bool SP2 = true>
; __device__ __forceinline__ void gemm_phase(LAS unsigned char* lds, const Gemm g, const Sched& S, const Epi& E) {
;     ...
;             const char* a1 = cA + (size_t)(t + 1) * kstep;
;             const char* a2 = last ? nA : cA + (size_t)(t + 2) * kstep; const char* b2 = last ? nB : cB + (size_t)(t + 2) * kstep;
;             const char* a3 = a2 + kstep; const char* b3 = b2 + kstep;
;             if constexpr (SP2) {
;             PG8_LDB(B0, 0, 0); PG8_LDB(B1, 0, 1); PG8_SCHED; PG8_LDA(At, 0, 0); PG8_STAGE(PG8_SA(1, 1), a1 + hstep, voffA);
;             PG8_WAIT_V(8); PG8_WAIT_L(0); PG8_BAR; PG8_MMA(0, 0, At, B0); PG8_MMA(0, 1, At, B1); PG8_BAR; PG8_SCHED;
;             PG8_LDA(At, 0, 1); PG8_STAGE(PG8_SB(0, 0), b2, voffB); PG8_STAGE(PG8_SB(0, 1), b2 + hstep, voffB); PG8_STAGE(PG8_SA(0, 0), a2, voffA);
;             PG8_WAIT_V(8); PG8_WAIT_L(0); PG8_BAR; PG8_MMA(1, 0, At, B0); PG8_MMA(1, 1, At, B1); PG8_BAR; PG8_SCHED;
;             PG8_LDB(B0, 1, 0); PG8_LDB(B1, 1, 1); PG8_SCHED; PG8_LDA(At, 1, 0); PG8_STAGE(PG8_SA(0, 1), a2 + hstep, voffA);
;             PG8_WAIT_V(8); PG8_WAIT_L(0); PG8_BAR; PG8_MMA(0, 0, At, B0); PG8_MMA(0, 1, At, B1); PG8_BAR; PG8_SCHED;
;             PG8_LDA(At, 1, 1); PG8_STAGE(PG8_SB(1, 0), b3, voffB); PG8_STAGE(PG8_SB(1, 1), b3 + hstep, voffB); PG8_STAGE(PG8_SA(1, 0), a3, voffA);
;             PG8_WAIT_V(8); PG8_WAIT_L(0); PG8_BAR; PG8_MMA(1, 0, At, B0); PG8_MMA(1, 1, At, B1); PG8_BAR; PG8_SCHED;
	s_add_i32 s46, 0, 0x18000
	s_add_i32 s47, 0, 0x1c000
	v_add_u32_e32 v154, s46, v147
	v_add_u32_e32 v182, s47, v147
	s_add_u32 s62, s62, 0x40000
	s_addc_u32 s63, s63, 0
	s_mov_b32 m0, s82
	ds_read_b128 v[138:141], v154
	global_load_lds_dwordx4 v128, s[62:63]
	ds_read_b128 v[142:145], v154 offset:1024
	ds_read_b128 v[150:153], v154 offset:2048
	ds_read_b128 v[154:157], v154 offset:3072
	ds_read_b128 v[170:173], v182
	ds_read_b128 v[174:177], v182 offset:1024
	ds_read_b128 v[178:181], v182 offset:2048
	ds_read_b128 v[182:185], v182 offset:3072
	ds_read_b128 v[186:189], v149 offset:32768
	s_mov_b32 m0, s83
	ds_read_b128 v[190:193], v149 offset:33792
	global_load_lds_dwordx4 v130, s[62:63]
	ds_read_b128 v[194:197], v149 offset:34816
	ds_read_b128 v[198:201], v149 offset:35840
	ds_read_b128 v[202:205], v149 offset:36864
	ds_read_b128 v[206:209], v149 offset:37888
	ds_read_b128 v[210:213], v149 offset:38912
	ds_read_b128 v[214:217], v149 offset:39936
	s_waitcnt vmcnt(8)
	s_waitcnt lgkmcnt(0)
	s_barrier
	s_setprio 1
	s_waitcnt lgkmcnt(0)
	v_mfma_f32_16x16x32_bf16 v[124:127], v[138:141], v[186:189], v[124:127]
	v_mfma_f32_16x16x32_bf16 v[120:123], v[150:153], v[186:189], v[120:123]
	v_mfma_f32_16x16x32_bf16 v[108:111], v[138:141], v[194:197], v[108:111]
	v_mfma_f32_16x16x32_bf16 v[104:107], v[150:153], v[194:197], v[104:107]
	v_mfma_f32_16x16x32_bf16 v[92:95], v[138:141], v[202:205], v[92:95]
	v_mfma_f32_16x16x32_bf16 v[88:91], v[150:153], v[202:205], v[88:91]
	v_mfma_f32_16x16x32_bf16 v[76:79], v[138:141], v[210:213], v[76:79]
	v_mfma_f32_16x16x32_bf16 v[72:75], v[150:153], v[210:213], v[72:75]
	v_mfma_f32_16x16x32_bf16 v[124:127], v[142:145], v[190:193], v[124:127]
	v_mfma_f32_16x16x32_bf16 v[120:123], v[154:157], v[190:193], v[120:123]
	v_mfma_f32_16x16x32_bf16 v[108:111], v[142:145], v[198:201], v[108:111]
	v_mfma_f32_16x16x32_bf16 v[104:107], v[154:157], v[198:201], v[104:107]
	v_mfma_f32_16x16x32_bf16 v[92:95], v[142:145], v[206:209], v[92:95]
	v_mfma_f32_16x16x32_bf16 v[88:91], v[154:157], v[206:209], v[88:91]
	v_mfma_f32_16x16x32_bf16 v[76:79], v[142:145], v[214:217], v[76:79]
	v_mfma_f32_16x16x32_bf16 v[72:75], v[154:157], v[214:217], v[72:75]
	s_setprio 0
	s_setprio 1
	v_mfma_f32_16x16x32_bf16 v[116:119], v[170:173], v[186:189], v[116:119]
	v_mfma_f32_16x16x32_bf16 v[112:115], v[178:181], v[186:189], v[112:115]
	v_mfma_f32_16x16x32_bf16 v[100:103], v[170:173], v[194:197], v[100:103]
	v_mfma_f32_16x16x32_bf16 v[96:99], v[178:181], v[194:197], v[96:99]
	v_mfma_f32_16x16x32_bf16 v[84:87], v[170:173], v[202:205], v[84:87]
	v_mfma_f32_16x16x32_bf16 v[80:83], v[178:181], v[202:205], v[80:83]
	v_mfma_f32_16x16x32_bf16 v[68:71], v[170:173], v[210:213], v[68:71]
	v_mfma_f32_16x16x32_bf16 v[64:67], v[178:181], v[210:213], v[64:67]
	v_mfma_f32_16x16x32_bf16 v[116:119], v[174:177], v[190:193], v[116:119]
	v_mfma_f32_16x16x32_bf16 v[112:115], v[182:185], v[190:193], v[112:115]
	v_mfma_f32_16x16x32_bf16 v[100:103], v[174:177], v[198:201], v[100:103]
	v_mfma_f32_16x16x32_bf16 v[96:99], v[182:185], v[198:201], v[96:99]
	v_mfma_f32_16x16x32_bf16 v[84:87], v[174:177], v[206:209], v[84:87]
	v_mfma_f32_16x16x32_bf16 v[80:83], v[182:185], v[206:209], v[80:83]
	v_mfma_f32_16x16x32_bf16 v[68:71], v[174:177], v[214:217], v[68:71]
	v_mfma_f32_16x16x32_bf16 v[64:67], v[182:185], v[214:217], v[64:67]
	s_setprio 0
	s_barrier
	s_add_i32 s46, s46, s73
	s_mov_b32 m0, s46
	s_add_u32 s98, s24, 0x80
	s_addc_u32 s99, s25, 0
	global_load_lds_dwordx4 v160, s[98:99]
	ds_read_b128 v[186:189], v149 offset:49152
	ds_read_b128 v[190:193], v149 offset:50176
	s_add_i32 m0, s46, 0x2000
	s_add_u32 s24, s24, 0x40080
	s_addc_u32 s25, s25, 0
	s_add_i32 s46, s47, s73
	global_load_lds_dwordx4 v132, s[98:99]
	ds_read_b128 v[194:197], v149 offset:51200
	ds_read_b128 v[198:201], v149 offset:52224
	s_mov_b32 m0, s46
	ds_read_b128 v[202:205], v149 offset:53248
	global_load_lds_dwordx4 v160, s[24:25]
	ds_read_b128 v[206:209], v149 offset:54272
	s_add_i32 m0, s46, 0x2000
	ds_read_b128 v[210:213], v149 offset:55296
	global_load_lds_dwordx4 v132, s[24:25]
	ds_read_b128 v[214:217], v149 offset:56320
	s_mov_b32 m0, s90
	s_add_u32 s98, s62, 0xfffc0080
	s_addc_u32 s99, s63, -1
	global_load_lds_dwordx4 v128, s[98:99]
	s_mov_b32 m0, s91
	s_nop 0
	global_load_lds_dwordx4 v130, s[98:99]
	s_waitcnt vmcnt(8)
	s_waitcnt lgkmcnt(0)
	s_barrier
	s_setprio 1
	s_waitcnt lgkmcnt(0)
	v_mfma_f32_16x16x32_bf16 v[60:63], v[138:141], v[186:189], v[60:63]
	v_mfma_f32_16x16x32_bf16 v[56:59], v[150:153], v[186:189], v[56:59]
	v_mfma_f32_16x16x32_bf16 v[44:47], v[138:141], v[194:197], v[44:47]
	v_mfma_f32_16x16x32_bf16 v[40:43], v[150:153], v[194:197], v[40:43]
	v_mfma_f32_16x16x32_bf16 v[28:31], v[138:141], v[202:205], v[28:31]
	v_mfma_f32_16x16x32_bf16 v[24:27], v[150:153], v[202:205], v[24:27]
	v_mfma_f32_16x16x32_bf16 v[12:15], v[138:141], v[210:213], v[12:15]
	v_mfma_f32_16x16x32_bf16 v[8:11], v[150:153], v[210:213], v[8:11]
	v_mfma_f32_16x16x32_bf16 v[60:63], v[142:145], v[190:193], v[60:63]
	v_mfma_f32_16x16x32_bf16 v[56:59], v[154:157], v[190:193], v[56:59]
	v_mfma_f32_16x16x32_bf16 v[44:47], v[142:145], v[198:201], v[44:47]
	v_mfma_f32_16x16x32_bf16 v[40:43], v[154:157], v[198:201], v[40:43]
	v_mfma_f32_16x16x32_bf16 v[28:31], v[142:145], v[206:209], v[28:31]
	v_mfma_f32_16x16x32_bf16 v[24:27], v[154:157], v[206:209], v[24:27]
	v_mfma_f32_16x16x32_bf16 v[12:15], v[142:145], v[214:217], v[12:15]
	v_mfma_f32_16x16x32_bf16 v[8:11], v[154:157], v[214:217], v[8:11]
	s_setprio 0
	s_setprio 1
	v_mfma_f32_16x16x32_bf16 v[52:55], v[170:173], v[186:189], v[52:55]
	v_mfma_f32_16x16x32_bf16 v[48:51], v[178:181], v[186:189], v[48:51]
	v_mfma_f32_16x16x32_bf16 v[36:39], v[170:173], v[194:197], v[36:39]
	v_mfma_f32_16x16x32_bf16 v[32:35], v[178:181], v[194:197], v[32:35]
	v_mfma_f32_16x16x32_bf16 v[20:23], v[170:173], v[202:205], v[20:23]
	v_mfma_f32_16x16x32_bf16 v[16:19], v[178:181], v[202:205], v[16:19]
	v_mfma_f32_16x16x32_bf16 v[4:7], v[170:173], v[210:213], v[4:7]
	v_mfma_f32_16x16x32_bf16 v[0:3], v[178:181], v[210:213], v[0:3]
	v_mfma_f32_16x16x32_bf16 v[52:55], v[174:177], v[190:193], v[52:55]
	v_mfma_f32_16x16x32_bf16 v[48:51], v[182:185], v[190:193], v[48:51]
	v_mfma_f32_16x16x32_bf16 v[36:39], v[174:177], v[198:201], v[36:39]
	v_mfma_f32_16x16x32_bf16 v[32:35], v[182:185], v[198:201], v[32:35]
	v_mfma_f32_16x16x32_bf16 v[20:23], v[174:177], v[206:209], v[20:23]
	v_mfma_f32_16x16x32_bf16 v[16:19], v[182:185], v[206:209], v[16:19]
	v_mfma_f32_16x16x32_bf16 v[4:7], v[174:177], v[214:217], v[4:7]
	v_mfma_f32_16x16x32_bf16 v[0:3], v[182:185], v[214:217], v[0:3]
	s_setprio 0
	s_barrier
	s_add_i32 s45, s45, 2
	s_add_u32 s60, s60, 0x100
	s_addc_u32 s61, s61, 0
	s_add_u32 s43, s43, 0x100
	s_addc_u32 s44, s44, 0
	s_cmp_gt_u32 s45, 13
	s_cbranch_scc0 .LBB0_211
	s_and_b64 vcc, exec, s[14:15]
	s_cbranch_vccz .LBB0_214
	s_barrier

; #define PG8_STAGE(bufoff, gbase, voff) do { _Pragma("unroll") for (int _i = 0; _i < 2; ++_i) \
;         __builtin_amdgcn_global_load_lds((const unsigned*)((const char*)(gbase) + (voff)[_i]), (LAS unsigned*)(lds + (bufoff) + ldsw + _i * 8192), 16, 0, 0); } while (0)
; #define PG8_LDA(dst, b, h) do { _Pragma("unroll") for (int m = 0; m < 4; ++m) _Pragma("unroll") for (int k = 0; k < 2; ++k) dst[m][k] = *(const LAS bf16x8*)(lds + PG8_SA(b, h) + aoff + m * 2048 + k * 1024); } while (0)
; #define PG8_LDB(dst, b, h) do { _Pragma("unroll") for (int n = 0; n < 2; ++n) _Pragma("unroll") for (int k = 0; k < 2; ++k) dst[n][k] = *(const LAS bf16x8*)(lds + PG8_SB(b, h) + boff + n * 2048 + k * 1024); } while (0)
; #define PG8_MMA(ai, bj, At, Bt) do { __builtin_amdgcn_s_setprio(1); _Pragma("unroll") for (int m = 0; m < 4; ++m) _Pragma("unroll") for (int n = 0; n < 2; ++n) _Pragma("unroll") for (int k = 0; k < 2; ++k) \
;         acc[ai][bj][m][n] = __builtin_amdgcn_mfma_f32_16x16x32_bf16(Bt[n][k], At[m][k], acc[ai][bj][m][n], 0, 0, 0); __builtin_amdgcn_s_setprio(0); } while (0)
; #define PG8_WAIT_V(n) asm volatile("s_waitcnt vmcnt(" #n ")" ::: "memory")
; #define PG8_WAIT_L(n) asm volatile("s_waitcnt lgkmcnt(" #n ")" ::: "memory")
; #define PG8_BAR __builtin_amdgcn_s_barrier()
; #define PG8_SCHED __builtin_amdgcn_sched_barrier(0)
; template <class Epi, class Sched, bool ALIGN_EPI = true, bool SP2 = true>
; __device__ __forceinline__ void gemm_phase(LAS unsigned char* lds, const Gemm g, const Sched& S, const Epi& E) {
;     ...
;             const char* a1 = cA + (size_t)(t + 1) * kstep;
;             const char* a2 = last ? nA : cA + (size_t)(t + 2) * kstep; const char* b2 = last ? nB : cB + (size_t)(t + 2) * kstep;
;             const char* a3 = a2 + kstep; const char* b3 = b2 + kstep;
;             if constexpr (SP2) {
;             PG8_LDB(B0, 0, 0); PG8_LDB(B1, 0, 1); PG8_SCHED; PG8_LDA(At, 0, 0); PG8_STAGE(PG8_SA(1, 1), a1 + hstep, voffA);
;             PG8_WAIT_V(8); PG8_WAIT_L(0); PG8_BAR; PG8_MMA(0, 0, At, B0); PG8_MMA(0, 1, At, B1); PG8_BAR; PG8_SCHED;
;             PG8_LDA(At, 0, 1); PG8_STAGE(PG8_SB(0, 0), b2, voffB); PG8_STAGE(PG8_SB(0, 1), b2 + hstep, voffB); PG8_STAGE(PG8_SA(0, 0), a2, voffA);
;             PG8_WAIT_V(8); PG8_WAIT_L(0); PG8_BAR; PG8_MMA(1, 0, At, B0); PG8_MMA(1, 1, At, B1); PG8_BAR; PG8_SCHED;
.LBB0_237:
	s_add_u32 s24, s54, 0xfffc0080
	s_addc_u32 s25, s55, -1
	s_add_i32 s46, 0, 0x10000
	s_cmp_eq_u32 s92, 12
	s_cselect_b32 s61, s2, s25
	s_cselect_b32 s60, s3, s24
	v_add_u32_e32 v142, s46, v145
	s_cselect_b32 s25, s17, s91
	s_cselect_b32 s24, s19, s90
	s_add_i32 s47, 0, 0x14000
	ds_read_b128 v[138:141], v142
	ds_read_b128 v[148:151], v142 offset:1024
	ds_read_b128 v[152:155], v142 offset:2048
	ds_read_b128 v[156:159], v142 offset:3072
	v_add_u32_e32 v142, s47, v145
	s_add_i32 m0, s44, 0xc000
	ds_read_b128 v[170:173], v142
	global_load_lds_dwordx4 v134, s[54:55]
	ds_read_b128 v[174:177], v142 offset:1024
	ds_read_b128 v[178:181], v142 offset:2048
	ds_read_b128 v[182:185], v142 offset:3072
	ds_read_b128 v[186:189], v147
	ds_read_b128 v[190:193], v147 offset:1024
	ds_read_b128 v[194:197], v147 offset:2048
	s_add_i32 m0, s44, 0xe000
	ds_read_b128 v[198:201], v147 offset:3072
	global_load_lds_dwordx4 v136, s[54:55]
	ds_read_b128 v[202:205], v147 offset:4096
	ds_read_b128 v[206:209], v147 offset:5120
	ds_read_b128 v[210:213], v147 offset:6144
	ds_read_b128 v[214:217], v147 offset:7168
	s_waitcnt vmcnt(8)
	s_waitcnt lgkmcnt(0)
	s_barrier
	s_setprio 1
	s_waitcnt lgkmcnt(0)
	v_mfma_f32_16x16x32_bf16 v[124:127], v[138:141], v[186:189], v[124:127]
	v_mfma_f32_16x16x32_bf16 v[120:123], v[152:155], v[186:189], v[120:123]
	v_mfma_f32_16x16x32_bf16 v[108:111], v[138:141], v[194:197], v[108:111]
	v_mfma_f32_16x16x32_bf16 v[104:107], v[152:155], v[194:197], v[104:107]
	v_mfma_f32_16x16x32_bf16 v[92:95], v[138:141], v[202:205], v[92:95]
	v_mfma_f32_16x16x32_bf16 v[88:91], v[152:155], v[202:205], v[88:91]
	v_mfma_f32_16x16x32_bf16 v[76:79], v[138:141], v[210:213], v[76:79]
	v_mfma_f32_16x16x32_bf16 v[72:75], v[152:155], v[210:213], v[72:75]
	v_mfma_f32_16x16x32_bf16 v[124:127], v[148:151], v[190:193], v[124:127]
	v_mfma_f32_16x16x32_bf16 v[120:123], v[156:159], v[190:193], v[120:123]
	v_mfma_f32_16x16x32_bf16 v[108:111], v[148:151], v[198:201], v[108:111]
	v_mfma_f32_16x16x32_bf16 v[104:107], v[156:159], v[198:201], v[104:107]
	v_mfma_f32_16x16x32_bf16 v[92:95], v[148:151], v[206:209], v[92:95]
	v_mfma_f32_16x16x32_bf16 v[88:91], v[156:159], v[206:209], v[88:91]
	v_mfma_f32_16x16x32_bf16 v[76:79], v[148:151], v[214:217], v[76:79]
	v_mfma_f32_16x16x32_bf16 v[72:75], v[156:159], v[214:217], v[72:75]
	s_setprio 0
	s_setprio 1
	v_mfma_f32_16x16x32_bf16 v[116:119], v[170:173], v[186:189], v[116:119]
	v_mfma_f32_16x16x32_bf16 v[112:115], v[178:181], v[186:189], v[112:115]
	v_mfma_f32_16x16x32_bf16 v[100:103], v[170:173], v[194:197], v[100:103]
	v_mfma_f32_16x16x32_bf16 v[96:99], v[178:181], v[194:197], v[96:99]
	v_mfma_f32_16x16x32_bf16 v[84:87], v[170:173], v[202:205], v[84:87]
	v_mfma_f32_16x16x32_bf16 v[80:83], v[178:181], v[202:205], v[80:83]
	v_mfma_f32_16x16x32_bf16 v[68:71], v[170:173], v[210:213], v[68:71]
	v_mfma_f32_16x16x32_bf16 v[64:67], v[178:181], v[210:213], v[64:67]
	v_mfma_f32_16x16x32_bf16 v[116:119], v[174:177], v[190:193], v[116:119]
	v_mfma_f32_16x16x32_bf16 v[112:115], v[182:185], v[190:193], v[112:115]
	v_mfma_f32_16x16x32_bf16 v[100:103], v[174:177], v[198:201], v[100:103]
	v_mfma_f32_16x16x32_bf16 v[96:99], v[182:185], v[198:201], v[96:99]
	v_mfma_f32_16x16x32_bf16 v[84:87], v[174:177], v[206:209], v[84:87]
	v_mfma_f32_16x16x32_bf16 v[80:83], v[182:185], v[206:209], v[80:83]
	v_mfma_f32_16x16x32_bf16 v[68:71], v[174:177], v[214:217], v[68:71]
	v_mfma_f32_16x16x32_bf16 v[64:67], v[182:185], v[214:217], v[64:67]
	s_setprio 0
	s_barrier
	s_add_i32 s46, s46, s43
	s_mov_b32 m0, s46
	ds_read_b128 v[186:189], v147 offset:16384
	global_load_lds_dwordx4 v160, s[24:25]
	ds_read_b128 v[190:193], v147 offset:17408
	ds_read_b128 v[194:197], v147 offset:18432
	s_add_i32 m0, s46, 0x2000
	s_add_u32 s94, s24, 0x40000
	s_addc_u32 s95, s25, 0
	s_add_i32 s46, s47, s43
	global_load_lds_dwordx4 v128, s[24:25]
	ds_read_b128 v[198:201], v147 offset:19456
	s_mov_b32 m0, s46
	ds_read_b128 v[202:205], v147 offset:20480
	global_load_lds_dwordx4 v160, s[94:95]
	ds_read_b128 v[206:209], v147 offset:21504
	s_add_i32 m0, s46, 0x2000
	ds_read_b128 v[210:213], v147 offset:22528
	global_load_lds_dwordx4 v128, s[94:95]
	ds_read_b128 v[214:217], v147 offset:23552
	s_mov_b32 m0, s44
	s_nop 0
	global_load_lds_dwordx4 v132, s[60:61]
	s_mov_b32 m0, s45
	s_nop 0
	global_load_lds_dwordx4 v130, s[60:61]
	s_waitcnt vmcnt(8)
	s_waitcnt lgkmcnt(0)
	s_barrier
	s_setprio 1
	s_waitcnt lgkmcnt(0)
	v_mfma_f32_16x16x32_bf16 v[60:63], v[138:141], v[186:189], v[60:63]
	v_mfma_f32_16x16x32_bf16 v[56:59], v[152:155], v[186:189], v[56:59]
	v_mfma_f32_16x16x32_bf16 v[44:47], v[138:141], v[194:197], v[44:47]
	v_mfma_f32_16x16x32_bf16 v[40:43], v[152:155], v[194:197], v[40:43]
	v_mfma_f32_16x16x32_bf16 v[28:31], v[138:141], v[202:205], v[28:31]
	v_mfma_f32_16x16x32_bf16 v[24:27], v[152:155], v[202:205], v[24:27]
	v_mfma_f32_16x16x32_bf16 v[12:15], v[138:141], v[210:213], v[12:15]
	v_mfma_f32_16x16x32_bf16 v[8:11], v[152:155], v[210:213], v[8:11]
	v_mfma_f32_16x16x32_bf16 v[60:63], v[148:151], v[190:193], v[60:63]
	v_mfma_f32_16x16x32_bf16 v[56:59], v[156:159], v[190:193], v[56:59]
	v_mfma_f32_16x16x32_bf16 v[44:47], v[148:151], v[198:201], v[44:47]
	v_mfma_f32_16x16x32_bf16 v[40:43], v[156:159], v[198:201], v[40:43]
	v_mfma_f32_16x16x32_bf16 v[28:31], v[148:151], v[206:209], v[28:31]
	v_mfma_f32_16x16x32_bf16 v[24:27], v[156:159], v[206:209], v[24:27]
	v_mfma_f32_16x16x32_bf16 v[12:15], v[148:151], v[214:217], v[12:15]
	v_mfma_f32_16x16x32_bf16 v[8:11], v[156:159], v[214:217], v[8:11]
	s_setprio 0
	s_setprio 1
	v_mfma_f32_16x16x32_bf16 v[52:55], v[170:173], v[186:189], v[52:55]
	v_mfma_f32_16x16x32_bf16 v[48:51], v[178:181], v[186:189], v[48:51]
	v_mfma_f32_16x16x32_bf16 v[36:39], v[170:173], v[194:197], v[36:39]
	v_mfma_f32_16x16x32_bf16 v[32:35], v[178:181], v[194:197], v[32:35]
	v_mfma_f32_16x16x32_bf16 v[20:23], v[170:173], v[202:205], v[20:23]
	v_mfma_f32_16x16x32_bf16 v[16:19], v[178:181], v[202:205], v[16:19]
	v_mfma_f32_16x16x32_bf16 v[4:7], v[170:173], v[210:213], v[4:7]
	v_mfma_f32_16x16x32_bf16 v[0:3], v[178:181], v[210:213], v[0:3]
	v_mfma_f32_16x16x32_bf16 v[52:55], v[174:177], v[190:193], v[52:55]
	v_mfma_f32_16x16x32_bf16 v[48:51], v[182:185], v[190:193], v[48:51]
	v_mfma_f32_16x16x32_bf16 v[36:39], v[174:177], v[198:201], v[36:39]
	v_mfma_f32_16x16x32_bf16 v[32:35], v[182:185], v[198:201], v[32:35]
	v_mfma_f32_16x16x32_bf16 v[20:23], v[174:177], v[206:209], v[20:23]
	v_mfma_f32_16x16x32_bf16 v[16:19], v[182:185], v[206:209], v[16:19]
	v_mfma_f32_16x16x32_bf16 v[4:7], v[174:177], v[214:217], v[4:7]
	v_mfma_f32_16x16x32_bf16 v[0:3], v[182:185], v[214:217], v[0:3]
	s_setprio 0
	s_barrier
; #define PG8_STAGE(bufoff, gbase, voff) do { _Pragma("unroll") for (int _i = 0; _i < 2; ++_i) \
;         __builtin_amdgcn_global_load_lds((const unsigned*)((const char*)(gbase) + (voff)[_i]), (LAS unsigned*)(lds + (bufoff) + ldsw + _i * 8192), 16, 0, 0); } while (0)
; #define PG8_LDA(dst, b, h) do { _Pragma("unroll") for (int m = 0; m < 4; ++m) _Pragma("unroll") for (int k = 0; k < 2; ++k) dst[m][k] = *(const LAS bf16x8*)(lds + PG8_SA(b, h) + aoff + m * 2048 + k * 1024); } while (0)
; #define PG8_LDB(dst, b, h) do { _Pragma("unroll") for (int n = 0; n < 2; ++n) _Pragma("unroll") for (int k = 0; k < 2; ++k) dst[n][k] = *(const LAS bf16x8*)(lds + PG8_SB(b, h) + boff + n * 2048 + k * 1024); } while (0)
; #define PG8_WAIT_V(n) asm volatile("s_waitcnt vmcnt(" #n ")" ::: "memory")
; #define PG8_WAIT_L(n) asm volatile("s_waitcnt lgkmcnt(" #n ")" ::: "memory")
; template <class Epi, class Sched, bool ALIGN_EPI = true, bool SP2 = true>
; __device__ __forceinline__ void gemm_phase(LAS unsigned char* lds, const Gemm g, const Sched& S, const Epi& E) {
;     ...
;             const char* a1 = cA + (size_t)(t + 1) * kstep;
;             const char* a2 = last ? nA : cA + (size_t)(t + 2) * kstep; const char* b2 = last ? nB : cB + (size_t)(t + 2) * kstep;
;             const char* a3 = a2 + kstep; const char* b3 = b2 + kstep;
;             if constexpr (SP2) {
;             PG8_LDB(B0, 0, 0); PG8_LDB(B1, 0, 1); PG8_SCHED; PG8_LDA(At, 0, 0); PG8_STAGE(PG8_SA(1, 1), a1 + hstep, voffA);
;             PG8_WAIT_V(8); PG8_WAIT_L(0); PG8_BAR; PG8_MMA(0, 0, At, B0); PG8_MMA(0, 1, At, B1); PG8_BAR; PG8_SCHED;
;             PG8_LDA(At, 0, 1); PG8_STAGE(PG8_SB(0, 0), b2, voffB); PG8_STAGE(PG8_SB(0, 1), b2 + hstep, voffB); PG8_STAGE(PG8_SA(0, 0), a2, voffA);
;             PG8_WAIT_V(8); PG8_WAIT_L(0); PG8_BAR; PG8_MMA(1, 0, At, B0); PG8_MMA(1, 1, At, B1); PG8_BAR; PG8_SCHED;
;             PG8_LDB(B0, 1, 0); PG8_LDB(B1, 1, 1); PG8_SCHED; PG8_LDA(At, 1, 0); PG8_STAGE(PG8_SA(0, 1), a2 + hstep, voffA);
;             PG8_WAIT_V(8); PG8_WAIT_L(0); PG8_BAR; PG8_MMA(0, 0, At, B0); PG8_MMA(0, 1, At, B1); PG8_BAR; PG8_SCHED;
;             PG8_LDA(At, 1, 1); PG8_STAGE(PG8_SB(1, 0), b3, voffB); PG8_STAGE(PG8_SB(1, 1), b3 + hstep, voffB); PG8_STAGE(PG8_SA(1, 0), a3, voffA);
;             PG8_WAIT_V(8); PG8_WAIT_L(0); PG8_BAR; PG8_MMA(1, 0, At, B0); PG8_MMA(1, 1, At, B1); PG8_BAR; PG8_SCHED;
	s_add_i32 s46, 0, 0x18000
	s_add_i32 s47, 0, 0x1c000
	v_add_u32_e32 v156, s46, v145
	v_add_u32_e32 v182, s47, v145
	s_add_u32 s60, s60, 0x40000
	s_addc_u32 s61, s61, 0
	s_mov_b32 m0, s62
	ds_read_b128 v[138:141], v156
	global_load_lds_dwordx4 v132, s[60:61]
	ds_read_b128 v[148:151], v156 offset:1024
	ds_read_b128 v[152:155], v156 offset:2048
	ds_read_b128 v[156:159], v156 offset:3072
	ds_read_b128 v[170:173], v182
	ds_read_b128 v[174:177], v182 offset:1024
	ds_read_b128 v[178:181], v182 offset:2048
	ds_read_b128 v[182:185], v182 offset:3072
	ds_read_b128 v[186:189], v147 offset:32768
	s_mov_b32 m0, s63
	ds_read_b128 v[190:193], v147 offset:33792
	global_load_lds_dwordx4 v130, s[60:61]
	ds_read_b128 v[194:197], v147 offset:34816
	ds_read_b128 v[198:201], v147 offset:35840
	ds_read_b128 v[202:205], v147 offset:36864
	ds_read_b128 v[206:209], v147 offset:37888
	ds_read_b128 v[210:213], v147 offset:38912
	ds_read_b128 v[214:217], v147 offset:39936
	s_waitcnt vmcnt(8)
	s_waitcnt lgkmcnt(0)
	s_barrier
	s_setprio 1
	s_waitcnt lgkmcnt(0)
	v_mfma_f32_16x16x32_bf16 v[124:127], v[138:141], v[186:189], v[124:127]
	v_mfma_f32_16x16x32_bf16 v[120:123], v[152:155], v[186:189], v[120:123]
	v_mfma_f32_16x16x32_bf16 v[108:111], v[138:141], v[194:197], v[108:111]
	v_mfma_f32_16x16x32_bf16 v[104:107], v[152:155], v[194:197], v[104:107]
	v_mfma_f32_16x16x32_bf16 v[92:95], v[138:141], v[202:205], v[92:95]
	v_mfma_f32_16x16x32_bf16 v[88:91], v[152:155], v[202:205], v[88:91]
	v_mfma_f32_16x16x32_bf16 v[76:79], v[138:141], v[210:213], v[76:79]
	v_mfma_f32_16x16x32_bf16 v[72:75], v[152:155], v[210:213], v[72:75]
	v_mfma_f32_16x16x32_bf16 v[124:127], v[148:151], v[190:193], v[124:127]
	v_mfma_f32_16x16x32_bf16 v[120:123], v[156:159], v[190:193], v[120:123]
	v_mfma_f32_16x16x32_bf16 v[108:111], v[148:151], v[198:201], v[108:111]
	v_mfma_f32_16x16x32_bf16 v[104:107], v[156:159], v[198:201], v[104:107]
	v_mfma_f32_16x16x32_bf16 v[92:95], v[148:151], v[206:209], v[92:95]
	v_mfma_f32_16x16x32_bf16 v[88:91], v[156:159], v[206:209], v[88:91]
	v_mfma_f32_16x16x32_bf16 v[76:79], v[148:151], v[214:217], v[76:79]
	v_mfma_f32_16x16x32_bf16 v[72:75], v[156:159], v[214:217], v[72:75]
	s_setprio 0
	s_setprio 1
	v_mfma_f32_16x16x32_bf16 v[116:119], v[170:173], v[186:189], v[116:119]
	v_mfma_f32_16x16x32_bf16 v[112:115], v[178:181], v[186:189], v[112:115]
	v_mfma_f32_16x16x32_bf16 v[100:103], v[170:173], v[194:197], v[100:103]
	v_mfma_f32_16x16x32_bf16 v[96:99], v[178:181], v[194:197], v[96:99]
	v_mfma_f32_16x16x32_bf16 v[84:87], v[170:173], v[202:205], v[84:87]
	v_mfma_f32_16x16x32_bf16 v[80:83], v[178:181], v[202:205], v[80:83]
	v_mfma_f32_16x16x32_bf16 v[68:71], v[170:173], v[210:213], v[68:71]
	v_mfma_f32_16x16x32_bf16 v[64:67], v[178:181], v[210:213], v[64:67]
	v_mfma_f32_16x16x32_bf16 v[116:119], v[174:177], v[190:193], v[116:119]
	v_mfma_f32_16x16x32_bf16 v[112:115], v[182:185], v[190:193], v[112:115]
	v_mfma_f32_16x16x32_bf16 v[100:103], v[174:177], v[198:201], v[100:103]
	v_mfma_f32_16x16x32_bf16 v[96:99], v[182:185], v[198:201], v[96:99]
	v_mfma_f32_16x16x32_bf16 v[84:87], v[174:177], v[206:209], v[84:87]
	v_mfma_f32_16x16x32_bf16 v[80:83], v[182:185], v[206:209], v[80:83]
	v_mfma_f32_16x16x32_bf16 v[68:71], v[174:177], v[214:217], v[68:71]
	v_mfma_f32_16x16x32_bf16 v[64:67], v[182:185], v[214:217], v[64:67]
	s_setprio 0
	s_barrier
	s_add_i32 s46, s46, s43
	s_mov_b32 m0, s46
	s_add_u32 s98, s24, 0x80
	s_addc_u32 s99, s25, 0
	global_load_lds_dwordx4 v160, s[98:99]
	ds_read_b128 v[186:189], v147 offset:49152
	ds_read_b128 v[190:193], v147 offset:50176
	s_add_i32 m0, s46, 0x2000
	s_add_u32 s24, s24, 0x40080
	s_addc_u32 s25, s25, 0
	s_add_i32 s46, s47, s43
	global_load_lds_dwordx4 v128, s[98:99]
	ds_read_b128 v[194:197], v147 offset:51200
	ds_read_b128 v[198:201], v147 offset:52224
	s_mov_b32 m0, s46
	ds_read_b128 v[202:205], v147 offset:53248
	global_load_lds_dwordx4 v160, s[24:25]
	ds_read_b128 v[206:209], v147 offset:54272
	s_add_i32 m0, s46, 0x2000
	ds_read_b128 v[210:213], v147 offset:55296
	global_load_lds_dwordx4 v128, s[24:25]
	ds_read_b128 v[214:217], v147 offset:56320
	s_mov_b32 m0, s67
	s_add_u32 s98, s60, 0xfffc0080
	s_addc_u32 s99, s61, -1
	global_load_lds_dwordx4 v132, s[98:99]
	s_mov_b32 m0, s72
	s_nop 0
	global_load_lds_dwordx4 v130, s[98:99]
	s_waitcnt vmcnt(8)
	s_waitcnt lgkmcnt(0)
	s_barrier
	s_setprio 1
	s_waitcnt lgkmcnt(0)
	v_mfma_f32_16x16x32_bf16 v[60:63], v[138:141], v[186:189], v[60:63]
	v_mfma_f32_16x16x32_bf16 v[56:59], v[152:155], v[186:189], v[56:59]
	v_mfma_f32_16x16x32_bf16 v[44:47], v[138:141], v[194:197], v[44:47]
	v_mfma_f32_16x16x32_bf16 v[40:43], v[152:155], v[194:197], v[40:43]
	v_mfma_f32_16x16x32_bf16 v[28:31], v[138:141], v[202:205], v[28:31]
	v_mfma_f32_16x16x32_bf16 v[24:27], v[152:155], v[202:205], v[24:27]
	v_mfma_f32_16x16x32_bf16 v[12:15], v[138:141], v[210:213], v[12:15]
	v_mfma_f32_16x16x32_bf16 v[8:11], v[152:155], v[210:213], v[8:11]
	v_mfma_f32_16x16x32_bf16 v[60:63], v[148:151], v[190:193], v[60:63]
	v_mfma_f32_16x16x32_bf16 v[56:59], v[156:159], v[190:193], v[56:59]
	v_mfma_f32_16x16x32_bf16 v[44:47], v[148:151], v[198:201], v[44:47]
	v_mfma_f32_16x16x32_bf16 v[40:43], v[156:159], v[198:201], v[40:43]
	v_mfma_f32_16x16x32_bf16 v[28:31], v[148:151], v[206:209], v[28:31]
	v_mfma_f32_16x16x32_bf16 v[24:27], v[156:159], v[206:209], v[24:27]
	v_mfma_f32_16x16x32_bf16 v[12:15], v[148:151], v[214:217], v[12:15]
	v_mfma_f32_16x16x32_bf16 v[8:11], v[156:159], v[214:217], v[8:11]
	s_setprio 0
	s_setprio 1
	v_mfma_f32_16x16x32_bf16 v[52:55], v[170:173], v[186:189], v[52:55]
	v_mfma_f32_16x16x32_bf16 v[48:51], v[178:181], v[186:189], v[48:51]
	v_mfma_f32_16x16x32_bf16 v[36:39], v[170:173], v[194:197], v[36:39]
	v_mfma_f32_16x16x32_bf16 v[32:35], v[178:181], v[194:197], v[32:35]
	v_mfma_f32_16x16x32_bf16 v[20:23], v[170:173], v[202:205], v[20:23]
	v_mfma_f32_16x16x32_bf16 v[16:19], v[178:181], v[202:205], v[16:19]
	v_mfma_f32_16x16x32_bf16 v[4:7], v[170:173], v[210:213], v[4:7]
	v_mfma_f32_16x16x32_bf16 v[0:3], v[178:181], v[210:213], v[0:3]
	v_mfma_f32_16x16x32_bf16 v[52:55], v[174:177], v[190:193], v[52:55]
	v_mfma_f32_16x16x32_bf16 v[48:51], v[182:185], v[190:193], v[48:51]
	v_mfma_f32_16x16x32_bf16 v[36:39], v[174:177], v[198:201], v[36:39]
	v_mfma_f32_16x16x32_bf16 v[32:35], v[182:185], v[198:201], v[32:35]
	v_mfma_f32_16x16x32_bf16 v[20:23], v[174:177], v[206:209], v[20:23]
	v_mfma_f32_16x16x32_bf16 v[16:19], v[182:185], v[206:209], v[16:19]
	v_mfma_f32_16x16x32_bf16 v[4:7], v[174:177], v[214:217], v[4:7]
	v_mfma_f32_16x16x32_bf16 v[0:3], v[182:185], v[214:217], v[0:3]
	s_setprio 0
	s_barrier
	s_add_i32 s92, s92, 2
	s_add_u32 s54, s54, 0x100
	s_addc_u32 s55, s55, 0
	s_add_u32 s90, s90, 0x100
	s_addc_u32 s91, s91, 0
	s_cmp_gt_u32 s92, 13
	s_cbranch_scc0 .LBB0_237
	s_and_b64 vcc, exec, s[14:15]
	s_cbranch_vccz .LBB0_240
	s_barrier

; #define PG8_STAGE(bufoff, gbase, voff) do { _Pragma("unroll") for (int _i = 0; _i < 2; ++_i) \
;         __builtin_amdgcn_global_load_lds((const unsigned*)((const char*)(gbase) + (voff)[_i]), (LAS unsigned*)(lds + (bufoff) + ldsw + _i * 8192), 16, 0, 0); } while (0)
; #define PG8_LDA(dst, b, h) do { _Pragma("unroll") for (int m = 0; m < 4; ++m) _Pragma("unroll") for (int k = 0; k < 2; ++k) dst[m][k] = *(const LAS bf16x8*)(lds + PG8_SA(b, h) + aoff + m * 2048 + k * 1024); } while (0)
; #define PG8_LDB(dst, b, h) do { _Pragma("unroll") for (int n = 0; n < 2; ++n) _Pragma("unroll") for (int k = 0; k < 2; ++k) dst[n][k] = *(const LAS bf16x8*)(lds + PG8_SB(b, h) + boff + n * 2048 + k * 1024); } while (0)
; #define PG8_MMA(ai, bj, At, Bt) do { __builtin_amdgcn_s_setprio(1); _Pragma("unroll") for (int m = 0; m < 4; ++m) _Pragma("unroll") for (int n = 0; n < 2; ++n) _Pragma("unroll") for (int k = 0; k < 2; ++k) \
;         acc[ai][bj][m][n] = __builtin_amdgcn_mfma_f32_16x16x32_bf16(Bt[n][k], At[m][k], acc[ai][bj][m][n], 0, 0, 0); __builtin_amdgcn_s_setprio(0); } while (0)
; #define PG8_WAIT_V(n) asm volatile("s_waitcnt vmcnt(" #n ")" ::: "memory")
; #define PG8_WAIT_L(n) asm volatile("s_waitcnt lgkmcnt(" #n ")" ::: "memory")
; #define PG8_BAR __builtin_amdgcn_s_barrier()
; #define PG8_SCHED __builtin_amdgcn_sched_barrier(0)
; template <class Epi, class Sched, bool ALIGN_EPI = true, bool SP2 = true>
; __device__ __forceinline__ void gemm_phase(LAS unsigned char* lds, const Gemm g, const Sched& S, const Epi& E) {
;     ...
;             const char* a1 = cA + (size_t)(t + 1) * kstep;
;             const char* a2 = last ? nA : cA + (size_t)(t + 2) * kstep; const char* b2 = last ? nB : cB + (size_t)(t + 2) * kstep;
;             const char* a3 = a2 + kstep; const char* b3 = b2 + kstep;
;             if constexpr (SP2) {
;             PG8_LDB(B0, 0, 0); PG8_LDB(B1, 0, 1); PG8_SCHED; PG8_LDA(At, 0, 0); PG8_STAGE(PG8_SA(1, 1), a1 + hstep, voffA);
;             PG8_WAIT_V(8); PG8_WAIT_L(0); PG8_BAR; PG8_MMA(0, 0, At, B0); PG8_MMA(0, 1, At, B1); PG8_BAR; PG8_SCHED;
;             PG8_LDA(At, 0, 1); PG8_STAGE(PG8_SB(0, 0), b2, voffB); PG8_STAGE(PG8_SB(0, 1), b2 + hstep, voffB); PG8_STAGE(PG8_SA(0, 0), a2, voffA);
;             PG8_WAIT_V(8); PG8_WAIT_L(0); PG8_BAR; PG8_MMA(1, 0, At, B0); PG8_MMA(1, 1, At, B1); PG8_BAR; PG8_SCHED;
.LBB0_354:
	s_add_u32 s24, s62, 0xfff80080
	s_addc_u32 s25, s63, -1
	s_add_i32 s43, 0, 0x10000
	s_cmp_eq_u32 s42, 28
	s_cselect_b32 s83, s2, s25
	s_cselect_b32 s82, s3, s24
	s_cselect_b32 s25, s7, s19
	s_cselect_b32 s24, s9, s18
	s_add_i32 s46, 0, 0x14000
	v_add_u32_e32 v150, s43, v155
	v_add_u32_e32 v158, s46, v155
	s_add_i32 m0, s16, 0xc000
	ds_read_b128 v[138:141], v150
	global_load_lds_dwordx4 v134, s[62:63]
	ds_read_b128 v[142:145], v150 offset:1024
	ds_read_b128 v[146:149], v150 offset:2048
	ds_read_b128 v[150:153], v150 offset:3072
	ds_read_b128 v[170:173], v158
	ds_read_b128 v[174:177], v158 offset:1024
	ds_read_b128 v[178:181], v158 offset:2048
	ds_read_b128 v[182:185], v158 offset:3072
	ds_read_b128 v[186:189], v157
	s_add_i32 m0, s16, 0xe000
	ds_read_b128 v[190:193], v157 offset:1024
	global_load_lds_dwordx4 v136, s[62:63]
	ds_read_b128 v[194:197], v157 offset:2048
	ds_read_b128 v[198:201], v157 offset:3072
	ds_read_b128 v[202:205], v157 offset:4096
	ds_read_b128 v[206:209], v157 offset:5120
	ds_read_b128 v[210:213], v157 offset:6144
	ds_read_b128 v[214:217], v157 offset:7168
	s_waitcnt vmcnt(8)
	s_waitcnt lgkmcnt(0)
	s_barrier
	s_setprio 1
	s_waitcnt lgkmcnt(0)
	v_mfma_f32_16x16x32_bf16 v[124:127], v[138:141], v[186:189], v[124:127]
	v_mfma_f32_16x16x32_bf16 v[120:123], v[146:149], v[186:189], v[120:123]
	v_mfma_f32_16x16x32_bf16 v[108:111], v[138:141], v[194:197], v[108:111]
	v_mfma_f32_16x16x32_bf16 v[104:107], v[146:149], v[194:197], v[104:107]
	v_mfma_f32_16x16x32_bf16 v[92:95], v[138:141], v[202:205], v[92:95]
	v_mfma_f32_16x16x32_bf16 v[88:91], v[146:149], v[202:205], v[88:91]
	v_mfma_f32_16x16x32_bf16 v[76:79], v[138:141], v[210:213], v[76:79]
	v_mfma_f32_16x16x32_bf16 v[72:75], v[146:149], v[210:213], v[72:75]
	v_mfma_f32_16x16x32_bf16 v[124:127], v[142:145], v[190:193], v[124:127]
	v_mfma_f32_16x16x32_bf16 v[120:123], v[150:153], v[190:193], v[120:123]
	v_mfma_f32_16x16x32_bf16 v[108:111], v[142:145], v[198:201], v[108:111]
	v_mfma_f32_16x16x32_bf16 v[104:107], v[150:153], v[198:201], v[104:107]
	v_mfma_f32_16x16x32_bf16 v[92:95], v[142:145], v[206:209], v[92:95]
	v_mfma_f32_16x16x32_bf16 v[88:91], v[150:153], v[206:209], v[88:91]
	v_mfma_f32_16x16x32_bf16 v[76:79], v[142:145], v[214:217], v[76:79]
	v_mfma_f32_16x16x32_bf16 v[72:75], v[150:153], v[214:217], v[72:75]
	s_setprio 0
	s_setprio 1
	v_mfma_f32_16x16x32_bf16 v[116:119], v[170:173], v[186:189], v[116:119]
	v_mfma_f32_16x16x32_bf16 v[112:115], v[178:181], v[186:189], v[112:115]
	v_mfma_f32_16x16x32_bf16 v[100:103], v[170:173], v[194:197], v[100:103]
	v_mfma_f32_16x16x32_bf16 v[96:99], v[178:181], v[194:197], v[96:99]
	v_mfma_f32_16x16x32_bf16 v[84:87], v[170:173], v[202:205], v[84:87]
	v_mfma_f32_16x16x32_bf16 v[80:83], v[178:181], v[202:205], v[80:83]
	v_mfma_f32_16x16x32_bf16 v[68:71], v[170:173], v[210:213], v[68:71]
	v_mfma_f32_16x16x32_bf16 v[64:67], v[178:181], v[210:213], v[64:67]
	v_mfma_f32_16x16x32_bf16 v[116:119], v[174:177], v[190:193], v[116:119]
	v_mfma_f32_16x16x32_bf16 v[112:115], v[182:185], v[190:193], v[112:115]
	v_mfma_f32_16x16x32_bf16 v[100:103], v[174:177], v[198:201], v[100:103]
	v_mfma_f32_16x16x32_bf16 v[96:99], v[182:185], v[198:201], v[96:99]
	v_mfma_f32_16x16x32_bf16 v[84:87], v[174:177], v[206:209], v[84:87]
	v_mfma_f32_16x16x32_bf16 v[80:83], v[182:185], v[206:209], v[80:83]
	v_mfma_f32_16x16x32_bf16 v[68:71], v[174:177], v[214:217], v[68:71]
	v_mfma_f32_16x16x32_bf16 v[64:67], v[182:185], v[214:217], v[64:67]
	s_setprio 0
	s_barrier
	s_add_i32 s43, s43, s41
	s_mov_b32 m0, s43
	ds_read_b128 v[186:189], v157 offset:16384
	global_load_lds_dwordx4 v160, s[24:25]
	ds_read_b128 v[190:193], v157 offset:17408
	ds_read_b128 v[194:197], v157 offset:18432
	s_add_i32 m0, s43, 0x2000
	s_add_u32 s44, s24, 0x80000
	s_addc_u32 s45, s25, 0
	s_add_i32 s43, s46, s41
	global_load_lds_dwordx4 v132, s[24:25]
	ds_read_b128 v[198:201], v157 offset:19456
	s_mov_b32 m0, s43
	ds_read_b128 v[202:205], v157 offset:20480
	global_load_lds_dwordx4 v160, s[44:45]
	ds_read_b128 v[206:209], v157 offset:21504
	s_add_i32 m0, s43, 0x2000
	ds_read_b128 v[210:213], v157 offset:22528
	global_load_lds_dwordx4 v132, s[44:45]
	ds_read_b128 v[214:217], v157 offset:23552
	s_mov_b32 m0, s16
	s_nop 0
	global_load_lds_dwordx4 v128, s[82:83]
	s_mov_b32 m0, s17
	s_nop 0
	global_load_lds_dwordx4 v130, s[82:83]
	s_waitcnt vmcnt(8)
	s_waitcnt lgkmcnt(0)
	s_barrier
	s_setprio 1
	s_waitcnt lgkmcnt(0)
	v_mfma_f32_16x16x32_bf16 v[60:63], v[138:141], v[186:189], v[60:63]
	v_mfma_f32_16x16x32_bf16 v[56:59], v[146:149], v[186:189], v[56:59]
	v_mfma_f32_16x16x32_bf16 v[44:47], v[138:141], v[194:197], v[44:47]
	v_mfma_f32_16x16x32_bf16 v[40:43], v[146:149], v[194:197], v[40:43]
	v_mfma_f32_16x16x32_bf16 v[28:31], v[138:141], v[202:205], v[28:31]
	v_mfma_f32_16x16x32_bf16 v[24:27], v[146:149], v[202:205], v[24:27]
	v_mfma_f32_16x16x32_bf16 v[12:15], v[138:141], v[210:213], v[12:15]
	v_mfma_f32_16x16x32_bf16 v[8:11], v[146:149], v[210:213], v[8:11]
	v_mfma_f32_16x16x32_bf16 v[60:63], v[142:145], v[190:193], v[60:63]
	v_mfma_f32_16x16x32_bf16 v[56:59], v[150:153], v[190:193], v[56:59]
	v_mfma_f32_16x16x32_bf16 v[44:47], v[142:145], v[198:201], v[44:47]
	v_mfma_f32_16x16x32_bf16 v[40:43], v[150:153], v[198:201], v[40:43]
	v_mfma_f32_16x16x32_bf16 v[28:31], v[142:145], v[206:209], v[28:31]
	v_mfma_f32_16x16x32_bf16 v[24:27], v[150:153], v[206:209], v[24:27]
	v_mfma_f32_16x16x32_bf16 v[12:15], v[142:145], v[214:217], v[12:15]
	v_mfma_f32_16x16x32_bf16 v[8:11], v[150:153], v[214:217], v[8:11]
	s_setprio 0
	s_setprio 1
	v_mfma_f32_16x16x32_bf16 v[52:55], v[170:173], v[186:189], v[52:55]
	v_mfma_f32_16x16x32_bf16 v[48:51], v[178:181], v[186:189], v[48:51]
	v_mfma_f32_16x16x32_bf16 v[36:39], v[170:173], v[194:197], v[36:39]
	v_mfma_f32_16x16x32_bf16 v[32:35], v[178:181], v[194:197], v[32:35]
	v_mfma_f32_16x16x32_bf16 v[20:23], v[170:173], v[202:205], v[20:23]
	v_mfma_f32_16x16x32_bf16 v[16:19], v[178:181], v[202:205], v[16:19]
	v_mfma_f32_16x16x32_bf16 v[4:7], v[170:173], v[210:213], v[4:7]
	v_mfma_f32_16x16x32_bf16 v[0:3], v[178:181], v[210:213], v[0:3]
	v_mfma_f32_16x16x32_bf16 v[52:55], v[174:177], v[190:193], v[52:55]
	v_mfma_f32_16x16x32_bf16 v[48:51], v[182:185], v[190:193], v[48:51]
	v_mfma_f32_16x16x32_bf16 v[36:39], v[174:177], v[198:201], v[36:39]
	v_mfma_f32_16x16x32_bf16 v[32:35], v[182:185], v[198:201], v[32:35]
	v_mfma_f32_16x16x32_bf16 v[20:23], v[174:177], v[206:209], v[20:23]
	v_mfma_f32_16x16x32_bf16 v[16:19], v[182:185], v[206:209], v[16:19]
	v_mfma_f32_16x16x32_bf16 v[4:7], v[174:177], v[214:217], v[4:7]
	v_mfma_f32_16x16x32_bf16 v[0:3], v[182:185], v[214:217], v[0:3]
	s_setprio 0
	s_barrier
; #define PG8_STAGE(bufoff, gbase, voff) do { _Pragma("unroll") for (int _i = 0; _i < 2; ++_i) \
;         __builtin_amdgcn_global_load_lds((const unsigned*)((const char*)(gbase) + (voff)[_i]), (LAS unsigned*)(lds + (bufoff) + ldsw + _i * 8192), 16, 0, 0); } while (0)
; #define PG8_LDA(dst, b, h) do { _Pragma("unroll") for (int m = 0; m < 4; ++m) _Pragma("unroll") for (int k = 0; k < 2; ++k) dst[m][k] = *(const LAS bf16x8*)(lds + PG8_SA(b, h) + aoff + m * 2048 + k * 1024); } while (0)
; #define PG8_LDB(dst, b, h) do { _Pragma("unroll") for (int n = 0; n < 2; ++n) _Pragma("unroll") for (int k = 0; k < 2; ++k) dst[n][k] = *(const LAS bf16x8*)(lds + PG8_SB(b, h) + boff + n * 2048 + k * 1024); } while (0)
; #define PG8_WAIT_V(n) asm volatile("s_waitcnt vmcnt(" #n ")" ::: "memory")
; #define PG8_WAIT_L(n) asm volatile("s_waitcnt lgkmcnt(" #n ")" ::: "memory")
; template <class Epi, class Sched, bool ALIGN_EPI = true, bool SP2 = true>
; __device__ __forceinline__ void gemm_phase(LAS unsigned char* lds, const Gemm g, const Sched& S, const Epi& E) {
;     ...
;             const char* a1 = cA + (size_t)(t + 1) * kstep;
;             const char* a2 = last ? nA : cA + (size_t)(t + 2) * kstep; const char* b2 = last ? nB : cB + (size_t)(t + 2) * kstep;
;             const char* a3 = a2 + kstep; const char* b3 = b2 + kstep;
;             if constexpr (SP2) {
;             PG8_LDB(B0, 0, 0); PG8_LDB(B1, 0, 1); PG8_SCHED; PG8_LDA(At, 0, 0); PG8_STAGE(PG8_SA(1, 1), a1 + hstep, voffA);
;             PG8_WAIT_V(8); PG8_WAIT_L(0); PG8_BAR; PG8_MMA(0, 0, At, B0); PG8_MMA(0, 1, At, B1); PG8_BAR; PG8_SCHED;
;             PG8_LDA(At, 0, 1); PG8_STAGE(PG8_SB(0, 0), b2, voffB); PG8_STAGE(PG8_SB(0, 1), b2 + hstep, voffB); PG8_STAGE(PG8_SA(0, 0), a2, voffA);
;             PG8_WAIT_V(8); PG8_WAIT_L(0); PG8_BAR; PG8_MMA(1, 0, At, B0); PG8_MMA(1, 1, At, B1); PG8_BAR; PG8_SCHED;
;             PG8_LDB(B0, 1, 0); PG8_LDB(B1, 1, 1); PG8_SCHED; PG8_LDA(At, 1, 0); PG8_STAGE(PG8_SA(0, 1), a2 + hstep, voffA);
;             PG8_WAIT_V(8); PG8_WAIT_L(0); PG8_BAR; PG8_MMA(0, 0, At, B0); PG8_MMA(0, 1, At, B1); PG8_BAR; PG8_SCHED;
;             PG8_LDA(At, 1, 1); PG8_STAGE(PG8_SB(1, 0), b3, voffB); PG8_STAGE(PG8_SB(1, 1), b3 + hstep, voffB); PG8_STAGE(PG8_SA(1, 0), a3, voffA);
;             PG8_WAIT_V(8); PG8_WAIT_L(0); PG8_BAR; PG8_MMA(1, 0, At, B0); PG8_MMA(1, 1, At, B1); PG8_BAR; PG8_SCHED;
	s_add_i32 s43, 0, 0x18000
	s_add_i32 s46, 0, 0x1c000
	v_add_u32_e32 v150, s43, v155
	v_add_u32_e32 v166, s46, v155
	s_add_u32 s44, s82, 0x80000
	s_addc_u32 s45, s83, 0
	s_mov_b32 m0, s30
	ds_read_b128 v[138:141], v150
	global_load_lds_dwordx4 v128, s[44:45]
	ds_read_b128 v[142:145], v150 offset:1024
	ds_read_b128 v[146:149], v150 offset:2048
	ds_read_b128 v[150:153], v150 offset:3072
	ds_read_b128 v[170:173], v166
	ds_read_b128 v[174:177], v166 offset:1024
	ds_read_b128 v[178:181], v166 offset:2048
	ds_read_b128 v[182:185], v166 offset:3072
	ds_read_b128 v[186:189], v157 offset:32768
	s_mov_b32 m0, s31
	ds_read_b128 v[190:193], v157 offset:33792
	global_load_lds_dwordx4 v130, s[44:45]
	ds_read_b128 v[194:197], v157 offset:34816
	ds_read_b128 v[198:201], v157 offset:35840
	ds_read_b128 v[202:205], v157 offset:36864
	ds_read_b128 v[206:209], v157 offset:37888
	ds_read_b128 v[210:213], v157 offset:38912
	ds_read_b128 v[214:217], v157 offset:39936
	s_waitcnt vmcnt(8)
	s_waitcnt lgkmcnt(0)
	s_barrier
	s_setprio 1
	s_waitcnt lgkmcnt(0)
	v_mfma_f32_16x16x32_bf16 v[124:127], v[138:141], v[186:189], v[124:127]
	v_mfma_f32_16x16x32_bf16 v[120:123], v[146:149], v[186:189], v[120:123]
	v_mfma_f32_16x16x32_bf16 v[108:111], v[138:141], v[194:197], v[108:111]
	v_mfma_f32_16x16x32_bf16 v[104:107], v[146:149], v[194:197], v[104:107]
	v_mfma_f32_16x16x32_bf16 v[92:95], v[138:141], v[202:205], v[92:95]
	v_mfma_f32_16x16x32_bf16 v[88:91], v[146:149], v[202:205], v[88:91]
	v_mfma_f32_16x16x32_bf16 v[76:79], v[138:141], v[210:213], v[76:79]
	v_mfma_f32_16x16x32_bf16 v[72:75], v[146:149], v[210:213], v[72:75]
	v_mfma_f32_16x16x32_bf16 v[124:127], v[142:145], v[190:193], v[124:127]
	v_mfma_f32_16x16x32_bf16 v[120:123], v[150:153], v[190:193], v[120:123]
	v_mfma_f32_16x16x32_bf16 v[108:111], v[142:145], v[198:201], v[108:111]
	v_mfma_f32_16x16x32_bf16 v[104:107], v[150:153], v[198:201], v[104:107]
	v_mfma_f32_16x16x32_bf16 v[92:95], v[142:145], v[206:209], v[92:95]
	v_mfma_f32_16x16x32_bf16 v[88:91], v[150:153], v[206:209], v[88:91]
	v_mfma_f32_16x16x32_bf16 v[76:79], v[142:145], v[214:217], v[76:79]
	v_mfma_f32_16x16x32_bf16 v[72:75], v[150:153], v[214:217], v[72:75]
	s_setprio 0
	s_setprio 1
	v_mfma_f32_16x16x32_bf16 v[116:119], v[170:173], v[186:189], v[116:119]
	v_mfma_f32_16x16x32_bf16 v[112:115], v[178:181], v[186:189], v[112:115]
	v_mfma_f32_16x16x32_bf16 v[100:103], v[170:173], v[194:197], v[100:103]
	v_mfma_f32_16x16x32_bf16 v[96:99], v[178:181], v[194:197], v[96:99]
	v_mfma_f32_16x16x32_bf16 v[84:87], v[170:173], v[202:205], v[84:87]
	v_mfma_f32_16x16x32_bf16 v[80:83], v[178:181], v[202:205], v[80:83]
	v_mfma_f32_16x16x32_bf16 v[68:71], v[170:173], v[210:213], v[68:71]
	v_mfma_f32_16x16x32_bf16 v[64:67], v[178:181], v[210:213], v[64:67]
	v_mfma_f32_16x16x32_bf16 v[116:119], v[174:177], v[190:193], v[116:119]
	v_mfma_f32_16x16x32_bf16 v[112:115], v[182:185], v[190:193], v[112:115]
	v_mfma_f32_16x16x32_bf16 v[100:103], v[174:177], v[198:201], v[100:103]
	v_mfma_f32_16x16x32_bf16 v[96:99], v[182:185], v[198:201], v[96:99]
	v_mfma_f32_16x16x32_bf16 v[84:87], v[174:177], v[206:209], v[84:87]
	v_mfma_f32_16x16x32_bf16 v[80:83], v[182:185], v[206:209], v[80:83]
	v_mfma_f32_16x16x32_bf16 v[68:71], v[174:177], v[214:217], v[68:71]
	v_mfma_f32_16x16x32_bf16 v[64:67], v[182:185], v[214:217], v[64:67]
	s_setprio 0
	s_barrier
	s_add_i32 s43, s43, s41
	s_mov_b32 m0, s43
	s_add_u32 s98, s24, 0x80
	s_addc_u32 s99, s25, 0
	global_load_lds_dwordx4 v160, s[98:99]
	ds_read_b128 v[186:189], v157 offset:49152
	ds_read_b128 v[190:193], v157 offset:50176
	s_add_i32 m0, s43, 0x2000
	s_add_u32 s24, s24, 0x80080
	s_addc_u32 s25, s25, 0
	s_add_i32 s43, s46, s41
	global_load_lds_dwordx4 v132, s[98:99]
	ds_read_b128 v[194:197], v157 offset:51200
	ds_read_b128 v[198:201], v157 offset:52224
	s_mov_b32 m0, s43
	ds_read_b128 v[202:205], v157 offset:53248
	global_load_lds_dwordx4 v160, s[24:25]
	ds_read_b128 v[206:209], v157 offset:54272
	s_add_i32 m0, s43, 0x2000
	ds_read_b128 v[210:213], v157 offset:55296
	global_load_lds_dwordx4 v132, s[24:25]
	ds_read_b128 v[214:217], v157 offset:56320
	s_mov_b32 m0, s60
	s_add_u32 s98, s82, 0x80
	s_addc_u32 s99, s83, 0
	global_load_lds_dwordx4 v128, s[98:99]
	s_mov_b32 m0, s61
	s_nop 0
	global_load_lds_dwordx4 v130, s[98:99]
	s_waitcnt vmcnt(8)
	s_waitcnt lgkmcnt(0)
	s_barrier
	s_setprio 1
	s_waitcnt lgkmcnt(0)
	v_mfma_f32_16x16x32_bf16 v[60:63], v[138:141], v[186:189], v[60:63]
	v_mfma_f32_16x16x32_bf16 v[56:59], v[146:149], v[186:189], v[56:59]
	v_mfma_f32_16x16x32_bf16 v[44:47], v[138:141], v[194:197], v[44:47]
	v_mfma_f32_16x16x32_bf16 v[40:43], v[146:149], v[194:197], v[40:43]
	v_mfma_f32_16x16x32_bf16 v[28:31], v[138:141], v[202:205], v[28:31]
	v_mfma_f32_16x16x32_bf16 v[24:27], v[146:149], v[202:205], v[24:27]
	v_mfma_f32_16x16x32_bf16 v[12:15], v[138:141], v[210:213], v[12:15]
	v_mfma_f32_16x16x32_bf16 v[8:11], v[146:149], v[210:213], v[8:11]
	v_mfma_f32_16x16x32_bf16 v[60:63], v[142:145], v[190:193], v[60:63]
	v_mfma_f32_16x16x32_bf16 v[56:59], v[150:153], v[190:193], v[56:59]
	v_mfma_f32_16x16x32_bf16 v[44:47], v[142:145], v[198:201], v[44:47]
	v_mfma_f32_16x16x32_bf16 v[40:43], v[150:153], v[198:201], v[40:43]
	v_mfma_f32_16x16x32_bf16 v[28:31], v[142:145], v[206:209], v[28:31]
	v_mfma_f32_16x16x32_bf16 v[24:27], v[150:153], v[206:209], v[24:27]
	v_mfma_f32_16x16x32_bf16 v[12:15], v[142:145], v[214:217], v[12:15]
	v_mfma_f32_16x16x32_bf16 v[8:11], v[150:153], v[214:217], v[8:11]
	s_setprio 0
	s_setprio 1
	v_mfma_f32_16x16x32_bf16 v[52:55], v[170:173], v[186:189], v[52:55]
	v_mfma_f32_16x16x32_bf16 v[48:51], v[178:181], v[186:189], v[48:51]
	v_mfma_f32_16x16x32_bf16 v[36:39], v[170:173], v[194:197], v[36:39]
	v_mfma_f32_16x16x32_bf16 v[32:35], v[178:181], v[194:197], v[32:35]
	v_mfma_f32_16x16x32_bf16 v[20:23], v[170:173], v[202:205], v[20:23]
	v_mfma_f32_16x16x32_bf16 v[16:19], v[178:181], v[202:205], v[16:19]
	v_mfma_f32_16x16x32_bf16 v[4:7], v[170:173], v[210:213], v[4:7]
	v_mfma_f32_16x16x32_bf16 v[0:3], v[178:181], v[210:213], v[0:3]
	v_mfma_f32_16x16x32_bf16 v[52:55], v[174:177], v[190:193], v[52:55]
	v_mfma_f32_16x16x32_bf16 v[48:51], v[182:185], v[190:193], v[48:51]
	v_mfma_f32_16x16x32_bf16 v[36:39], v[174:177], v[198:201], v[36:39]
	v_mfma_f32_16x16x32_bf16 v[32:35], v[182:185], v[198:201], v[32:35]
	v_mfma_f32_16x16x32_bf16 v[20:23], v[174:177], v[206:209], v[20:23]
	v_mfma_f32_16x16x32_bf16 v[16:19], v[182:185], v[206:209], v[16:19]
	v_mfma_f32_16x16x32_bf16 v[4:7], v[174:177], v[214:217], v[4:7]
	v_mfma_f32_16x16x32_bf16 v[0:3], v[182:185], v[214:217], v[0:3]
	s_setprio 0
	s_barrier
	s_add_i32 s42, s42, 2
	s_add_u32 s62, s62, 0x100
	s_addc_u32 s63, s63, 0
	s_add_u32 s18, s18, 0x100
	s_addc_u32 s19, s19, 0
	s_cmp_gt_u32 s42, 29
	s_cbranch_scc0 .LBB0_354
	s_and_b64 vcc, exec, s[14:15]
	s_cbranch_vccz .LBB0_357
	s_barrier

; #define PG8_STAGE(bufoff, gbase, voff) do { _Pragma("unroll") for (int _i = 0; _i < 2; ++_i) \
;         __builtin_amdgcn_global_load_lds((const unsigned*)((const char*)(gbase) + (voff)[_i]), (LAS unsigned*)(lds + (bufoff) + ldsw + _i * 8192), 16, 0, 0); } while (0)
; #define PG8_LDA(dst, b, h) do { _Pragma("unroll") for (int m = 0; m < 4; ++m) _Pragma("unroll") for (int k = 0; k < 2; ++k) dst[m][k] = *(const LAS bf16x8*)(lds + PG8_SA(b, h) + aoff + m * 2048 + k * 1024); } while (0)
; #define PG8_LDB(dst, b, h) do { _Pragma("unroll") for (int n = 0; n < 2; ++n) _Pragma("unroll") for (int k = 0; k < 2; ++k) dst[n][k] = *(const LAS bf16x8*)(lds + PG8_SB(b, h) + boff + n * 2048 + k * 1024); } while (0)
; #define PG8_MMA(ai, bj, At, Bt) do { __builtin_amdgcn_s_setprio(1); _Pragma("unroll") for (int m = 0; m < 4; ++m) _Pragma("unroll") for (int n = 0; n < 2; ++n) _Pragma("unroll") for (int k = 0; k < 2; ++k) \
;         acc[ai][bj][m][n] = __builtin_amdgcn_mfma_f32_16x16x32_bf16(Bt[n][k], At[m][k], acc[ai][bj][m][n], 0, 0, 0); __builtin_amdgcn_s_setprio(0); } while (0)
; #define PG8_WAIT_V(n) asm volatile("s_waitcnt vmcnt(" #n ")" ::: "memory")
; #define PG8_WAIT_L(n) asm volatile("s_waitcnt lgkmcnt(" #n ")" ::: "memory")
; #define PG8_BAR __builtin_amdgcn_s_barrier()
; #define PG8_SCHED __builtin_amdgcn_sched_barrier(0)
; template <class Epi, class Sched, bool ALIGN_EPI = true, bool SP2 = true>
; __device__ __forceinline__ void gemm_phase(LAS unsigned char* lds, const Gemm g, const Sched& S, const Epi& E) {
;     ...
;             const char* a1 = cA + (size_t)(t + 1) * kstep;
;             const char* a2 = last ? nA : cA + (size_t)(t + 2) * kstep; const char* b2 = last ? nB : cB + (size_t)(t + 2) * kstep;
;             const char* a3 = a2 + kstep; const char* b3 = b2 + kstep;
;             if constexpr (SP2) {
;             PG8_LDB(B0, 0, 0); PG8_LDB(B1, 0, 1); PG8_SCHED; PG8_LDA(At, 0, 0); PG8_STAGE(PG8_SA(1, 1), a1 + hstep, voffA);
;             PG8_WAIT_V(8); PG8_WAIT_L(0); PG8_BAR; PG8_MMA(0, 0, At, B0); PG8_MMA(0, 1, At, B1); PG8_BAR; PG8_SCHED;
;             PG8_LDA(At, 0, 1); PG8_STAGE(PG8_SB(0, 0), b2, voffB); PG8_STAGE(PG8_SB(0, 1), b2 + hstep, voffB); PG8_STAGE(PG8_SA(0, 0), a2, voffA);
;             PG8_WAIT_V(8); PG8_WAIT_L(0); PG8_BAR; PG8_MMA(1, 0, At, B0); PG8_MMA(1, 1, At, B1); PG8_BAR; PG8_SCHED;
.LBB0_566:
	s_add_u32 s54, s52, 0x100
	s_addc_u32 s55, s53, 0
	s_add_i32 s46, 0, 0x10000
	s_cmpk_eq_i32 s89, 0x54
	s_cselect_b32 s61, s9, s55
	s_cselect_b32 s60, s8, s54
	v_add_u32_e32 v142, s46, v145
	s_cselect_b32 s25, s31, s3
	s_cselect_b32 s24, s30, s2
	s_add_i32 s47, 0, 0x14000
	ds_read_b128 v[138:141], v142
	ds_read_b128 v[148:151], v142 offset:1024
	ds_read_b128 v[152:155], v142 offset:2048
	ds_read_b128 v[156:159], v142 offset:3072
	v_add_u32_e32 v142, s47, v145
	s_add_i32 m0, s63, 0xc000
	ds_read_b128 v[170:173], v142
	global_load_lds_dwordx4 v134, s[52:53]
	ds_read_b128 v[174:177], v142 offset:1024
	ds_read_b128 v[178:181], v142 offset:2048
	ds_read_b128 v[182:185], v142 offset:3072
	ds_read_b128 v[186:189], v147
	ds_read_b128 v[190:193], v147 offset:1024
	ds_read_b128 v[194:197], v147 offset:2048
	s_add_i32 m0, s63, 0xe000
	ds_read_b128 v[198:201], v147 offset:3072
	global_load_lds_dwordx4 v136, s[52:53]
	ds_read_b128 v[202:205], v147 offset:4096
	ds_read_b128 v[206:209], v147 offset:5120
	ds_read_b128 v[210:213], v147 offset:6144
	ds_read_b128 v[214:217], v147 offset:7168
	s_waitcnt vmcnt(8)
	s_waitcnt lgkmcnt(0)
	s_barrier
	s_setprio 1
	s_waitcnt lgkmcnt(0)
	v_mfma_f32_16x16x32_bf16 v[124:127], v[138:141], v[186:189], v[124:127]
	v_mfma_f32_16x16x32_bf16 v[120:123], v[152:155], v[186:189], v[120:123]
	v_mfma_f32_16x16x32_bf16 v[108:111], v[138:141], v[194:197], v[108:111]
	v_mfma_f32_16x16x32_bf16 v[104:107], v[152:155], v[194:197], v[104:107]
	v_mfma_f32_16x16x32_bf16 v[92:95], v[138:141], v[202:205], v[92:95]
	v_mfma_f32_16x16x32_bf16 v[88:91], v[152:155], v[202:205], v[88:91]
	v_mfma_f32_16x16x32_bf16 v[76:79], v[138:141], v[210:213], v[76:79]
	v_mfma_f32_16x16x32_bf16 v[72:75], v[152:155], v[210:213], v[72:75]
	v_mfma_f32_16x16x32_bf16 v[124:127], v[148:151], v[190:193], v[124:127]
	v_mfma_f32_16x16x32_bf16 v[120:123], v[156:159], v[190:193], v[120:123]
	v_mfma_f32_16x16x32_bf16 v[108:111], v[148:151], v[198:201], v[108:111]
	v_mfma_f32_16x16x32_bf16 v[104:107], v[156:159], v[198:201], v[104:107]
	v_mfma_f32_16x16x32_bf16 v[92:95], v[148:151], v[206:209], v[92:95]
	v_mfma_f32_16x16x32_bf16 v[88:91], v[156:159], v[206:209], v[88:91]
	v_mfma_f32_16x16x32_bf16 v[76:79], v[148:151], v[214:217], v[76:79]
	v_mfma_f32_16x16x32_bf16 v[72:75], v[156:159], v[214:217], v[72:75]
	s_setprio 0
	s_setprio 1
	v_mfma_f32_16x16x32_bf16 v[116:119], v[170:173], v[186:189], v[116:119]
	v_mfma_f32_16x16x32_bf16 v[112:115], v[178:181], v[186:189], v[112:115]
	v_mfma_f32_16x16x32_bf16 v[100:103], v[170:173], v[194:197], v[100:103]
	v_mfma_f32_16x16x32_bf16 v[96:99], v[178:181], v[194:197], v[96:99]
	v_mfma_f32_16x16x32_bf16 v[84:87], v[170:173], v[202:205], v[84:87]
	v_mfma_f32_16x16x32_bf16 v[80:83], v[178:181], v[202:205], v[80:83]
	v_mfma_f32_16x16x32_bf16 v[68:71], v[170:173], v[210:213], v[68:71]
	v_mfma_f32_16x16x32_bf16 v[64:67], v[178:181], v[210:213], v[64:67]
	v_mfma_f32_16x16x32_bf16 v[116:119], v[174:177], v[190:193], v[116:119]
	v_mfma_f32_16x16x32_bf16 v[112:115], v[182:185], v[190:193], v[112:115]
	v_mfma_f32_16x16x32_bf16 v[100:103], v[174:177], v[198:201], v[100:103]
	v_mfma_f32_16x16x32_bf16 v[96:99], v[182:185], v[198:201], v[96:99]
	v_mfma_f32_16x16x32_bf16 v[84:87], v[174:177], v[206:209], v[84:87]
	v_mfma_f32_16x16x32_bf16 v[80:83], v[182:185], v[206:209], v[80:83]
	v_mfma_f32_16x16x32_bf16 v[68:71], v[174:177], v[214:217], v[68:71]
	v_mfma_f32_16x16x32_bf16 v[64:67], v[182:185], v[214:217], v[64:67]
	s_setprio 0
	s_barrier
	s_add_i32 s46, s46, s62
	s_mov_b32 m0, s46
	ds_read_b128 v[186:189], v147 offset:16384
	global_load_lds_dwordx4 v160, s[24:25]
	ds_read_b128 v[190:193], v147 offset:17408
	ds_read_b128 v[194:197], v147 offset:18432
	s_add_i32 m0, s46, 0x2000
	s_add_u32 s52, s24, 0x160000
	s_addc_u32 s53, s25, 0
	s_add_i32 s46, s47, s62
	global_load_lds_dwordx4 v132, s[24:25]
	ds_read_b128 v[198:201], v147 offset:19456
	s_mov_b32 m0, s46
	ds_read_b128 v[202:205], v147 offset:20480
	global_load_lds_dwordx4 v160, s[52:53]
	ds_read_b128 v[206:209], v147 offset:21504
	s_add_i32 m0, s46, 0x2000
	ds_read_b128 v[210:213], v147 offset:22528
	global_load_lds_dwordx4 v132, s[52:53]
	ds_read_b128 v[214:217], v147 offset:23552
	s_mov_b32 m0, s63
	s_nop 0
	global_load_lds_dwordx4 v128, s[60:61]
	s_mov_b32 m0, s66
	s_nop 0
	global_load_lds_dwordx4 v130, s[60:61]
	s_waitcnt vmcnt(8)
	s_waitcnt lgkmcnt(0)
	s_barrier
	s_setprio 1
	s_waitcnt lgkmcnt(0)
	v_mfma_f32_16x16x32_bf16 v[60:63], v[138:141], v[186:189], v[60:63]
	v_mfma_f32_16x16x32_bf16 v[56:59], v[152:155], v[186:189], v[56:59]
	v_mfma_f32_16x16x32_bf16 v[44:47], v[138:141], v[194:197], v[44:47]
	v_mfma_f32_16x16x32_bf16 v[40:43], v[152:155], v[194:197], v[40:43]
	v_mfma_f32_16x16x32_bf16 v[28:31], v[138:141], v[202:205], v[28:31]
	v_mfma_f32_16x16x32_bf16 v[24:27], v[152:155], v[202:205], v[24:27]
	v_mfma_f32_16x16x32_bf16 v[12:15], v[138:141], v[210:213], v[12:15]
	v_mfma_f32_16x16x32_bf16 v[8:11], v[152:155], v[210:213], v[8:11]
	v_mfma_f32_16x16x32_bf16 v[60:63], v[148:151], v[190:193], v[60:63]
	v_mfma_f32_16x16x32_bf16 v[56:59], v[156:159], v[190:193], v[56:59]
	v_mfma_f32_16x16x32_bf16 v[44:47], v[148:151], v[198:201], v[44:47]
	v_mfma_f32_16x16x32_bf16 v[40:43], v[156:159], v[198:201], v[40:43]
	v_mfma_f32_16x16x32_bf16 v[28:31], v[148:151], v[206:209], v[28:31]
	v_mfma_f32_16x16x32_bf16 v[24:27], v[156:159], v[206:209], v[24:27]
	v_mfma_f32_16x16x32_bf16 v[12:15], v[148:151], v[214:217], v[12:15]
	v_mfma_f32_16x16x32_bf16 v[8:11], v[156:159], v[214:217], v[8:11]
	s_setprio 0
	s_setprio 1
	v_mfma_f32_16x16x32_bf16 v[52:55], v[170:173], v[186:189], v[52:55]
	v_mfma_f32_16x16x32_bf16 v[48:51], v[178:181], v[186:189], v[48:51]
	v_mfma_f32_16x16x32_bf16 v[36:39], v[170:173], v[194:197], v[36:39]
	v_mfma_f32_16x16x32_bf16 v[32:35], v[178:181], v[194:197], v[32:35]
	v_mfma_f32_16x16x32_bf16 v[20:23], v[170:173], v[202:205], v[20:23]
	v_mfma_f32_16x16x32_bf16 v[16:19], v[178:181], v[202:205], v[16:19]
	v_mfma_f32_16x16x32_bf16 v[4:7], v[170:173], v[210:213], v[4:7]
	v_mfma_f32_16x16x32_bf16 v[0:3], v[178:181], v[210:213], v[0:3]
	v_mfma_f32_16x16x32_bf16 v[52:55], v[174:177], v[190:193], v[52:55]
	v_mfma_f32_16x16x32_bf16 v[48:51], v[182:185], v[190:193], v[48:51]
	v_mfma_f32_16x16x32_bf16 v[36:39], v[174:177], v[198:201], v[36:39]
	v_mfma_f32_16x16x32_bf16 v[32:35], v[182:185], v[198:201], v[32:35]
	v_mfma_f32_16x16x32_bf16 v[20:23], v[174:177], v[206:209], v[20:23]
	v_mfma_f32_16x16x32_bf16 v[16:19], v[182:185], v[206:209], v[16:19]
	v_mfma_f32_16x16x32_bf16 v[4:7], v[174:177], v[214:217], v[4:7]
	v_mfma_f32_16x16x32_bf16 v[0:3], v[182:185], v[214:217], v[0:3]
	s_setprio 0
	s_barrier
; #define PG8_STAGE(bufoff, gbase, voff) do { _Pragma("unroll") for (int _i = 0; _i < 2; ++_i) \
;         __builtin_amdgcn_global_load_lds((const unsigned*)((const char*)(gbase) + (voff)[_i]), (LAS unsigned*)(lds + (bufoff) + ldsw + _i * 8192), 16, 0, 0); } while (0)
; #define PG8_LDA(dst, b, h) do { _Pragma("unroll") for (int m = 0; m < 4; ++m) _Pragma("unroll") for (int k = 0; k < 2; ++k) dst[m][k] = *(const LAS bf16x8*)(lds + PG8_SA(b, h) + aoff + m * 2048 + k * 1024); } while (0)
; #define PG8_LDB(dst, b, h) do { _Pragma("unroll") for (int n = 0; n < 2; ++n) _Pragma("unroll") for (int k = 0; k < 2; ++k) dst[n][k] = *(const LAS bf16x8*)(lds + PG8_SB(b, h) + boff + n * 2048 + k * 1024); } while (0)
; #define PG8_WAIT_V(n) asm volatile("s_waitcnt vmcnt(" #n ")" ::: "memory")
; #define PG8_WAIT_L(n) asm volatile("s_waitcnt lgkmcnt(" #n ")" ::: "memory")
; template <class Epi, class Sched, bool ALIGN_EPI = true, bool SP2 = true>
; __device__ __forceinline__ void gemm_phase(LAS unsigned char* lds, const Gemm g, const Sched& S, const Epi& E) {
;     ...
;             const char* a1 = cA + (size_t)(t + 1) * kstep;
;             const char* a2 = last ? nA : cA + (size_t)(t + 2) * kstep; const char* b2 = last ? nB : cB + (size_t)(t + 2) * kstep;
;             const char* a3 = a2 + kstep; const char* b3 = b2 + kstep;
;             if constexpr (SP2) {
;             PG8_LDB(B0, 0, 0); PG8_LDB(B1, 0, 1); PG8_SCHED; PG8_LDA(At, 0, 0); PG8_STAGE(PG8_SA(1, 1), a1 + hstep, voffA);
;             PG8_WAIT_V(8); PG8_WAIT_L(0); PG8_BAR; PG8_MMA(0, 0, At, B0); PG8_MMA(0, 1, At, B1); PG8_BAR; PG8_SCHED;
;             PG8_LDA(At, 0, 1); PG8_STAGE(PG8_SB(0, 0), b2, voffB); PG8_STAGE(PG8_SB(0, 1), b2 + hstep, voffB); PG8_STAGE(PG8_SA(0, 0), a2, voffA);
;             PG8_WAIT_V(8); PG8_WAIT_L(0); PG8_BAR; PG8_MMA(1, 0, At, B0); PG8_MMA(1, 1, At, B1); PG8_BAR; PG8_SCHED;
;             PG8_LDB(B0, 1, 0); PG8_LDB(B1, 1, 1); PG8_SCHED; PG8_LDA(At, 1, 0); PG8_STAGE(PG8_SA(0, 1), a2 + hstep, voffA);
;             PG8_WAIT_V(8); PG8_WAIT_L(0); PG8_BAR; PG8_MMA(0, 0, At, B0); PG8_MMA(0, 1, At, B1); PG8_BAR; PG8_SCHED;
;             PG8_LDA(At, 1, 1); PG8_STAGE(PG8_SB(1, 0), b3, voffB); PG8_STAGE(PG8_SB(1, 1), b3 + hstep, voffB); PG8_STAGE(PG8_SA(1, 0), a3, voffA);
;             PG8_WAIT_V(8); PG8_WAIT_L(0); PG8_BAR; PG8_MMA(1, 0, At, B0); PG8_MMA(1, 1, At, B1); PG8_BAR; PG8_SCHED;
	s_add_i32 s46, 0, 0x18000
	s_add_i32 s47, 0, 0x1c000
	v_add_u32_e32 v156, s46, v145
	v_add_u32_e32 v166, s47, v145
	s_add_u32 s52, s60, 0x160000
	s_addc_u32 s53, s61, 0
	s_mov_b32 m0, s67
	ds_read_b128 v[138:141], v156
	global_load_lds_dwordx4 v128, s[52:53]
	ds_read_b128 v[148:151], v156 offset:1024
	ds_read_b128 v[152:155], v156 offset:2048
	ds_read_b128 v[156:159], v156 offset:3072
	ds_read_b128 v[170:173], v166
	ds_read_b128 v[174:177], v166 offset:1024
	ds_read_b128 v[178:181], v166 offset:2048
	ds_read_b128 v[182:185], v166 offset:3072
	ds_read_b128 v[186:189], v147 offset:32768
	s_mov_b32 m0, s72
	ds_read_b128 v[190:193], v147 offset:33792
	global_load_lds_dwordx4 v130, s[52:53]
	ds_read_b128 v[194:197], v147 offset:34816
	ds_read_b128 v[198:201], v147 offset:35840
	ds_read_b128 v[202:205], v147 offset:36864
	ds_read_b128 v[206:209], v147 offset:37888
	ds_read_b128 v[210:213], v147 offset:38912
	ds_read_b128 v[214:217], v147 offset:39936
	s_waitcnt vmcnt(8)
	s_waitcnt lgkmcnt(0)
	s_barrier
	s_setprio 1
	s_waitcnt lgkmcnt(0)
	v_mfma_f32_16x16x32_bf16 v[124:127], v[138:141], v[186:189], v[124:127]
	v_mfma_f32_16x16x32_bf16 v[120:123], v[152:155], v[186:189], v[120:123]
	v_mfma_f32_16x16x32_bf16 v[108:111], v[138:141], v[194:197], v[108:111]
	v_mfma_f32_16x16x32_bf16 v[104:107], v[152:155], v[194:197], v[104:107]
	v_mfma_f32_16x16x32_bf16 v[92:95], v[138:141], v[202:205], v[92:95]
	v_mfma_f32_16x16x32_bf16 v[88:91], v[152:155], v[202:205], v[88:91]
	v_mfma_f32_16x16x32_bf16 v[76:79], v[138:141], v[210:213], v[76:79]
	v_mfma_f32_16x16x32_bf16 v[72:75], v[152:155], v[210:213], v[72:75]
	v_mfma_f32_16x16x32_bf16 v[124:127], v[148:151], v[190:193], v[124:127]
	v_mfma_f32_16x16x32_bf16 v[120:123], v[156:159], v[190:193], v[120:123]
	v_mfma_f32_16x16x32_bf16 v[108:111], v[148:151], v[198:201], v[108:111]
	v_mfma_f32_16x16x32_bf16 v[104:107], v[156:159], v[198:201], v[104:107]
	v_mfma_f32_16x16x32_bf16 v[92:95], v[148:151], v[206:209], v[92:95]
	v_mfma_f32_16x16x32_bf16 v[88:91], v[156:159], v[206:209], v[88:91]
	v_mfma_f32_16x16x32_bf16 v[76:79], v[148:151], v[214:217], v[76:79]
	v_mfma_f32_16x16x32_bf16 v[72:75], v[156:159], v[214:217], v[72:75]
	s_setprio 0
	s_setprio 1
	v_mfma_f32_16x16x32_bf16 v[116:119], v[170:173], v[186:189], v[116:119]
	v_mfma_f32_16x16x32_bf16 v[112:115], v[178:181], v[186:189], v[112:115]
	v_mfma_f32_16x16x32_bf16 v[100:103], v[170:173], v[194:197], v[100:103]
	v_mfma_f32_16x16x32_bf16 v[96:99], v[178:181], v[194:197], v[96:99]
	v_mfma_f32_16x16x32_bf16 v[84:87], v[170:173], v[202:205], v[84:87]
	v_mfma_f32_16x16x32_bf16 v[80:83], v[178:181], v[202:205], v[80:83]
	v_mfma_f32_16x16x32_bf16 v[68:71], v[170:173], v[210:213], v[68:71]
	v_mfma_f32_16x16x32_bf16 v[64:67], v[178:181], v[210:213], v[64:67]
	v_mfma_f32_16x16x32_bf16 v[116:119], v[174:177], v[190:193], v[116:119]
	v_mfma_f32_16x16x32_bf16 v[112:115], v[182:185], v[190:193], v[112:115]
	v_mfma_f32_16x16x32_bf16 v[100:103], v[174:177], v[198:201], v[100:103]
	v_mfma_f32_16x16x32_bf16 v[96:99], v[182:185], v[198:201], v[96:99]
	v_mfma_f32_16x16x32_bf16 v[84:87], v[174:177], v[206:209], v[84:87]
	v_mfma_f32_16x16x32_bf16 v[80:83], v[182:185], v[206:209], v[80:83]
	v_mfma_f32_16x16x32_bf16 v[68:71], v[174:177], v[214:217], v[68:71]
	v_mfma_f32_16x16x32_bf16 v[64:67], v[182:185], v[214:217], v[64:67]
	s_setprio 0
	s_barrier
	s_add_i32 s46, s46, s62
	s_mov_b32 m0, s46
	s_add_u32 s98, s24, 0x80
	s_addc_u32 s99, s25, 0
	global_load_lds_dwordx4 v160, s[98:99]
	ds_read_b128 v[186:189], v147 offset:49152
	ds_read_b128 v[190:193], v147 offset:50176
	s_add_i32 m0, s46, 0x2000
	s_add_u32 s24, s24, 0x160080
	s_addc_u32 s25, s25, 0
	s_add_i32 s46, s47, s62
	global_load_lds_dwordx4 v132, s[98:99]
	ds_read_b128 v[194:197], v147 offset:51200
	ds_read_b128 v[198:201], v147 offset:52224
	s_mov_b32 m0, s46
	ds_read_b128 v[202:205], v147 offset:53248
	global_load_lds_dwordx4 v160, s[24:25]
	ds_read_b128 v[206:209], v147 offset:54272
	s_add_i32 m0, s46, 0x2000
	ds_read_b128 v[210:213], v147 offset:55296
	global_load_lds_dwordx4 v132, s[24:25]
	ds_read_b128 v[214:217], v147 offset:56320
	s_mov_b32 m0, s73
	s_add_u32 s98, s52, 0xffea0080
	s_addc_u32 s99, s53, -1
	global_load_lds_dwordx4 v128, s[98:99]
	s_mov_b32 m0, s79
	s_nop 0
	global_load_lds_dwordx4 v130, s[98:99]
	s_waitcnt vmcnt(8)
	s_waitcnt lgkmcnt(0)
	s_barrier
	s_setprio 1
	s_waitcnt lgkmcnt(0)
	v_mfma_f32_16x16x32_bf16 v[60:63], v[138:141], v[186:189], v[60:63]
	v_mfma_f32_16x16x32_bf16 v[56:59], v[152:155], v[186:189], v[56:59]
	v_mfma_f32_16x16x32_bf16 v[44:47], v[138:141], v[194:197], v[44:47]
	v_mfma_f32_16x16x32_bf16 v[40:43], v[152:155], v[194:197], v[40:43]
	v_mfma_f32_16x16x32_bf16 v[28:31], v[138:141], v[202:205], v[28:31]
	v_mfma_f32_16x16x32_bf16 v[24:27], v[152:155], v[202:205], v[24:27]
	v_mfma_f32_16x16x32_bf16 v[12:15], v[138:141], v[210:213], v[12:15]
	v_mfma_f32_16x16x32_bf16 v[8:11], v[152:155], v[210:213], v[8:11]
	v_mfma_f32_16x16x32_bf16 v[60:63], v[148:151], v[190:193], v[60:63]
	v_mfma_f32_16x16x32_bf16 v[56:59], v[156:159], v[190:193], v[56:59]
	v_mfma_f32_16x16x32_bf16 v[44:47], v[148:151], v[198:201], v[44:47]
	v_mfma_f32_16x16x32_bf16 v[40:43], v[156:159], v[198:201], v[40:43]
	v_mfma_f32_16x16x32_bf16 v[28:31], v[148:151], v[206:209], v[28:31]
	v_mfma_f32_16x16x32_bf16 v[24:27], v[156:159], v[206:209], v[24:27]
	v_mfma_f32_16x16x32_bf16 v[12:15], v[148:151], v[214:217], v[12:15]
	v_mfma_f32_16x16x32_bf16 v[8:11], v[156:159], v[214:217], v[8:11]
	s_setprio 0
	s_setprio 1
	v_mfma_f32_16x16x32_bf16 v[52:55], v[170:173], v[186:189], v[52:55]
	v_mfma_f32_16x16x32_bf16 v[48:51], v[178:181], v[186:189], v[48:51]
	v_mfma_f32_16x16x32_bf16 v[36:39], v[170:173], v[194:197], v[36:39]
	v_mfma_f32_16x16x32_bf16 v[32:35], v[178:181], v[194:197], v[32:35]
	v_mfma_f32_16x16x32_bf16 v[20:23], v[170:173], v[202:205], v[20:23]
	v_mfma_f32_16x16x32_bf16 v[16:19], v[178:181], v[202:205], v[16:19]
	v_mfma_f32_16x16x32_bf16 v[4:7], v[170:173], v[210:213], v[4:7]
	v_mfma_f32_16x16x32_bf16 v[0:3], v[178:181], v[210:213], v[0:3]
	v_mfma_f32_16x16x32_bf16 v[52:55], v[174:177], v[190:193], v[52:55]
	v_mfma_f32_16x16x32_bf16 v[48:51], v[182:185], v[190:193], v[48:51]
	v_mfma_f32_16x16x32_bf16 v[36:39], v[174:177], v[198:201], v[36:39]
	v_mfma_f32_16x16x32_bf16 v[32:35], v[182:185], v[198:201], v[32:35]
	v_mfma_f32_16x16x32_bf16 v[20:23], v[174:177], v[206:209], v[20:23]
	v_mfma_f32_16x16x32_bf16 v[16:19], v[182:185], v[206:209], v[16:19]
	v_mfma_f32_16x16x32_bf16 v[4:7], v[174:177], v[214:217], v[4:7]
	v_mfma_f32_16x16x32_bf16 v[0:3], v[182:185], v[214:217], v[0:3]
	s_setprio 0
	s_barrier
	s_add_i32 s89, s89, 2
	s_add_u32 s2, s2, 0x100
	s_addc_u32 s3, s3, 0
	s_cmpk_gt_u32 s89, 0x55
	s_mov_b64 s[52:53], s[54:55]
	s_cbranch_scc0 .LBB0_566
	s_and_b64 vcc, exec, s[18:19]
	s_cbranch_vccz .LBB0_569
	s_barrier

; #define PG8_STAGE(bufoff, gbase, voff) do { _Pragma("unroll") for (int _i = 0; _i < 2; ++_i) \
;         __builtin_amdgcn_global_load_lds((const unsigned*)((const char*)(gbase) + (voff)[_i]), (LAS unsigned*)(lds + (bufoff) + ldsw + _i * 8192), 16, 0, 0); } while (0)
; #define PG8_LDA(dst, b, h) do { _Pragma("unroll") for (int m = 0; m < 4; ++m) _Pragma("unroll") for (int k = 0; k < 2; ++k) dst[m][k] = *(const LAS bf16x8*)(lds + PG8_SA(b, h) + aoff + m * 2048 + k * 1024); } while (0)
; #define PG8_LDB(dst, b, h) do { _Pragma("unroll") for (int n = 0; n < 2; ++n) _Pragma("unroll") for (int k = 0; k < 2; ++k) dst[n][k] = *(const LAS bf16x8*)(lds + PG8_SB(b, h) + boff + n * 2048 + k * 1024); } while (0)
; #define PG8_MMA(ai, bj, At, Bt) do { __builtin_amdgcn_s_setprio(1); _Pragma("unroll") for (int m = 0; m < 4; ++m) _Pragma("unroll") for (int n = 0; n < 2; ++n) _Pragma("unroll") for (int k = 0; k < 2; ++k) \
;         acc[ai][bj][m][n] = __builtin_amdgcn_mfma_f32_16x16x32_bf16(Bt[n][k], At[m][k], acc[ai][bj][m][n], 0, 0, 0); __builtin_amdgcn_s_setprio(0); } while (0)
; #define PG8_WAIT_V(n) asm volatile("s_waitcnt vmcnt(" #n ")" ::: "memory")
; #define PG8_WAIT_L(n) asm volatile("s_waitcnt lgkmcnt(" #n ")" ::: "memory")
; #define PG8_BAR __builtin_amdgcn_s_barrier()
; #define PG8_SCHED __builtin_amdgcn_sched_barrier(0)
; template <class Epi, class Sched, bool ALIGN_EPI = true, bool SP2 = true>
; __device__ __forceinline__ void gemm_phase(LAS unsigned char* lds, const Gemm g, const Sched& S, const Epi& E) {
;     ...
;             const char* a1 = cA + (size_t)(t + 1) * kstep;
;             const char* a2 = last ? nA : cA + (size_t)(t + 2) * kstep; const char* b2 = last ? nB : cB + (size_t)(t + 2) * kstep;
;             const char* a3 = a2 + kstep; const char* b3 = b2 + kstep;
;             if constexpr (SP2) {
;             PG8_LDB(B0, 0, 0); PG8_LDB(B1, 0, 1); PG8_SCHED; PG8_LDA(At, 0, 0); PG8_STAGE(PG8_SA(1, 1), a1 + hstep, voffA);
;             PG8_WAIT_V(8); PG8_WAIT_L(0); PG8_BAR; PG8_MMA(0, 0, At, B0); PG8_MMA(0, 1, At, B1); PG8_BAR; PG8_SCHED;
;             PG8_LDA(At, 0, 1); PG8_STAGE(PG8_SB(0, 0), b2, voffB); PG8_STAGE(PG8_SB(0, 1), b2 + hstep, voffB); PG8_STAGE(PG8_SA(0, 0), a2, voffA);
;             PG8_WAIT_V(8); PG8_WAIT_L(0); PG8_BAR; PG8_MMA(1, 0, At, B0); PG8_MMA(1, 1, At, B1); PG8_BAR; PG8_SCHED;
.LBB0_600:
	s_add_u32 s24, s54, 0xfff80080
	s_addc_u32 s25, s55, -1
	s_add_i32 s46, 0, 0x10000
	s_cmp_eq_u32 s83, 28
	s_cselect_b32 s61, s2, s25
	s_cselect_b32 s60, s3, s24
	v_add_u32_e32 v142, s46, v145
	s_cselect_b32 s25, s15, s82
	s_cselect_b32 s24, s17, s79
	s_add_i32 s47, 0, 0x14000
	ds_read_b128 v[138:141], v142
	ds_read_b128 v[148:151], v142 offset:1024
	ds_read_b128 v[152:155], v142 offset:2048
	ds_read_b128 v[156:159], v142 offset:3072
	v_add_u32_e32 v142, s47, v145
	s_add_i32 m0, s43, 0xc000
	ds_read_b128 v[170:173], v142
	global_load_lds_dwordx4 v134, s[54:55]
	ds_read_b128 v[174:177], v142 offset:1024
	ds_read_b128 v[178:181], v142 offset:2048
	ds_read_b128 v[182:185], v142 offset:3072
	ds_read_b128 v[186:189], v147
	ds_read_b128 v[190:193], v147 offset:1024
	ds_read_b128 v[194:197], v147 offset:2048
	s_add_i32 m0, s43, 0xe000
	ds_read_b128 v[198:201], v147 offset:3072
	global_load_lds_dwordx4 v136, s[54:55]
	ds_read_b128 v[202:205], v147 offset:4096
	ds_read_b128 v[206:209], v147 offset:5120
	ds_read_b128 v[210:213], v147 offset:6144
	ds_read_b128 v[214:217], v147 offset:7168
	s_waitcnt vmcnt(8)
	s_waitcnt lgkmcnt(0)
	s_barrier
	s_setprio 1
	s_waitcnt lgkmcnt(0)
	v_mfma_f32_16x16x32_bf16 v[124:127], v[138:141], v[186:189], v[124:127]
	v_mfma_f32_16x16x32_bf16 v[116:119], v[152:155], v[186:189], v[116:119]
	v_mfma_f32_16x16x32_bf16 v[108:111], v[138:141], v[194:197], v[108:111]
	v_mfma_f32_16x16x32_bf16 v[100:103], v[152:155], v[194:197], v[100:103]
	v_mfma_f32_16x16x32_bf16 v[92:95], v[138:141], v[202:205], v[92:95]
	v_mfma_f32_16x16x32_bf16 v[84:87], v[152:155], v[202:205], v[84:87]
	v_mfma_f32_16x16x32_bf16 v[76:79], v[138:141], v[210:213], v[76:79]
	v_mfma_f32_16x16x32_bf16 v[68:71], v[152:155], v[210:213], v[68:71]
	v_mfma_f32_16x16x32_bf16 v[124:127], v[148:151], v[190:193], v[124:127]
	v_mfma_f32_16x16x32_bf16 v[116:119], v[156:159], v[190:193], v[116:119]
	v_mfma_f32_16x16x32_bf16 v[108:111], v[148:151], v[198:201], v[108:111]
	v_mfma_f32_16x16x32_bf16 v[100:103], v[156:159], v[198:201], v[100:103]
	v_mfma_f32_16x16x32_bf16 v[92:95], v[148:151], v[206:209], v[92:95]
	v_mfma_f32_16x16x32_bf16 v[84:87], v[156:159], v[206:209], v[84:87]
	v_mfma_f32_16x16x32_bf16 v[76:79], v[148:151], v[214:217], v[76:79]
	v_mfma_f32_16x16x32_bf16 v[68:71], v[156:159], v[214:217], v[68:71]
	s_setprio 0
	s_setprio 1
	v_mfma_f32_16x16x32_bf16 v[120:123], v[170:173], v[186:189], v[120:123]
	v_mfma_f32_16x16x32_bf16 v[112:115], v[178:181], v[186:189], v[112:115]
	v_mfma_f32_16x16x32_bf16 v[104:107], v[170:173], v[194:197], v[104:107]
	v_mfma_f32_16x16x32_bf16 v[96:99], v[178:181], v[194:197], v[96:99]
	v_mfma_f32_16x16x32_bf16 v[88:91], v[170:173], v[202:205], v[88:91]
	v_mfma_f32_16x16x32_bf16 v[80:83], v[178:181], v[202:205], v[80:83]
	v_mfma_f32_16x16x32_bf16 v[72:75], v[170:173], v[210:213], v[72:75]
	v_mfma_f32_16x16x32_bf16 v[64:67], v[178:181], v[210:213], v[64:67]
	v_mfma_f32_16x16x32_bf16 v[120:123], v[174:177], v[190:193], v[120:123]
	v_mfma_f32_16x16x32_bf16 v[112:115], v[182:185], v[190:193], v[112:115]
	v_mfma_f32_16x16x32_bf16 v[104:107], v[174:177], v[198:201], v[104:107]
	v_mfma_f32_16x16x32_bf16 v[96:99], v[182:185], v[198:201], v[96:99]
	v_mfma_f32_16x16x32_bf16 v[88:91], v[174:177], v[206:209], v[88:91]
	v_mfma_f32_16x16x32_bf16 v[80:83], v[182:185], v[206:209], v[80:83]
	v_mfma_f32_16x16x32_bf16 v[72:75], v[174:177], v[214:217], v[72:75]
	v_mfma_f32_16x16x32_bf16 v[64:67], v[182:185], v[214:217], v[64:67]
	s_setprio 0
	s_barrier
	s_add_i32 s46, s46, s62
	s_mov_b32 m0, s46
	ds_read_b128 v[186:189], v147 offset:16384
	global_load_lds_dwordx4 v160, s[24:25]
	ds_read_b128 v[190:193], v147 offset:17408
	ds_read_b128 v[194:197], v147 offset:18432
	s_add_i32 m0, s46, 0x2000
	s_add_u32 s88, s24, 0x80000
	s_addc_u32 s89, s25, 0
	s_add_i32 s46, s47, s62
	global_load_lds_dwordx4 v128, s[24:25]
	ds_read_b128 v[198:201], v147 offset:19456
	s_mov_b32 m0, s46
	ds_read_b128 v[202:205], v147 offset:20480
	global_load_lds_dwordx4 v160, s[88:89]
	ds_read_b128 v[206:209], v147 offset:21504
	s_add_i32 m0, s46, 0x2000
	ds_read_b128 v[210:213], v147 offset:22528
	global_load_lds_dwordx4 v128, s[88:89]
	ds_read_b128 v[214:217], v147 offset:23552
	s_mov_b32 m0, s43
	s_nop 0
	global_load_lds_dwordx4 v132, s[60:61]
	s_mov_b32 m0, s44
	s_nop 0
	global_load_lds_dwordx4 v130, s[60:61]
	s_waitcnt vmcnt(8)
	s_waitcnt lgkmcnt(0)
	s_barrier
	s_setprio 1
	s_waitcnt lgkmcnt(0)
	v_mfma_f32_16x16x32_bf16 v[60:63], v[138:141], v[186:189], v[60:63]
	v_mfma_f32_16x16x32_bf16 v[52:55], v[152:155], v[186:189], v[52:55]
	v_mfma_f32_16x16x32_bf16 v[44:47], v[138:141], v[194:197], v[44:47]
	v_mfma_f32_16x16x32_bf16 v[36:39], v[152:155], v[194:197], v[36:39]
	v_mfma_f32_16x16x32_bf16 v[28:31], v[138:141], v[202:205], v[28:31]
	v_mfma_f32_16x16x32_bf16 v[20:23], v[152:155], v[202:205], v[20:23]
	v_mfma_f32_16x16x32_bf16 v[12:15], v[138:141], v[210:213], v[12:15]
	v_mfma_f32_16x16x32_bf16 v[4:7], v[152:155], v[210:213], v[4:7]
	v_mfma_f32_16x16x32_bf16 v[60:63], v[148:151], v[190:193], v[60:63]
	v_mfma_f32_16x16x32_bf16 v[52:55], v[156:159], v[190:193], v[52:55]
	v_mfma_f32_16x16x32_bf16 v[44:47], v[148:151], v[198:201], v[44:47]
	v_mfma_f32_16x16x32_bf16 v[36:39], v[156:159], v[198:201], v[36:39]
	v_mfma_f32_16x16x32_bf16 v[28:31], v[148:151], v[206:209], v[28:31]
	v_mfma_f32_16x16x32_bf16 v[20:23], v[156:159], v[206:209], v[20:23]
	v_mfma_f32_16x16x32_bf16 v[12:15], v[148:151], v[214:217], v[12:15]
	v_mfma_f32_16x16x32_bf16 v[4:7], v[156:159], v[214:217], v[4:7]
	s_setprio 0
	s_setprio 1
	v_mfma_f32_16x16x32_bf16 v[56:59], v[170:173], v[186:189], v[56:59]
	v_mfma_f32_16x16x32_bf16 v[48:51], v[178:181], v[186:189], v[48:51]
	v_mfma_f32_16x16x32_bf16 v[40:43], v[170:173], v[194:197], v[40:43]
	v_mfma_f32_16x16x32_bf16 v[32:35], v[178:181], v[194:197], v[32:35]
	v_mfma_f32_16x16x32_bf16 v[24:27], v[170:173], v[202:205], v[24:27]
	v_mfma_f32_16x16x32_bf16 v[16:19], v[178:181], v[202:205], v[16:19]
	v_mfma_f32_16x16x32_bf16 v[8:11], v[170:173], v[210:213], v[8:11]
	v_mfma_f32_16x16x32_bf16 v[0:3], v[178:181], v[210:213], v[0:3]
	v_mfma_f32_16x16x32_bf16 v[56:59], v[174:177], v[190:193], v[56:59]
	v_mfma_f32_16x16x32_bf16 v[48:51], v[182:185], v[190:193], v[48:51]
	v_mfma_f32_16x16x32_bf16 v[40:43], v[174:177], v[198:201], v[40:43]
	v_mfma_f32_16x16x32_bf16 v[32:35], v[182:185], v[198:201], v[32:35]
	v_mfma_f32_16x16x32_bf16 v[24:27], v[174:177], v[206:209], v[24:27]
	v_mfma_f32_16x16x32_bf16 v[16:19], v[182:185], v[206:209], v[16:19]
	v_mfma_f32_16x16x32_bf16 v[8:11], v[174:177], v[214:217], v[8:11]
	v_mfma_f32_16x16x32_bf16 v[0:3], v[182:185], v[214:217], v[0:3]
	s_setprio 0
	s_barrier
; #define PG8_STAGE(bufoff, gbase, voff) do { _Pragma("unroll") for (int _i = 0; _i < 2; ++_i) \
;         __builtin_amdgcn_global_load_lds((const unsigned*)((const char*)(gbase) + (voff)[_i]), (LAS unsigned*)(lds + (bufoff) + ldsw + _i * 8192), 16, 0, 0); } while (0)
; #define PG8_LDA(dst, b, h) do { _Pragma("unroll") for (int m = 0; m < 4; ++m) _Pragma("unroll") for (int k = 0; k < 2; ++k) dst[m][k] = *(const LAS bf16x8*)(lds + PG8_SA(b, h) + aoff + m * 2048 + k * 1024); } while (0)
; #define PG8_LDB(dst, b, h) do { _Pragma("unroll") for (int n = 0; n < 2; ++n) _Pragma("unroll") for (int k = 0; k < 2; ++k) dst[n][k] = *(const LAS bf16x8*)(lds + PG8_SB(b, h) + boff + n * 2048 + k * 1024); } while (0)
; #define PG8_MMA(ai, bj, At, Bt) do { __builtin_amdgcn_s_setprio(1); _Pragma("unroll") for (int m = 0; m < 4; ++m) _Pragma("unroll") for (int n = 0; n < 2; ++n) _Pragma("unroll") for (int k = 0; k < 2; ++k) \
;         acc[ai][bj][m][n] = __builtin_amdgcn_mfma_f32_16x16x32_bf16(Bt[n][k], At[m][k], acc[ai][bj][m][n], 0, 0, 0); __builtin_amdgcn_s_setprio(0); } while (0)
; #define PG8_WAIT_V(n) asm volatile("s_waitcnt vmcnt(" #n ")" ::: "memory")
; #define PG8_WAIT_L(n) asm volatile("s_waitcnt lgkmcnt(" #n ")" ::: "memory")
; #define PG8_BAR __builtin_amdgcn_s_barrier()
; #define PG8_SCHED __builtin_amdgcn_sched_barrier(0)
; template <class Epi, class Sched, bool ALIGN_EPI = true, bool SP2 = true>
; __device__ __forceinline__ void gemm_phase(LAS unsigned char* lds, const Gemm g, const Sched& S, const Epi& E) {
;     ...
;             PG8_LDB(B0, 1, 0); PG8_LDB(B1, 1, 1); PG8_SCHED; PG8_LDA(At, 1, 0); PG8_STAGE(PG8_SA(0, 1), a2 + hstep, voffA);
;             PG8_WAIT_V(8); PG8_WAIT_L(0); PG8_BAR; PG8_MMA(0, 0, At, B0); PG8_MMA(0, 1, At, B1); PG8_BAR; PG8_SCHED;
;             PG8_LDA(At, 1, 1); PG8_STAGE(PG8_SB(1, 0), b3, voffB); PG8_STAGE(PG8_SB(1, 1), b3 + hstep, voffB); PG8_STAGE(PG8_SA(1, 0), a3, voffA);
;             PG8_WAIT_V(8); PG8_WAIT_L(0); PG8_BAR; PG8_MMA(1, 0, At, B0); PG8_MMA(1, 1, At, B1); PG8_BAR; PG8_SCHED;
	s_add_i32 s46, 0, 0x18000
	s_add_i32 s47, 0, 0x1c000
	v_add_u32_e32 v156, s46, v145
	v_add_u32_e32 v166, s47, v145
	s_add_u32 s60, s60, 0x80000
	s_addc_u32 s61, s61, 0
	s_mov_b32 m0, s45
	ds_read_b128 v[138:141], v156
	global_load_lds_dwordx4 v132, s[60:61]
	ds_read_b128 v[148:151], v156 offset:1024
	ds_read_b128 v[152:155], v156 offset:2048
	ds_read_b128 v[156:159], v156 offset:3072
	ds_read_b128 v[170:173], v166
	ds_read_b128 v[174:177], v166 offset:1024
	ds_read_b128 v[178:181], v166 offset:2048
	ds_read_b128 v[182:185], v166 offset:3072
	ds_read_b128 v[186:189], v147 offset:32768
	s_mov_b32 m0, s53
	ds_read_b128 v[190:193], v147 offset:33792
	global_load_lds_dwordx4 v130, s[60:61]
	ds_read_b128 v[194:197], v147 offset:34816
	ds_read_b128 v[198:201], v147 offset:35840
	ds_read_b128 v[202:205], v147 offset:36864
	ds_read_b128 v[206:209], v147 offset:37888
	ds_read_b128 v[210:213], v147 offset:38912
	ds_read_b128 v[214:217], v147 offset:39936
	s_waitcnt vmcnt(8)
	s_waitcnt lgkmcnt(0)
	s_barrier
	s_setprio 1
	s_waitcnt lgkmcnt(0)
	v_mfma_f32_16x16x32_bf16 v[124:127], v[138:141], v[186:189], v[124:127]
	v_mfma_f32_16x16x32_bf16 v[116:119], v[152:155], v[186:189], v[116:119]
	v_mfma_f32_16x16x32_bf16 v[108:111], v[138:141], v[194:197], v[108:111]
	v_mfma_f32_16x16x32_bf16 v[100:103], v[152:155], v[194:197], v[100:103]
	v_mfma_f32_16x16x32_bf16 v[92:95], v[138:141], v[202:205], v[92:95]
	v_mfma_f32_16x16x32_bf16 v[84:87], v[152:155], v[202:205], v[84:87]
	v_mfma_f32_16x16x32_bf16 v[76:79], v[138:141], v[210:213], v[76:79]
	v_mfma_f32_16x16x32_bf16 v[68:71], v[152:155], v[210:213], v[68:71]
	v_mfma_f32_16x16x32_bf16 v[124:127], v[148:151], v[190:193], v[124:127]
	v_mfma_f32_16x16x32_bf16 v[116:119], v[156:159], v[190:193], v[116:119]
	v_mfma_f32_16x16x32_bf16 v[108:111], v[148:151], v[198:201], v[108:111]
	v_mfma_f32_16x16x32_bf16 v[100:103], v[156:159], v[198:201], v[100:103]
	v_mfma_f32_16x16x32_bf16 v[92:95], v[148:151], v[206:209], v[92:95]
	v_mfma_f32_16x16x32_bf16 v[84:87], v[156:159], v[206:209], v[84:87]
	v_mfma_f32_16x16x32_bf16 v[76:79], v[148:151], v[214:217], v[76:79]
	v_mfma_f32_16x16x32_bf16 v[68:71], v[156:159], v[214:217], v[68:71]
	s_setprio 0
	s_setprio 1
	v_mfma_f32_16x16x32_bf16 v[120:123], v[170:173], v[186:189], v[120:123]
	v_mfma_f32_16x16x32_bf16 v[112:115], v[178:181], v[186:189], v[112:115]
	v_mfma_f32_16x16x32_bf16 v[104:107], v[170:173], v[194:197], v[104:107]
	v_mfma_f32_16x16x32_bf16 v[96:99], v[178:181], v[194:197], v[96:99]
	v_mfma_f32_16x16x32_bf16 v[88:91], v[170:173], v[202:205], v[88:91]
	v_mfma_f32_16x16x32_bf16 v[80:83], v[178:181], v[202:205], v[80:83]
	v_mfma_f32_16x16x32_bf16 v[72:75], v[170:173], v[210:213], v[72:75]
	v_mfma_f32_16x16x32_bf16 v[64:67], v[178:181], v[210:213], v[64:67]
	v_mfma_f32_16x16x32_bf16 v[120:123], v[174:177], v[190:193], v[120:123]
	v_mfma_f32_16x16x32_bf16 v[112:115], v[182:185], v[190:193], v[112:115]
	v_mfma_f32_16x16x32_bf16 v[104:107], v[174:177], v[198:201], v[104:107]
	v_mfma_f32_16x16x32_bf16 v[96:99], v[182:185], v[198:201], v[96:99]
	v_mfma_f32_16x16x32_bf16 v[88:91], v[174:177], v[206:209], v[88:91]
	v_mfma_f32_16x16x32_bf16 v[80:83], v[182:185], v[206:209], v[80:83]
	v_mfma_f32_16x16x32_bf16 v[72:75], v[174:177], v[214:217], v[72:75]
	v_mfma_f32_16x16x32_bf16 v[64:67], v[182:185], v[214:217], v[64:67]
	s_setprio 0
	s_barrier
	s_add_i32 s46, s46, s62
	s_mov_b32 m0, s46
	s_add_u32 s98, s24, 0x80
	s_addc_u32 s99, s25, 0
	global_load_lds_dwordx4 v160, s[98:99]
	ds_read_b128 v[186:189], v147 offset:49152
	ds_read_b128 v[190:193], v147 offset:50176
	s_add_i32 m0, s46, 0x2000
	s_add_u32 s24, s24, 0x80080
	s_addc_u32 s25, s25, 0
	s_add_i32 s46, s47, s62
	global_load_lds_dwordx4 v128, s[98:99]
	ds_read_b128 v[194:197], v147 offset:51200
	ds_read_b128 v[198:201], v147 offset:52224
	s_mov_b32 m0, s46
	ds_read_b128 v[202:205], v147 offset:53248
	global_load_lds_dwordx4 v160, s[24:25]
	ds_read_b128 v[206:209], v147 offset:54272
	s_add_i32 m0, s46, 0x2000
	ds_read_b128 v[210:213], v147 offset:55296
	global_load_lds_dwordx4 v128, s[24:25]
	ds_read_b128 v[214:217], v147 offset:56320
	s_mov_b32 m0, s63
	s_add_u32 s98, s60, 0xfff80080
	s_addc_u32 s99, s61, -1
	global_load_lds_dwordx4 v132, s[98:99]
	s_mov_b32 m0, s66
	s_nop 0
	global_load_lds_dwordx4 v130, s[98:99]
	s_waitcnt vmcnt(8)
	s_waitcnt lgkmcnt(0)
	s_barrier
	s_setprio 1
	s_waitcnt lgkmcnt(0)
	v_mfma_f32_16x16x32_bf16 v[60:63], v[138:141], v[186:189], v[60:63]
	v_mfma_f32_16x16x32_bf16 v[52:55], v[152:155], v[186:189], v[52:55]
	v_mfma_f32_16x16x32_bf16 v[44:47], v[138:141], v[194:197], v[44:47]
	v_mfma_f32_16x16x32_bf16 v[36:39], v[152:155], v[194:197], v[36:39]
	v_mfma_f32_16x16x32_bf16 v[28:31], v[138:141], v[202:205], v[28:31]
	v_mfma_f32_16x16x32_bf16 v[20:23], v[152:155], v[202:205], v[20:23]
	v_mfma_f32_16x16x32_bf16 v[12:15], v[138:141], v[210:213], v[12:15]
	v_mfma_f32_16x16x32_bf16 v[4:7], v[152:155], v[210:213], v[4:7]
	v_mfma_f32_16x16x32_bf16 v[60:63], v[148:151], v[190:193], v[60:63]
	v_mfma_f32_16x16x32_bf16 v[52:55], v[156:159], v[190:193], v[52:55]
	v_mfma_f32_16x16x32_bf16 v[44:47], v[148:151], v[198:201], v[44:47]
	v_mfma_f32_16x16x32_bf16 v[36:39], v[156:159], v[198:201], v[36:39]
	v_mfma_f32_16x16x32_bf16 v[28:31], v[148:151], v[206:209], v[28:31]
	v_mfma_f32_16x16x32_bf16 v[20:23], v[156:159], v[206:209], v[20:23]
	v_mfma_f32_16x16x32_bf16 v[12:15], v[148:151], v[214:217], v[12:15]
	v_mfma_f32_16x16x32_bf16 v[4:7], v[156:159], v[214:217], v[4:7]
	s_setprio 0
	s_setprio 1
	v_mfma_f32_16x16x32_bf16 v[56:59], v[170:173], v[186:189], v[56:59]
	v_mfma_f32_16x16x32_bf16 v[48:51], v[178:181], v[186:189], v[48:51]
	v_mfma_f32_16x16x32_bf16 v[40:43], v[170:173], v[194:197], v[40:43]
	v_mfma_f32_16x16x32_bf16 v[32:35], v[178:181], v[194:197], v[32:35]
	v_mfma_f32_16x16x32_bf16 v[24:27], v[170:173], v[202:205], v[24:27]
	v_mfma_f32_16x16x32_bf16 v[16:19], v[178:181], v[202:205], v[16:19]
	v_mfma_f32_16x16x32_bf16 v[8:11], v[170:173], v[210:213], v[8:11]
	v_mfma_f32_16x16x32_bf16 v[0:3], v[178:181], v[210:213], v[0:3]
	v_mfma_f32_16x16x32_bf16 v[56:59], v[174:177], v[190:193], v[56:59]
	v_mfma_f32_16x16x32_bf16 v[48:51], v[182:185], v[190:193], v[48:51]
	v_mfma_f32_16x16x32_bf16 v[40:43], v[174:177], v[198:201], v[40:43]
	v_mfma_f32_16x16x32_bf16 v[32:35], v[182:185], v[198:201], v[32:35]
	v_mfma_f32_16x16x32_bf16 v[24:27], v[174:177], v[206:209], v[24:27]
	v_mfma_f32_16x16x32_bf16 v[16:19], v[182:185], v[206:209], v[16:19]
	v_mfma_f32_16x16x32_bf16 v[8:11], v[174:177], v[214:217], v[8:11]
	v_mfma_f32_16x16x32_bf16 v[0:3], v[182:185], v[214:217], v[0:3]
	s_setprio 0
	s_barrier
	s_add_i32 s83, s83, 2
	s_add_u32 s54, s54, 0x100
	s_addc_u32 s55, s55, 0
	s_add_u32 s79, s79, 0x100
	s_addc_u32 s82, s82, 0
	s_cmp_gt_u32 s83, 29
	s_cbranch_scc0 .LBB0_600
	s_and_b64 vcc, exec, s[10:11]
	s_cbranch_vccz .LBB0_603
	s_barrier
